# deleted the 28 provably redundant compiler-inserted s_waitcnt lgkmcnt(0) at the head of each K-loop MFMA block (the inline-asm lgkmcnt(0) before the barrier already drained; nothing issues in between)
# speedup vs baseline: 1.0083x; 1.0083x over previous
; #define PG8_STAGE(bufoff, gbase, voff) do { _Pragma("unroll") for (int _i = 0; _i < 2; ++_i) \
;         __builtin_amdgcn_global_load_lds((const unsigned*)((const char*)(gbase) + (voff)[_i]), (LAS unsigned*)(lds + (bufoff) + ldsw + _i * 8192), 16, 0, 0); } while (0)
; #define PG8_LDA(dst, b, h) do { _Pragma("unroll") for (int m = 0; m < 4; ++m) _Pragma("unroll") for (int k = 0; k < 2; ++k) dst[m][k] = *(const LAS bf16x8*)(lds + PG8_SA(b, h) + aoff + m * 2048 + k * 1024); } while (0)
; #define PG8_LDB(dst, b, h) do { _Pragma("unroll") for (int n = 0; n < 2; ++n) _Pragma("unroll") for (int k = 0; k < 2; ++k) dst[n][k] = *(const LAS bf16x8*)(lds + PG8_SB(b, h) + boff + n * 2048 + k * 1024); } while (0)
; #define PG8_MMA(ai, bj, At, Bt) do { __builtin_amdgcn_s_setprio(1); _Pragma("unroll") for (int m = 0; m < 4; ++m) _Pragma("unroll") for (int n = 0; n < 2; ++n) _Pragma("unroll") for (int k = 0; k < 2; ++k) \
;         acc[ai][bj][m][n] = __builtin_amdgcn_mfma_f32_16x16x32_bf16(Bt[n][k], At[m][k], acc[ai][bj][m][n], 0, 0, 0); __builtin_amdgcn_s_setprio(0); } while (0)
; #define PG8_WAIT_V(n) asm volatile("s_waitcnt vmcnt(" #n ")" ::: "memory")
; #define PG8_WAIT_L(n) asm volatile("s_waitcnt lgkmcnt(" #n ")" ::: "memory")
; #define PG8_BAR __builtin_amdgcn_s_barrier()
; #define PG8_SCHED __builtin_amdgcn_sched_barrier(0)
; template <class Epi, class Sched>
; __device__ __forceinline__ void gemm_phase(LAS unsigned char* lds, const Gemm g, const Sched& S, const Epi& E) {
;     ...
;             const bool last = (t == nt - 2);
;             const char* a1 = cA + (size_t)(t + 1) * kstep;
;             const char* a2 = last ? nA : cA + (size_t)(t + 2) * kstep; const char* b2 = last ? nB : cB + (size_t)(t + 2) * kstep;
;             const char* a3 = a2 + kstep; const char* b3 = b2 + kstep;
;             PG8_LDB(B0, 0, 0); PG8_LDB(B1, 0, 1); PG8_SCHED; PG8_LDA(At, 0, 0); PG8_STAGE(PG8_SA(1, 1), a1 + hstepA, voffA);
;             PG8_WAIT_V(8); PG8_WAIT_L(0); PG8_BAR; PG8_MMA(0, 0, At, B0); PG8_MMA(0, 1, At, B1); PG8_BAR; PG8_SCHED;
;             PG8_LDA(At, 0, 1); PG8_STAGE(PG8_SB(0, 0), b2, voffB); PG8_STAGE(PG8_SB(0, 1), b2 + hstepB, voffB); PG8_STAGE(PG8_SA(0, 0), a2, voffA);
;             PG8_WAIT_V(8); PG8_WAIT_L(0); PG8_BAR; PG8_MMA(1, 0, At, B0); PG8_MMA(1, 1, At, B1); PG8_BAR; PG8_SCHED;
.LBB0_122:
	ds_read_b128 v[128:131], v209
	ds_read_b128 v[132:135], v209 offset:1024
	ds_read_b128 v[136:139], v209 offset:2048
	ds_read_b128 v[140:143], v209 offset:3072
	ds_read_b128 v[144:147], v210
	ds_read_b128 v[148:151], v210 offset:1024
	ds_read_b128 v[152:155], v210 offset:2048
	ds_read_b128 v[156:159], v210 offset:3072
	s_add_u32 s4, s0, 0xfff80080
	s_addc_u32 s5, s1, -1
	s_cmp_eq_u32 s87, 28
	s_cselect_b32 s7, s8, s5
	s_cselect_b32 s6, s9, s4
	s_cselect_b32 s5, s10, s35
	s_cselect_b32 s4, s11, s34
	v_lshl_add_u64 v[216:217], s[0:1], 0, v[178:179]
	s_add_i32 m0, s15, 0xc000
	ds_read_b128 v[160:163], v211
	ds_read_b128 v[164:167], v211 offset:1024
	ds_read_b128 v[182:185], v211 offset:2048
	ds_read_b128 v[186:189], v211 offset:3072
	ds_read_b128 v[190:193], v211 offset:4096
	ds_read_b128 v[194:197], v211 offset:5120
	ds_read_b128 v[198:201], v211 offset:6144
	ds_read_b128 v[202:205], v211 offset:7168
	global_load_lds_dwordx4 v[216:217], off
	v_lshl_add_u64 v[216:217], s[0:1], 0, v[180:181]
	s_add_i32 m0, s15, 0xe000
	s_nop 0
	global_load_lds_dwordx4 v[216:217], off
	s_waitcnt vmcnt(8)
	s_waitcnt lgkmcnt(0)
	s_barrier
	s_setprio 1
	v_mfma_f32_16x16x32_bf16 v[124:127], v[128:131], v[160:163], v[124:127]
	v_mfma_f32_16x16x32_bf16 v[120:123], v[136:139], v[160:163], v[120:123]
	v_mfma_f32_16x16x32_bf16 v[116:119], v[128:131], v[182:185], v[116:119]
	v_mfma_f32_16x16x32_bf16 v[112:115], v[136:139], v[182:185], v[112:115]
	v_mfma_f32_16x16x32_bf16 v[108:111], v[128:131], v[190:193], v[108:111]
	v_mfma_f32_16x16x32_bf16 v[104:107], v[136:139], v[190:193], v[104:107]
	v_mfma_f32_16x16x32_bf16 v[96:99], v[128:131], v[198:201], v[96:99]
	v_mfma_f32_16x16x32_bf16 v[100:103], v[136:139], v[198:201], v[100:103]
	v_mfma_f32_16x16x32_bf16 v[124:127], v[132:135], v[164:167], v[124:127]
	v_mfma_f32_16x16x32_bf16 v[120:123], v[140:143], v[164:167], v[120:123]
	v_mfma_f32_16x16x32_bf16 v[116:119], v[132:135], v[186:189], v[116:119]
	v_mfma_f32_16x16x32_bf16 v[112:115], v[140:143], v[186:189], v[112:115]
	v_mfma_f32_16x16x32_bf16 v[108:111], v[132:135], v[194:197], v[108:111]
	v_mfma_f32_16x16x32_bf16 v[104:107], v[140:143], v[194:197], v[104:107]
	v_mfma_f32_16x16x32_bf16 v[96:99], v[132:135], v[202:205], v[96:99]
	v_mfma_f32_16x16x32_bf16 v[100:103], v[140:143], v[202:205], v[100:103]
	s_setprio 0
	s_setprio 1
	v_mfma_f32_16x16x32_bf16 v[60:63], v[144:147], v[160:163], v[60:63]
	v_mfma_f32_16x16x32_bf16 v[56:59], v[152:155], v[160:163], v[56:59]
	v_mfma_f32_16x16x32_bf16 v[52:55], v[144:147], v[182:185], v[52:55]
	v_mfma_f32_16x16x32_bf16 v[48:51], v[152:155], v[182:185], v[48:51]
	v_mfma_f32_16x16x32_bf16 v[44:47], v[144:147], v[190:193], v[44:47]
	v_mfma_f32_16x16x32_bf16 v[40:43], v[152:155], v[190:193], v[40:43]
	v_mfma_f32_16x16x32_bf16 v[32:35], v[144:147], v[198:201], v[32:35]
	v_mfma_f32_16x16x32_bf16 v[36:39], v[152:155], v[198:201], v[36:39]
	v_mfma_f32_16x16x32_bf16 v[60:63], v[148:151], v[164:167], v[60:63]
	v_mfma_f32_16x16x32_bf16 v[56:59], v[156:159], v[164:167], v[56:59]
	v_mfma_f32_16x16x32_bf16 v[52:55], v[148:151], v[186:189], v[52:55]
	v_mfma_f32_16x16x32_bf16 v[48:51], v[156:159], v[186:189], v[48:51]
	v_mfma_f32_16x16x32_bf16 v[44:47], v[148:151], v[194:197], v[44:47]
	v_mfma_f32_16x16x32_bf16 v[40:43], v[156:159], v[194:197], v[40:43]
	v_mfma_f32_16x16x32_bf16 v[32:35], v[148:151], v[202:205], v[32:35]
	v_mfma_f32_16x16x32_bf16 v[36:39], v[156:159], v[202:205], v[36:39]
	s_setprio 0
	s_barrier
	s_add_i32 s26, s33, s14
	v_lshl_add_u64 v[216:217], s[4:5], 0, v[170:171]
	s_mov_b32 m0, s26
	ds_read_b128 v[160:163], v211 offset:16384
	ds_read_b128 v[164:167], v211 offset:17408
	ds_read_b128 v[182:185], v211 offset:18432
	ds_read_b128 v[186:189], v211 offset:19456
	ds_read_b128 v[190:193], v211 offset:20480
	ds_read_b128 v[194:197], v211 offset:21504
	ds_read_b128 v[198:201], v211 offset:22528
	ds_read_b128 v[202:205], v211 offset:23552
	global_load_lds_dwordx4 v[216:217], off
	s_add_i32 m0, s26, 0x2000
	s_add_u32 s96, s4, 0x80000
	v_lshl_add_u64 v[218:219], s[4:5], 0, v[174:175]
	s_addc_u32 s97, s5, 0
	s_add_i32 s26, s36, s14
	global_load_lds_dwordx4 v[218:219], off
	v_lshl_add_u64 v[220:221], s[96:97], 0, v[170:171]
	s_mov_b32 m0, s26
	v_lshl_add_u64 v[222:223], s[6:7], 0, v[172:173]
	global_load_lds_dwordx4 v[220:221], off
	v_lshl_add_u64 v[220:221], s[96:97], 0, v[174:175]
	s_add_i32 m0, s26, 0x2000
	s_nop 0
	global_load_lds_dwordx4 v[220:221], off
	v_lshl_add_u64 v[220:221], s[6:7], 0, v[168:169]
	s_mov_b32 m0, s15
	s_nop 0
	global_load_lds_dwordx4 v[220:221], off
	s_mov_b32 m0, s28
	s_nop 0
	global_load_lds_dwordx4 v[222:223], off
	s_waitcnt vmcnt(8)
	s_waitcnt lgkmcnt(0)
	s_barrier
; #define PG8_STAGE(bufoff, gbase, voff) do { _Pragma("unroll") for (int _i = 0; _i < 2; ++_i) \
;         __builtin_amdgcn_global_load_lds((const unsigned*)((const char*)(gbase) + (voff)[_i]), (LAS unsigned*)(lds + (bufoff) + ldsw + _i * 8192), 16, 0, 0); } while (0)
; #define PG8_LDA(dst, b, h) do { _Pragma("unroll") for (int m = 0; m < 4; ++m) _Pragma("unroll") for (int k = 0; k < 2; ++k) dst[m][k] = *(const LAS bf16x8*)(lds + PG8_SA(b, h) + aoff + m * 2048 + k * 1024); } while (0)
; #define PG8_LDB(dst, b, h) do { _Pragma("unroll") for (int n = 0; n < 2; ++n) _Pragma("unroll") for (int k = 0; k < 2; ++k) dst[n][k] = *(const LAS bf16x8*)(lds + PG8_SB(b, h) + boff + n * 2048 + k * 1024); } while (0)
; #define PG8_MMA(ai, bj, At, Bt) do { __builtin_amdgcn_s_setprio(1); _Pragma("unroll") for (int m = 0; m < 4; ++m) _Pragma("unroll") for (int n = 0; n < 2; ++n) _Pragma("unroll") for (int k = 0; k < 2; ++k) \
;         acc[ai][bj][m][n] = __builtin_amdgcn_mfma_f32_16x16x32_bf16(Bt[n][k], At[m][k], acc[ai][bj][m][n], 0, 0, 0); __builtin_amdgcn_s_setprio(0); } while (0)
; #define PG8_WAIT_V(n) asm volatile("s_waitcnt vmcnt(" #n ")" ::: "memory")
; #define PG8_WAIT_L(n) asm volatile("s_waitcnt lgkmcnt(" #n ")" ::: "memory")
; #define PG8_BAR __builtin_amdgcn_s_barrier()
; #define PG8_SCHED __builtin_amdgcn_sched_barrier(0)
; template <class Epi, class Sched>
; __device__ __forceinline__ void gemm_phase(LAS unsigned char* lds, const Gemm g, const Sched& S, const Epi& E) {
;     ...
;             PG8_LDA(At, 0, 1); PG8_STAGE(PG8_SB(0, 0), b2, voffB); PG8_STAGE(PG8_SB(0, 1), b2 + hstepB, voffB); PG8_STAGE(PG8_SA(0, 0), a2, voffA);
;             PG8_WAIT_V(8); PG8_WAIT_L(0); PG8_BAR; PG8_MMA(1, 0, At, B0); PG8_MMA(1, 1, At, B1); PG8_BAR; PG8_SCHED;
;             PG8_LDB(B0, 1, 0); PG8_LDB(B1, 1, 1); PG8_SCHED; PG8_LDA(At, 1, 0); PG8_STAGE(PG8_SA(0, 1), a2 + hstepA, voffA);
;             PG8_WAIT_V(8); PG8_WAIT_L(0); PG8_BAR; PG8_MMA(0, 0, At, B0); PG8_MMA(0, 1, At, B1); PG8_BAR; PG8_SCHED;
	s_setprio 1
	v_mfma_f32_16x16x32_bf16 v[92:95], v[128:131], v[160:163], v[92:95]
	v_mfma_f32_16x16x32_bf16 v[88:91], v[136:139], v[160:163], v[88:91]
	v_mfma_f32_16x16x32_bf16 v[84:87], v[128:131], v[182:185], v[84:87]
	v_mfma_f32_16x16x32_bf16 v[80:83], v[136:139], v[182:185], v[80:83]
	v_mfma_f32_16x16x32_bf16 v[76:79], v[128:131], v[190:193], v[76:79]
	v_mfma_f32_16x16x32_bf16 v[72:75], v[136:139], v[190:193], v[72:75]
	v_mfma_f32_16x16x32_bf16 v[64:67], v[128:131], v[198:201], v[64:67]
	v_mfma_f32_16x16x32_bf16 v[68:71], v[136:139], v[198:201], v[68:71]
	v_mfma_f32_16x16x32_bf16 v[92:95], v[132:135], v[164:167], v[92:95]
	v_mfma_f32_16x16x32_bf16 v[88:91], v[140:143], v[164:167], v[88:91]
	v_mfma_f32_16x16x32_bf16 v[84:87], v[132:135], v[186:189], v[84:87]
	v_mfma_f32_16x16x32_bf16 v[80:83], v[140:143], v[186:189], v[80:83]
	v_mfma_f32_16x16x32_bf16 v[76:79], v[132:135], v[194:197], v[76:79]
	v_mfma_f32_16x16x32_bf16 v[72:75], v[140:143], v[194:197], v[72:75]
	v_mfma_f32_16x16x32_bf16 v[64:67], v[132:135], v[202:205], v[64:67]
	v_mfma_f32_16x16x32_bf16 v[68:71], v[140:143], v[202:205], v[68:71]
	s_setprio 0
	s_setprio 1
	v_mfma_f32_16x16x32_bf16 v[28:31], v[144:147], v[160:163], v[28:31]
	v_mfma_f32_16x16x32_bf16 v[24:27], v[152:155], v[160:163], v[24:27]
	v_mfma_f32_16x16x32_bf16 v[20:23], v[144:147], v[182:185], v[20:23]
	v_mfma_f32_16x16x32_bf16 v[16:19], v[152:155], v[182:185], v[16:19]
	v_mfma_f32_16x16x32_bf16 v[12:15], v[144:147], v[190:193], v[12:15]
	v_mfma_f32_16x16x32_bf16 v[8:11], v[152:155], v[190:193], v[8:11]
	v_mfma_f32_16x16x32_bf16 v[0:3], v[144:147], v[198:201], v[0:3]
	v_mfma_f32_16x16x32_bf16 v[4:7], v[152:155], v[198:201], v[4:7]
	v_mfma_f32_16x16x32_bf16 v[28:31], v[148:151], v[164:167], v[28:31]
	v_mfma_f32_16x16x32_bf16 v[24:27], v[156:159], v[164:167], v[24:27]
	v_mfma_f32_16x16x32_bf16 v[20:23], v[148:151], v[186:189], v[20:23]
	v_mfma_f32_16x16x32_bf16 v[16:19], v[156:159], v[186:189], v[16:19]
	v_mfma_f32_16x16x32_bf16 v[12:15], v[148:151], v[194:197], v[12:15]
	v_mfma_f32_16x16x32_bf16 v[8:11], v[156:159], v[194:197], v[8:11]
	v_mfma_f32_16x16x32_bf16 v[0:3], v[148:151], v[202:205], v[0:3]
	v_mfma_f32_16x16x32_bf16 v[4:7], v[156:159], v[202:205], v[4:7]
	s_setprio 0
	s_barrier
	s_add_i32 s37, 0, 0x18000
	s_add_i32 s26, 0, 0x1c000
	v_add_u32_e32 v140, s37, v208
	v_add_u32_e32 v156, s26, v208
	ds_read_b128 v[128:131], v140
	ds_read_b128 v[132:135], v140 offset:1024
	ds_read_b128 v[136:139], v140 offset:2048
	ds_read_b128 v[140:143], v140 offset:3072
	ds_read_b128 v[144:147], v156
	ds_read_b128 v[148:151], v156 offset:1024
	ds_read_b128 v[152:155], v156 offset:2048
	ds_read_b128 v[156:159], v156 offset:3072
	s_add_u32 s6, s6, 0x80000
	s_addc_u32 s7, s7, 0
	s_mov_b32 m0, s29
	v_lshl_add_u64 v[224:225], s[6:7], 0, v[168:169]
	ds_read_b128 v[160:163], v211 offset:32768
	ds_read_b128 v[164:167], v211 offset:33792
	ds_read_b128 v[182:185], v211 offset:34816
	ds_read_b128 v[186:189], v211 offset:35840
	ds_read_b128 v[190:193], v211 offset:36864
	ds_read_b128 v[194:197], v211 offset:37888
	ds_read_b128 v[198:201], v211 offset:38912
	ds_read_b128 v[202:205], v211 offset:39936
	global_load_lds_dwordx4 v[224:225], off
	v_lshl_add_u64 v[224:225], s[6:7], 0, v[172:173]
	s_mov_b32 m0, s30
	s_nop 0
	global_load_lds_dwordx4 v[224:225], off
	s_waitcnt vmcnt(8)
	s_waitcnt lgkmcnt(0)
	s_barrier
	s_setprio 1
	v_mfma_f32_16x16x32_bf16 v[124:127], v[128:131], v[160:163], v[124:127]
	v_mfma_f32_16x16x32_bf16 v[120:123], v[136:139], v[160:163], v[120:123]
	v_mfma_f32_16x16x32_bf16 v[116:119], v[128:131], v[182:185], v[116:119]
	v_mfma_f32_16x16x32_bf16 v[112:115], v[136:139], v[182:185], v[112:115]
	v_mfma_f32_16x16x32_bf16 v[108:111], v[128:131], v[190:193], v[108:111]
	v_mfma_f32_16x16x32_bf16 v[104:107], v[136:139], v[190:193], v[104:107]
	v_mfma_f32_16x16x32_bf16 v[96:99], v[128:131], v[198:201], v[96:99]
	v_mfma_f32_16x16x32_bf16 v[100:103], v[136:139], v[198:201], v[100:103]
	v_mfma_f32_16x16x32_bf16 v[124:127], v[132:135], v[164:167], v[124:127]
	v_mfma_f32_16x16x32_bf16 v[120:123], v[140:143], v[164:167], v[120:123]
	v_mfma_f32_16x16x32_bf16 v[116:119], v[132:135], v[186:189], v[116:119]
	v_mfma_f32_16x16x32_bf16 v[112:115], v[140:143], v[186:189], v[112:115]
	v_mfma_f32_16x16x32_bf16 v[108:111], v[132:135], v[194:197], v[108:111]
	v_mfma_f32_16x16x32_bf16 v[104:107], v[140:143], v[194:197], v[104:107]
	v_mfma_f32_16x16x32_bf16 v[96:99], v[132:135], v[202:205], v[96:99]
	v_mfma_f32_16x16x32_bf16 v[100:103], v[140:143], v[202:205], v[100:103]
	s_setprio 0
	s_setprio 1
	v_mfma_f32_16x16x32_bf16 v[60:63], v[144:147], v[160:163], v[60:63]
	v_mfma_f32_16x16x32_bf16 v[56:59], v[152:155], v[160:163], v[56:59]
	v_mfma_f32_16x16x32_bf16 v[52:55], v[144:147], v[182:185], v[52:55]
	v_mfma_f32_16x16x32_bf16 v[48:51], v[152:155], v[182:185], v[48:51]
	v_mfma_f32_16x16x32_bf16 v[44:47], v[144:147], v[190:193], v[44:47]
	v_mfma_f32_16x16x32_bf16 v[40:43], v[152:155], v[190:193], v[40:43]
	v_mfma_f32_16x16x32_bf16 v[32:35], v[144:147], v[198:201], v[32:35]
	v_mfma_f32_16x16x32_bf16 v[36:39], v[152:155], v[198:201], v[36:39]
	v_mfma_f32_16x16x32_bf16 v[60:63], v[148:151], v[164:167], v[60:63]
	v_mfma_f32_16x16x32_bf16 v[56:59], v[156:159], v[164:167], v[56:59]
	v_mfma_f32_16x16x32_bf16 v[52:55], v[148:151], v[186:189], v[52:55]
	v_mfma_f32_16x16x32_bf16 v[48:51], v[156:159], v[186:189], v[48:51]
	v_mfma_f32_16x16x32_bf16 v[44:47], v[148:151], v[194:197], v[44:47]
	v_mfma_f32_16x16x32_bf16 v[40:43], v[156:159], v[194:197], v[40:43]
	v_mfma_f32_16x16x32_bf16 v[32:35], v[148:151], v[202:205], v[32:35]
	v_mfma_f32_16x16x32_bf16 v[36:39], v[156:159], v[202:205], v[36:39]
	s_setprio 0
	s_barrier
; #define PG8_STAGE(bufoff, gbase, voff) do { _Pragma("unroll") for (int _i = 0; _i < 2; ++_i) \
;         __builtin_amdgcn_global_load_lds((const unsigned*)((const char*)(gbase) + (voff)[_i]), (LAS unsigned*)(lds + (bufoff) + ldsw + _i * 8192), 16, 0, 0); } while (0)
; #define PG8_LDA(dst, b, h) do { _Pragma("unroll") for (int m = 0; m < 4; ++m) _Pragma("unroll") for (int k = 0; k < 2; ++k) dst[m][k] = *(const LAS bf16x8*)(lds + PG8_SA(b, h) + aoff + m * 2048 + k * 1024); } while (0)
; #define PG8_MMA(ai, bj, At, Bt) do { __builtin_amdgcn_s_setprio(1); _Pragma("unroll") for (int m = 0; m < 4; ++m) _Pragma("unroll") for (int n = 0; n < 2; ++n) _Pragma("unroll") for (int k = 0; k < 2; ++k) \
;         acc[ai][bj][m][n] = __builtin_amdgcn_mfma_f32_16x16x32_bf16(Bt[n][k], At[m][k], acc[ai][bj][m][n], 0, 0, 0); __builtin_amdgcn_s_setprio(0); } while (0)
; #define PG8_WAIT_V(n) asm volatile("s_waitcnt vmcnt(" #n ")" ::: "memory")
; #define PG8_WAIT_L(n) asm volatile("s_waitcnt lgkmcnt(" #n ")" ::: "memory")
; #define PG8_BAR __builtin_amdgcn_s_barrier()
; #define PG8_SCHED __builtin_amdgcn_sched_barrier(0)
; template <class Epi, class Sched>
; __device__ __forceinline__ void gemm_phase(LAS unsigned char* lds, const Gemm g, const Sched& S, const Epi& E) {
;     ...
;             PG8_WAIT_V(8); PG8_WAIT_L(0); PG8_BAR; PG8_MMA(0, 0, At, B0); PG8_MMA(0, 1, At, B1); PG8_BAR; PG8_SCHED;
;             PG8_LDA(At, 1, 1); PG8_STAGE(PG8_SB(1, 0), b3, voffB); PG8_STAGE(PG8_SB(1, 1), b3 + hstepB, voffB); PG8_STAGE(PG8_SA(1, 0), a3, voffA);
;             PG8_WAIT_V(8); PG8_WAIT_L(0); PG8_BAR; PG8_MMA(1, 0, At, B0); PG8_MMA(1, 1, At, B1); PG8_BAR; PG8_SCHED;
;         }
	s_add_i32 s6, s37, s14
	v_lshl_add_u64 v[216:217], v[216:217], 0, s[80:81]
	s_mov_b32 m0, s6
	ds_read_b128 v[160:163], v211 offset:49152
	ds_read_b128 v[164:167], v211 offset:50176
	ds_read_b128 v[182:185], v211 offset:51200
	ds_read_b128 v[186:189], v211 offset:52224
	ds_read_b128 v[190:193], v211 offset:53248
	ds_read_b128 v[194:197], v211 offset:54272
	ds_read_b128 v[198:201], v211 offset:55296
	ds_read_b128 v[202:205], v211 offset:56320
	global_load_lds_dwordx4 v[216:217], off
	s_add_i32 m0, s6, 0x2000
	s_add_u32 s4, s4, 0x80080
	v_lshl_add_u64 v[216:217], v[218:219], 0, s[80:81]
	s_addc_u32 s5, s5, 0
	s_add_i32 s6, s26, s14
	global_load_lds_dwordx4 v[216:217], off
	v_lshl_add_u64 v[216:217], s[4:5], 0, v[170:171]
	s_mov_b32 m0, s6
	s_nop 0
	global_load_lds_dwordx4 v[216:217], off
	v_lshl_add_u64 v[216:217], s[4:5], 0, v[174:175]
	s_add_i32 m0, s6, 0x2000
	s_nop 0
	global_load_lds_dwordx4 v[216:217], off
	v_lshl_add_u64 v[216:217], v[220:221], 0, s[80:81]
	s_mov_b32 m0, s21
	s_nop 0
	global_load_lds_dwordx4 v[216:217], off
	v_lshl_add_u64 v[216:217], v[222:223], 0, s[80:81]
	s_mov_b32 m0, s18
	s_nop 0
	global_load_lds_dwordx4 v[216:217], off
	s_waitcnt vmcnt(8)
	s_waitcnt lgkmcnt(0)
	s_barrier
	s_setprio 1
	v_mfma_f32_16x16x32_bf16 v[92:95], v[128:131], v[160:163], v[92:95]
	v_mfma_f32_16x16x32_bf16 v[88:91], v[136:139], v[160:163], v[88:91]
	v_mfma_f32_16x16x32_bf16 v[84:87], v[128:131], v[182:185], v[84:87]
	v_mfma_f32_16x16x32_bf16 v[80:83], v[136:139], v[182:185], v[80:83]
	v_mfma_f32_16x16x32_bf16 v[76:79], v[128:131], v[190:193], v[76:79]
	v_mfma_f32_16x16x32_bf16 v[72:75], v[136:139], v[190:193], v[72:75]
	v_mfma_f32_16x16x32_bf16 v[64:67], v[128:131], v[198:201], v[64:67]
	v_mfma_f32_16x16x32_bf16 v[68:71], v[136:139], v[198:201], v[68:71]
	v_mfma_f32_16x16x32_bf16 v[92:95], v[132:135], v[164:167], v[92:95]
	v_mfma_f32_16x16x32_bf16 v[88:91], v[140:143], v[164:167], v[88:91]
	v_mfma_f32_16x16x32_bf16 v[84:87], v[132:135], v[186:189], v[84:87]
	v_mfma_f32_16x16x32_bf16 v[80:83], v[140:143], v[186:189], v[80:83]
	v_mfma_f32_16x16x32_bf16 v[76:79], v[132:135], v[194:197], v[76:79]
	v_mfma_f32_16x16x32_bf16 v[72:75], v[140:143], v[194:197], v[72:75]
	v_mfma_f32_16x16x32_bf16 v[64:67], v[132:135], v[202:205], v[64:67]
	v_mfma_f32_16x16x32_bf16 v[68:71], v[140:143], v[202:205], v[68:71]
	s_setprio 0
	s_setprio 1
	v_mfma_f32_16x16x32_bf16 v[28:31], v[144:147], v[160:163], v[28:31]
	v_mfma_f32_16x16x32_bf16 v[24:27], v[152:155], v[160:163], v[24:27]
	v_mfma_f32_16x16x32_bf16 v[20:23], v[144:147], v[182:185], v[20:23]
	v_mfma_f32_16x16x32_bf16 v[16:19], v[152:155], v[182:185], v[16:19]
	v_mfma_f32_16x16x32_bf16 v[12:15], v[144:147], v[190:193], v[12:15]
	v_mfma_f32_16x16x32_bf16 v[8:11], v[152:155], v[190:193], v[8:11]
	v_mfma_f32_16x16x32_bf16 v[0:3], v[144:147], v[198:201], v[0:3]
	v_mfma_f32_16x16x32_bf16 v[4:7], v[152:155], v[198:201], v[4:7]
	v_mfma_f32_16x16x32_bf16 v[28:31], v[148:151], v[164:167], v[28:31]
	v_mfma_f32_16x16x32_bf16 v[24:27], v[156:159], v[164:167], v[24:27]
	v_mfma_f32_16x16x32_bf16 v[20:23], v[148:151], v[186:189], v[20:23]
	v_mfma_f32_16x16x32_bf16 v[16:19], v[156:159], v[186:189], v[16:19]
	v_mfma_f32_16x16x32_bf16 v[12:15], v[148:151], v[194:197], v[12:15]
	v_mfma_f32_16x16x32_bf16 v[8:11], v[156:159], v[194:197], v[8:11]
	v_mfma_f32_16x16x32_bf16 v[0:3], v[148:151], v[202:205], v[0:3]
	v_mfma_f32_16x16x32_bf16 v[4:7], v[156:159], v[202:205], v[4:7]
	s_setprio 0
	s_barrier
	s_add_i32 s87, s87, 2
	s_add_u32 s0, s0, 0x100
	s_addc_u32 s1, s1, 0
	s_add_u32 s34, s34, 0x100
	s_addc_u32 s35, s35, 0
	s_cmp_gt_u32 s87, 29
	s_cbranch_scc0 .LBB0_122
	s_and_b64 vcc, exec, s[82:83]
	s_cbranch_vccz .LBB0_125
	s_barrier

; #define PG8_STAGE(bufoff, gbase, voff) do { _Pragma("unroll") for (int _i = 0; _i < 2; ++_i) \
;         __builtin_amdgcn_global_load_lds((const unsigned*)((const char*)(gbase) + (voff)[_i]), (LAS unsigned*)(lds + (bufoff) + ldsw + _i * 8192), 16, 0, 0); } while (0)
; #define PG8_LDA(dst, b, h) do { _Pragma("unroll") for (int m = 0; m < 4; ++m) _Pragma("unroll") for (int k = 0; k < 2; ++k) dst[m][k] = *(const LAS bf16x8*)(lds + PG8_SA(b, h) + aoff + m * 2048 + k * 1024); } while (0)
; #define PG8_LDB(dst, b, h) do { _Pragma("unroll") for (int n = 0; n < 2; ++n) _Pragma("unroll") for (int k = 0; k < 2; ++k) dst[n][k] = *(const LAS bf16x8*)(lds + PG8_SB(b, h) + boff + n * 2048 + k * 1024); } while (0)
; #define PG8_MMA(ai, bj, At, Bt) do { __builtin_amdgcn_s_setprio(1); _Pragma("unroll") for (int m = 0; m < 4; ++m) _Pragma("unroll") for (int n = 0; n < 2; ++n) _Pragma("unroll") for (int k = 0; k < 2; ++k) \
;         acc[ai][bj][m][n] = __builtin_amdgcn_mfma_f32_16x16x32_bf16(Bt[n][k], At[m][k], acc[ai][bj][m][n], 0, 0, 0); __builtin_amdgcn_s_setprio(0); } while (0)
; #define PG8_WAIT_V(n) asm volatile("s_waitcnt vmcnt(" #n ")" ::: "memory")
; #define PG8_WAIT_L(n) asm volatile("s_waitcnt lgkmcnt(" #n ")" ::: "memory")
; #define PG8_BAR __builtin_amdgcn_s_barrier()
; #define PG8_SCHED __builtin_amdgcn_sched_barrier(0)
; template <class Epi, class Sched>
; __device__ __forceinline__ void gemm_phase(LAS unsigned char* lds, const Gemm g, const Sched& S, const Epi& E) {
;     ...
;             const bool last = (t == nt - 2);
;             const char* a1 = cA + (size_t)(t + 1) * kstep;
;             const char* a2 = last ? nA : cA + (size_t)(t + 2) * kstep; const char* b2 = last ? nB : cB + (size_t)(t + 2) * kstep;
;             const char* a3 = a2 + kstep; const char* b3 = b2 + kstep;
;             PG8_LDB(B0, 0, 0); PG8_LDB(B1, 0, 1); PG8_SCHED; PG8_LDA(At, 0, 0); PG8_STAGE(PG8_SA(1, 1), a1 + hstepA, voffA);
;             PG8_WAIT_V(8); PG8_WAIT_L(0); PG8_BAR; PG8_MMA(0, 0, At, B0); PG8_MMA(0, 1, At, B1); PG8_BAR; PG8_SCHED;
;             PG8_LDA(At, 0, 1); PG8_STAGE(PG8_SB(0, 0), b2, voffB); PG8_STAGE(PG8_SB(0, 1), b2 + hstepB, voffB); PG8_STAGE(PG8_SA(0, 0), a2, voffA);
;             PG8_WAIT_V(8); PG8_WAIT_L(0); PG8_BAR; PG8_MMA(1, 0, At, B0); PG8_MMA(1, 1, At, B1); PG8_BAR; PG8_SCHED;
.LBB0_531:
	s_add_u32 s61, s76, s82
	s_addc_u32 s73, s77, s83
	s_add_u32 s86, s61, 0x100
	s_addc_u32 s87, s73, 0
	s_and_b64 s[84:85], s[80:81], exec
	s_cselect_b32 s85, s12, s87
	s_cselect_b32 s84, s13, s86
	s_add_u32 s82, s74, s82
	s_addc_u32 s83, s75, s83
	s_add_u32 s82, s82, 0x100
	s_addc_u32 s83, s83, 0
	s_and_b64 s[80:81], s[80:81], exec
	s_cselect_b32 s87, s49, s83
	s_cselect_b32 s86, s59, s82
	s_add_u32 s90, s61, 0x40080
	ds_read_b128 v[128:131], v163
	ds_read_b128 v[132:135], v163 offset:1024
	ds_read_b128 v[136:139], v163 offset:2048
	ds_read_b128 v[140:143], v163 offset:3072
	ds_read_b128 v[156:159], v164
	ds_read_b128 v[166:169], v164 offset:1024
	ds_read_b128 v[170:173], v164 offset:2048
	ds_read_b128 v[174:177], v164 offset:3072
	s_addc_u32 s91, s73, 0
	s_add_i32 s97, s33, s14
	s_add_i32 m0, s15, 0xc000
	s_add_i32 vcc_lo, s15, 0xe000
	s_add_i32 s94, s97, 0x2000
	s_add_u32 s88, s86, 0x10000
	s_addc_u32 s89, s87, 0
	s_add_i32 s96, s36, s14
	s_add_i32 s95, s96, 0x2000
	s_add_u32 s82, s84, 0x40000
	s_addc_u32 s83, s85, 0
	s_add_i32 s93, s37, s14
	s_add_i32 s73, s93, 0x2000
	s_add_u32 s80, s86, 0x10080
	s_addc_u32 s81, s87, 0
	s_add_i32 s92, s26, s14
	s_add_i32 s61, s92, 0x2000
	v_lshl_add_u64 v[210:211], s[90:91], 0, v[150:151]
	ds_read_b128 v[178:181], v165
	ds_read_b128 v[182:185], v165 offset:1024
	ds_read_b128 v[186:189], v165 offset:2048
	ds_read_b128 v[190:193], v165 offset:3072
	ds_read_b128 v[194:197], v165 offset:4096
	ds_read_b128 v[198:201], v165 offset:5120
	ds_read_b128 v[202:205], v165 offset:6144
	ds_read_b128 v[206:209], v165 offset:7168
	global_load_lds_dwordx4 v[210:211], off
	v_lshl_add_u64 v[210:211], s[90:91], 0, v[146:147]
	s_mov_b32 m0, vcc_lo
	s_nop 0
	global_load_lds_dwordx4 v[210:211], off
	s_waitcnt vmcnt(8)
	s_waitcnt lgkmcnt(0)
	s_barrier
	s_setprio 1
	v_mfma_f32_16x16x32_bf16 v[124:127], v[128:131], v[178:181], v[124:127]
	v_mfma_f32_16x16x32_bf16 v[120:123], v[136:139], v[178:181], v[120:123]
	v_mfma_f32_16x16x32_bf16 v[116:119], v[128:131], v[186:189], v[116:119]
	v_mfma_f32_16x16x32_bf16 v[112:115], v[136:139], v[186:189], v[112:115]
	v_mfma_f32_16x16x32_bf16 v[108:111], v[128:131], v[194:197], v[108:111]
	v_mfma_f32_16x16x32_bf16 v[100:103], v[136:139], v[194:197], v[100:103]
	v_mfma_f32_16x16x32_bf16 v[92:95], v[128:131], v[202:205], v[92:95]
	v_mfma_f32_16x16x32_bf16 v[84:87], v[136:139], v[202:205], v[84:87]
	v_mfma_f32_16x16x32_bf16 v[124:127], v[132:135], v[182:185], v[124:127]
	v_mfma_f32_16x16x32_bf16 v[120:123], v[140:143], v[182:185], v[120:123]
	v_mfma_f32_16x16x32_bf16 v[116:119], v[132:135], v[190:193], v[116:119]
	v_mfma_f32_16x16x32_bf16 v[112:115], v[140:143], v[190:193], v[112:115]
	v_mfma_f32_16x16x32_bf16 v[108:111], v[132:135], v[198:201], v[108:111]
	v_mfma_f32_16x16x32_bf16 v[100:103], v[140:143], v[198:201], v[100:103]
	v_mfma_f32_16x16x32_bf16 v[92:95], v[132:135], v[206:209], v[92:95]
	v_mfma_f32_16x16x32_bf16 v[84:87], v[140:143], v[206:209], v[84:87]
	s_setprio 0
	s_setprio 1
	v_mfma_f32_16x16x32_bf16 v[104:107], v[156:159], v[178:181], v[104:107]
	v_mfma_f32_16x16x32_bf16 v[96:99], v[170:173], v[178:181], v[96:99]
	v_mfma_f32_16x16x32_bf16 v[88:91], v[156:159], v[186:189], v[88:91]
	v_mfma_f32_16x16x32_bf16 v[80:83], v[170:173], v[186:189], v[80:83]
	v_mfma_f32_16x16x32_bf16 v[76:79], v[156:159], v[194:197], v[76:79]
	v_mfma_f32_16x16x32_bf16 v[72:75], v[170:173], v[194:197], v[72:75]
	v_mfma_f32_16x16x32_bf16 v[68:71], v[156:159], v[202:205], v[68:71]
	v_mfma_f32_16x16x32_bf16 v[64:67], v[170:173], v[202:205], v[64:67]
	v_mfma_f32_16x16x32_bf16 v[104:107], v[166:169], v[182:185], v[104:107]
	v_mfma_f32_16x16x32_bf16 v[96:99], v[174:177], v[182:185], v[96:99]
	v_mfma_f32_16x16x32_bf16 v[88:91], v[166:169], v[190:193], v[88:91]
	v_mfma_f32_16x16x32_bf16 v[80:83], v[174:177], v[190:193], v[80:83]
	v_mfma_f32_16x16x32_bf16 v[76:79], v[166:169], v[198:201], v[76:79]
	v_mfma_f32_16x16x32_bf16 v[72:75], v[174:177], v[198:201], v[72:75]
	v_mfma_f32_16x16x32_bf16 v[68:71], v[166:169], v[206:209], v[68:71]
	v_mfma_f32_16x16x32_bf16 v[64:67], v[174:177], v[206:209], v[64:67]
	s_setprio 0
	s_barrier
	s_mov_b32 m0, s97
	v_lshl_add_u64 v[210:211], s[86:87], 0, v[148:149]
	ds_read_b128 v[178:181], v165 offset:16384
	ds_read_b128 v[182:185], v165 offset:17408
	ds_read_b128 v[186:189], v165 offset:18432
	ds_read_b128 v[190:193], v165 offset:19456
	ds_read_b128 v[194:197], v165 offset:20480
	ds_read_b128 v[198:201], v165 offset:21504
	ds_read_b128 v[202:205], v165 offset:22528
	ds_read_b128 v[206:209], v165 offset:23552
	global_load_lds_dwordx4 v[210:211], off
	v_lshl_add_u64 v[216:217], s[86:87], 0, v[144:145]
	s_mov_b32 m0, s94
	v_lshl_add_u64 v[218:219], s[88:89], 0, v[148:149]
	global_load_lds_dwordx4 v[216:217], off
	s_mov_b32 m0, s96
	v_lshl_add_u64 v[220:221], s[84:85], 0, v[146:147]
	global_load_lds_dwordx4 v[218:219], off
	v_lshl_add_u64 v[218:219], s[88:89], 0, v[144:145]
	s_mov_b32 m0, s95
	s_nop 0
	global_load_lds_dwordx4 v[218:219], off
	v_lshl_add_u64 v[218:219], s[84:85], 0, v[150:151]
	s_mov_b32 m0, s15
	s_nop 0
	global_load_lds_dwordx4 v[218:219], off
	s_mov_b32 m0, s18
	s_nop 0
	global_load_lds_dwordx4 v[220:221], off
	s_waitcnt vmcnt(8)
	s_waitcnt lgkmcnt(0)
	s_barrier
; #define PG8_STAGE(bufoff, gbase, voff) do { _Pragma("unroll") for (int _i = 0; _i < 2; ++_i) \
;         __builtin_amdgcn_global_load_lds((const unsigned*)((const char*)(gbase) + (voff)[_i]), (LAS unsigned*)(lds + (bufoff) + ldsw + _i * 8192), 16, 0, 0); } while (0)
; #define PG8_LDA(dst, b, h) do { _Pragma("unroll") for (int m = 0; m < 4; ++m) _Pragma("unroll") for (int k = 0; k < 2; ++k) dst[m][k] = *(const LAS bf16x8*)(lds + PG8_SA(b, h) + aoff + m * 2048 + k * 1024); } while (0)
; #define PG8_LDB(dst, b, h) do { _Pragma("unroll") for (int n = 0; n < 2; ++n) _Pragma("unroll") for (int k = 0; k < 2; ++k) dst[n][k] = *(const LAS bf16x8*)(lds + PG8_SB(b, h) + boff + n * 2048 + k * 1024); } while (0)
; #define PG8_MMA(ai, bj, At, Bt) do { __builtin_amdgcn_s_setprio(1); _Pragma("unroll") for (int m = 0; m < 4; ++m) _Pragma("unroll") for (int n = 0; n < 2; ++n) _Pragma("unroll") for (int k = 0; k < 2; ++k) \
;         acc[ai][bj][m][n] = __builtin_amdgcn_mfma_f32_16x16x32_bf16(Bt[n][k], At[m][k], acc[ai][bj][m][n], 0, 0, 0); __builtin_amdgcn_s_setprio(0); } while (0)
; #define PG8_WAIT_V(n) asm volatile("s_waitcnt vmcnt(" #n ")" ::: "memory")
; #define PG8_WAIT_L(n) asm volatile("s_waitcnt lgkmcnt(" #n ")" ::: "memory")
; #define PG8_BAR __builtin_amdgcn_s_barrier()
; #define PG8_SCHED __builtin_amdgcn_sched_barrier(0)
; template <class Epi, class Sched>
; __device__ __forceinline__ void gemm_phase(LAS unsigned char* lds, const Gemm g, const Sched& S, const Epi& E) {
;     ...
;             PG8_LDA(At, 0, 1); PG8_STAGE(PG8_SB(0, 0), b2, voffB); PG8_STAGE(PG8_SB(0, 1), b2 + hstepB, voffB); PG8_STAGE(PG8_SA(0, 0), a2, voffA);
;             PG8_WAIT_V(8); PG8_WAIT_L(0); PG8_BAR; PG8_MMA(1, 0, At, B0); PG8_MMA(1, 1, At, B1); PG8_BAR; PG8_SCHED;
;             PG8_LDB(B0, 1, 0); PG8_LDB(B1, 1, 1); PG8_SCHED; PG8_LDA(At, 1, 0); PG8_STAGE(PG8_SA(0, 1), a2 + hstepA, voffA);
;             PG8_WAIT_V(8); PG8_WAIT_L(0); PG8_BAR; PG8_MMA(0, 0, At, B0); PG8_MMA(0, 1, At, B1); PG8_BAR; PG8_SCHED;
	s_setprio 1
	v_mfma_f32_16x16x32_bf16 v[60:63], v[128:131], v[178:181], v[60:63]
	v_mfma_f32_16x16x32_bf16 v[56:59], v[136:139], v[178:181], v[56:59]
	v_mfma_f32_16x16x32_bf16 v[48:51], v[128:131], v[186:189], v[48:51]
	v_mfma_f32_16x16x32_bf16 v[40:43], v[136:139], v[186:189], v[40:43]
	v_mfma_f32_16x16x32_bf16 v[32:35], v[128:131], v[194:197], v[32:35]
	v_mfma_f32_16x16x32_bf16 v[24:27], v[136:139], v[194:197], v[24:27]
	v_mfma_f32_16x16x32_bf16 v[16:19], v[128:131], v[202:205], v[16:19]
	v_mfma_f32_16x16x32_bf16 v[8:11], v[136:139], v[202:205], v[8:11]
	v_mfma_f32_16x16x32_bf16 v[60:63], v[132:135], v[182:185], v[60:63]
	v_mfma_f32_16x16x32_bf16 v[56:59], v[140:143], v[182:185], v[56:59]
	v_mfma_f32_16x16x32_bf16 v[48:51], v[132:135], v[190:193], v[48:51]
	v_mfma_f32_16x16x32_bf16 v[40:43], v[140:143], v[190:193], v[40:43]
	v_mfma_f32_16x16x32_bf16 v[32:35], v[132:135], v[198:201], v[32:35]
	v_mfma_f32_16x16x32_bf16 v[24:27], v[140:143], v[198:201], v[24:27]
	v_mfma_f32_16x16x32_bf16 v[16:19], v[132:135], v[206:209], v[16:19]
	v_mfma_f32_16x16x32_bf16 v[8:11], v[140:143], v[206:209], v[8:11]
	s_setprio 0
	s_setprio 1
	v_mfma_f32_16x16x32_bf16 v[52:55], v[156:159], v[178:181], v[52:55]
	v_mfma_f32_16x16x32_bf16 v[44:47], v[170:173], v[178:181], v[44:47]
	v_mfma_f32_16x16x32_bf16 v[36:39], v[156:159], v[186:189], v[36:39]
	v_mfma_f32_16x16x32_bf16 v[28:31], v[170:173], v[186:189], v[28:31]
	v_mfma_f32_16x16x32_bf16 v[20:23], v[156:159], v[194:197], v[20:23]
	v_mfma_f32_16x16x32_bf16 v[12:15], v[170:173], v[194:197], v[12:15]
	v_mfma_f32_16x16x32_bf16 v[4:7], v[156:159], v[202:205], v[4:7]
	v_mfma_f32_16x16x32_bf16 v[0:3], v[170:173], v[202:205], v[0:3]
	v_mfma_f32_16x16x32_bf16 v[52:55], v[166:169], v[182:185], v[52:55]
	v_mfma_f32_16x16x32_bf16 v[44:47], v[174:177], v[182:185], v[44:47]
	v_mfma_f32_16x16x32_bf16 v[36:39], v[166:169], v[190:193], v[36:39]
	v_mfma_f32_16x16x32_bf16 v[28:31], v[174:177], v[190:193], v[28:31]
	v_mfma_f32_16x16x32_bf16 v[20:23], v[166:169], v[198:201], v[20:23]
	v_mfma_f32_16x16x32_bf16 v[12:15], v[174:177], v[198:201], v[12:15]
	v_mfma_f32_16x16x32_bf16 v[4:7], v[166:169], v[206:209], v[4:7]
	v_mfma_f32_16x16x32_bf16 v[0:3], v[174:177], v[206:209], v[0:3]
	s_setprio 0
	s_barrier
	v_add_u32_e32 v140, s37, v162
	v_add_u32_e32 v174, s26, v162
	ds_read_b128 v[128:131], v140
	ds_read_b128 v[132:135], v140 offset:1024
	ds_read_b128 v[136:139], v140 offset:2048
	ds_read_b128 v[140:143], v140 offset:3072
	ds_read_b128 v[156:159], v174
	ds_read_b128 v[166:169], v174 offset:1024
	ds_read_b128 v[170:173], v174 offset:2048
	ds_read_b128 v[174:177], v174 offset:3072
	s_mov_b32 m0, s19
	v_lshl_add_u64 v[222:223], s[82:83], 0, v[150:151]
	ds_read_b128 v[178:181], v165 offset:32768
	ds_read_b128 v[182:185], v165 offset:33792
	ds_read_b128 v[186:189], v165 offset:34816
	ds_read_b128 v[190:193], v165 offset:35840
	ds_read_b128 v[194:197], v165 offset:36864
	ds_read_b128 v[198:201], v165 offset:37888
	ds_read_b128 v[202:205], v165 offset:38912
	ds_read_b128 v[206:209], v165 offset:39936
	global_load_lds_dwordx4 v[222:223], off
	v_lshl_add_u64 v[222:223], s[82:83], 0, v[146:147]
	s_mov_b32 m0, s21
	s_nop 0
	global_load_lds_dwordx4 v[222:223], off
	s_waitcnt vmcnt(8)
	s_waitcnt lgkmcnt(0)
	s_barrier
	s_setprio 1
	v_mfma_f32_16x16x32_bf16 v[124:127], v[128:131], v[178:181], v[124:127]
	v_mfma_f32_16x16x32_bf16 v[120:123], v[136:139], v[178:181], v[120:123]
	v_mfma_f32_16x16x32_bf16 v[116:119], v[128:131], v[186:189], v[116:119]
	v_mfma_f32_16x16x32_bf16 v[112:115], v[136:139], v[186:189], v[112:115]
	v_mfma_f32_16x16x32_bf16 v[108:111], v[128:131], v[194:197], v[108:111]
	v_mfma_f32_16x16x32_bf16 v[100:103], v[136:139], v[194:197], v[100:103]
	v_mfma_f32_16x16x32_bf16 v[92:95], v[128:131], v[202:205], v[92:95]
	v_mfma_f32_16x16x32_bf16 v[84:87], v[136:139], v[202:205], v[84:87]
	v_mfma_f32_16x16x32_bf16 v[124:127], v[132:135], v[182:185], v[124:127]
	v_mfma_f32_16x16x32_bf16 v[120:123], v[140:143], v[182:185], v[120:123]
	v_mfma_f32_16x16x32_bf16 v[116:119], v[132:135], v[190:193], v[116:119]
	v_mfma_f32_16x16x32_bf16 v[112:115], v[140:143], v[190:193], v[112:115]
	v_mfma_f32_16x16x32_bf16 v[108:111], v[132:135], v[198:201], v[108:111]
	v_mfma_f32_16x16x32_bf16 v[100:103], v[140:143], v[198:201], v[100:103]
	v_mfma_f32_16x16x32_bf16 v[92:95], v[132:135], v[206:209], v[92:95]
	v_mfma_f32_16x16x32_bf16 v[84:87], v[140:143], v[206:209], v[84:87]
	s_setprio 0
	s_setprio 1
	v_mfma_f32_16x16x32_bf16 v[104:107], v[156:159], v[178:181], v[104:107]
	v_mfma_f32_16x16x32_bf16 v[96:99], v[170:173], v[178:181], v[96:99]
	v_mfma_f32_16x16x32_bf16 v[88:91], v[156:159], v[186:189], v[88:91]
	v_mfma_f32_16x16x32_bf16 v[80:83], v[170:173], v[186:189], v[80:83]
	v_mfma_f32_16x16x32_bf16 v[76:79], v[156:159], v[194:197], v[76:79]
	v_mfma_f32_16x16x32_bf16 v[72:75], v[170:173], v[194:197], v[72:75]
	v_mfma_f32_16x16x32_bf16 v[68:71], v[156:159], v[202:205], v[68:71]
	v_mfma_f32_16x16x32_bf16 v[64:67], v[170:173], v[202:205], v[64:67]
	v_mfma_f32_16x16x32_bf16 v[104:107], v[166:169], v[182:185], v[104:107]
	v_mfma_f32_16x16x32_bf16 v[96:99], v[174:177], v[182:185], v[96:99]
	v_mfma_f32_16x16x32_bf16 v[88:91], v[166:169], v[190:193], v[88:91]
	v_mfma_f32_16x16x32_bf16 v[80:83], v[174:177], v[190:193], v[80:83]
	v_mfma_f32_16x16x32_bf16 v[76:79], v[166:169], v[198:201], v[76:79]
	v_mfma_f32_16x16x32_bf16 v[72:75], v[174:177], v[198:201], v[72:75]
	v_mfma_f32_16x16x32_bf16 v[68:71], v[166:169], v[206:209], v[68:71]
	v_mfma_f32_16x16x32_bf16 v[64:67], v[174:177], v[206:209], v[64:67]
	s_setprio 0
	s_barrier
; #define PG8_STAGE(bufoff, gbase, voff) do { _Pragma("unroll") for (int _i = 0; _i < 2; ++_i) \
;         __builtin_amdgcn_global_load_lds((const unsigned*)((const char*)(gbase) + (voff)[_i]), (LAS unsigned*)(lds + (bufoff) + ldsw + _i * 8192), 16, 0, 0); } while (0)
; #define PG8_LDA(dst, b, h) do { _Pragma("unroll") for (int m = 0; m < 4; ++m) _Pragma("unroll") for (int k = 0; k < 2; ++k) dst[m][k] = *(const LAS bf16x8*)(lds + PG8_SA(b, h) + aoff + m * 2048 + k * 1024); } while (0)
; #define PG8_MMA(ai, bj, At, Bt) do { __builtin_amdgcn_s_setprio(1); _Pragma("unroll") for (int m = 0; m < 4; ++m) _Pragma("unroll") for (int n = 0; n < 2; ++n) _Pragma("unroll") for (int k = 0; k < 2; ++k) \
;         acc[ai][bj][m][n] = __builtin_amdgcn_mfma_f32_16x16x32_bf16(Bt[n][k], At[m][k], acc[ai][bj][m][n], 0, 0, 0); __builtin_amdgcn_s_setprio(0); } while (0)
; #define PG8_WAIT_V(n) asm volatile("s_waitcnt vmcnt(" #n ")" ::: "memory")
; #define PG8_WAIT_L(n) asm volatile("s_waitcnt lgkmcnt(" #n ")" ::: "memory")
; #define PG8_BAR __builtin_amdgcn_s_barrier()
; #define PG8_SCHED __builtin_amdgcn_sched_barrier(0)
; template <class Epi, class Sched>
; __device__ __forceinline__ void gemm_phase(LAS unsigned char* lds, const Gemm g, const Sched& S, const Epi& E) {
;     ...
;             PG8_WAIT_V(8); PG8_WAIT_L(0); PG8_BAR; PG8_MMA(0, 0, At, B0); PG8_MMA(0, 1, At, B1); PG8_BAR; PG8_SCHED;
;             PG8_LDA(At, 1, 1); PG8_STAGE(PG8_SB(1, 0), b3, voffB); PG8_STAGE(PG8_SB(1, 1), b3 + hstepB, voffB); PG8_STAGE(PG8_SA(1, 0), a3, voffA);
;             PG8_WAIT_V(8); PG8_WAIT_L(0); PG8_BAR; PG8_MMA(1, 0, At, B0); PG8_MMA(1, 1, At, B1); PG8_BAR; PG8_SCHED;
;         }
;         if (wr == 0) PG8_BAR;
	s_mov_b32 m0, s93
	v_lshl_add_u64 v[210:211], v[210:211], 0, s[8:9]
	ds_read_b128 v[178:181], v165 offset:49152
	ds_read_b128 v[182:185], v165 offset:50176
	ds_read_b128 v[186:189], v165 offset:51200
	ds_read_b128 v[190:193], v165 offset:52224
	ds_read_b128 v[194:197], v165 offset:53248
	ds_read_b128 v[198:201], v165 offset:54272
	ds_read_b128 v[202:205], v165 offset:55296
	ds_read_b128 v[206:209], v165 offset:56320
	global_load_lds_dwordx4 v[210:211], off
	v_lshl_add_u64 v[210:211], v[216:217], 0, s[8:9]
	s_mov_b32 m0, s73
	s_nop 0
	global_load_lds_dwordx4 v[210:211], off
	v_lshl_add_u64 v[210:211], s[80:81], 0, v[148:149]
	s_mov_b32 m0, s92
	s_nop 0
	global_load_lds_dwordx4 v[210:211], off
	v_lshl_add_u64 v[210:211], s[80:81], 0, v[144:145]
	s_mov_b32 m0, s61
	s_nop 0
	global_load_lds_dwordx4 v[210:211], off
	v_lshl_add_u64 v[210:211], v[218:219], 0, s[8:9]
	s_mov_b32 m0, s34
	s_nop 0
	global_load_lds_dwordx4 v[210:211], off
	v_lshl_add_u64 v[210:211], v[220:221], 0, s[8:9]
	s_mov_b32 m0, s35
	s_nop 0
	global_load_lds_dwordx4 v[210:211], off
	s_waitcnt vmcnt(8)
	s_waitcnt lgkmcnt(0)
	s_barrier
	s_setprio 1
	v_mfma_f32_16x16x32_bf16 v[60:63], v[128:131], v[178:181], v[60:63]
	v_mfma_f32_16x16x32_bf16 v[56:59], v[136:139], v[178:181], v[56:59]
	v_mfma_f32_16x16x32_bf16 v[48:51], v[128:131], v[186:189], v[48:51]
	v_mfma_f32_16x16x32_bf16 v[40:43], v[136:139], v[186:189], v[40:43]
	v_mfma_f32_16x16x32_bf16 v[32:35], v[128:131], v[194:197], v[32:35]
	v_mfma_f32_16x16x32_bf16 v[24:27], v[136:139], v[194:197], v[24:27]
	v_mfma_f32_16x16x32_bf16 v[16:19], v[128:131], v[202:205], v[16:19]
	v_mfma_f32_16x16x32_bf16 v[8:11], v[136:139], v[202:205], v[8:11]
	v_mfma_f32_16x16x32_bf16 v[60:63], v[132:135], v[182:185], v[60:63]
	v_mfma_f32_16x16x32_bf16 v[56:59], v[140:143], v[182:185], v[56:59]
	v_mfma_f32_16x16x32_bf16 v[48:51], v[132:135], v[190:193], v[48:51]
	v_mfma_f32_16x16x32_bf16 v[40:43], v[140:143], v[190:193], v[40:43]
	v_mfma_f32_16x16x32_bf16 v[32:35], v[132:135], v[198:201], v[32:35]
	v_mfma_f32_16x16x32_bf16 v[24:27], v[140:143], v[198:201], v[24:27]
	v_mfma_f32_16x16x32_bf16 v[16:19], v[132:135], v[206:209], v[16:19]
	v_mfma_f32_16x16x32_bf16 v[8:11], v[140:143], v[206:209], v[8:11]
	s_setprio 0
	s_setprio 1
	v_mfma_f32_16x16x32_bf16 v[52:55], v[156:159], v[178:181], v[52:55]
	v_mfma_f32_16x16x32_bf16 v[44:47], v[170:173], v[178:181], v[44:47]
	v_mfma_f32_16x16x32_bf16 v[36:39], v[156:159], v[186:189], v[36:39]
	v_mfma_f32_16x16x32_bf16 v[28:31], v[170:173], v[186:189], v[28:31]
	v_mfma_f32_16x16x32_bf16 v[20:23], v[156:159], v[194:197], v[20:23]
	v_mfma_f32_16x16x32_bf16 v[12:15], v[170:173], v[194:197], v[12:15]
	v_mfma_f32_16x16x32_bf16 v[4:7], v[156:159], v[202:205], v[4:7]
	v_mfma_f32_16x16x32_bf16 v[0:3], v[170:173], v[202:205], v[0:3]
	v_mfma_f32_16x16x32_bf16 v[52:55], v[166:169], v[182:185], v[52:55]
	v_mfma_f32_16x16x32_bf16 v[44:47], v[174:177], v[182:185], v[44:47]
	v_mfma_f32_16x16x32_bf16 v[36:39], v[166:169], v[190:193], v[36:39]
	v_mfma_f32_16x16x32_bf16 v[28:31], v[174:177], v[190:193], v[28:31]
	v_mfma_f32_16x16x32_bf16 v[20:23], v[166:169], v[198:201], v[20:23]
	v_mfma_f32_16x16x32_bf16 v[12:15], v[174:177], v[198:201], v[12:15]
	v_mfma_f32_16x16x32_bf16 v[4:7], v[166:169], v[206:209], v[4:7]
	v_mfma_f32_16x16x32_bf16 v[0:3], v[174:177], v[206:209], v[0:3]
	s_setprio 0
	s_barrier
	s_andn2_b64 vcc, exec, s[78:79]
	s_mov_b64 s[80:81], -1
	s_mov_b64 s[78:79], 0
	s_mov_b64 s[82:83], 0x100
	s_cbranch_vccz .LBB0_531
	v_readlane_b32 s80, v248, 11
	s_and_b64 vcc, exec, s[56:57]
	v_readlane_b32 s81, v248, 12
	v_readlane_b32 s82, v248, 13
	v_readlane_b32 s83, v248, 14
	v_readlane_b32 s84, v248, 15
	v_readlane_b32 s85, v248, 16
	v_readlane_b32 s86, v248, 17
	v_readlane_b32 s87, v248, 18
	v_readlane_b32 s88, v248, 19
	v_readlane_b32 s89, v248, 20
	v_readlane_b32 s90, v248, 21
	v_readlane_b32 s91, v248, 22
	v_readlane_b32 s92, v248, 23
	v_readlane_b32 s93, v248, 24
	v_readlane_b32 s94, v248, 25
	v_readlane_b32 s95, v248, 26
	s_cbranch_vccz .LBB0_534
	s_barrier

; #define PG8_STAGE(bufoff, gbase, voff) do { _Pragma("unroll") for (int _i = 0; _i < 2; ++_i) \
;         __builtin_amdgcn_global_load_lds((const unsigned*)((const char*)(gbase) + (voff)[_i]), (LAS unsigned*)(lds + (bufoff) + ldsw + _i * 8192), 16, 0, 0); } while (0)
; #define PG8_LDA(dst, b, h) do { _Pragma("unroll") for (int m = 0; m < 4; ++m) _Pragma("unroll") for (int k = 0; k < 2; ++k) dst[m][k] = *(const LAS bf16x8*)(lds + PG8_SA(b, h) + aoff + m * 2048 + k * 1024); } while (0)
; #define PG8_LDB(dst, b, h) do { _Pragma("unroll") for (int n = 0; n < 2; ++n) _Pragma("unroll") for (int k = 0; k < 2; ++k) dst[n][k] = *(const LAS bf16x8*)(lds + PG8_SB(b, h) + boff + n * 2048 + k * 1024); } while (0)
; #define PG8_MMA(ai, bj, At, Bt) do { __builtin_amdgcn_s_setprio(1); _Pragma("unroll") for (int m = 0; m < 4; ++m) _Pragma("unroll") for (int n = 0; n < 2; ++n) _Pragma("unroll") for (int k = 0; k < 2; ++k) \
;         acc[ai][bj][m][n] = __builtin_amdgcn_mfma_f32_16x16x32_bf16(Bt[n][k], At[m][k], acc[ai][bj][m][n], 0, 0, 0); __builtin_amdgcn_s_setprio(0); } while (0)
; #define PG8_WAIT_V(n) asm volatile("s_waitcnt vmcnt(" #n ")" ::: "memory")
; #define PG8_WAIT_L(n) asm volatile("s_waitcnt lgkmcnt(" #n ")" ::: "memory")
; #define PG8_BAR __builtin_amdgcn_s_barrier()
; #define PG8_SCHED __builtin_amdgcn_sched_barrier(0)
; template <class Epi, class Sched>
; __device__ __forceinline__ void gemm_phase(LAS unsigned char* lds, const Gemm g, const Sched& S, const Epi& E) {
;     ...
;             const bool last = (t == nt - 2);
;             const char* a1 = cA + (size_t)(t + 1) * kstep;
;             const char* a2 = last ? nA : cA + (size_t)(t + 2) * kstep; const char* b2 = last ? nB : cB + (size_t)(t + 2) * kstep;
;             const char* a3 = a2 + kstep; const char* b3 = b2 + kstep;
;             PG8_LDB(B0, 0, 0); PG8_LDB(B1, 0, 1); PG8_SCHED; PG8_LDA(At, 0, 0); PG8_STAGE(PG8_SA(1, 1), a1 + hstepA, voffA);
;             PG8_WAIT_V(8); PG8_WAIT_L(0); PG8_BAR; PG8_MMA(0, 0, At, B0); PG8_MMA(0, 1, At, B1); PG8_BAR; PG8_SCHED;
;             PG8_LDA(At, 0, 1); PG8_STAGE(PG8_SB(0, 0), b2, voffB); PG8_STAGE(PG8_SB(0, 1), b2 + hstepB, voffB); PG8_STAGE(PG8_SA(0, 0), a2, voffA);
;             PG8_WAIT_V(8); PG8_WAIT_L(0); PG8_BAR; PG8_MMA(1, 0, At, B0); PG8_MMA(1, 1, At, B1); PG8_BAR; PG8_SCHED;
.LBB0_553:
	s_add_u32 s35, s78, s82
	s_addc_u32 s45, s79, s83
	s_add_u32 s63, s35, 0x100
	s_addc_u32 s65, s45, 0
	s_and_b64 s[48:49], s[80:81], exec
	s_cselect_b32 s85, s71, s65
	s_cselect_b32 s84, s70, s63
	s_add_u32 s48, s76, s82
	s_addc_u32 s49, s77, s83
	s_add_u32 s63, s48, 0x100
	s_addc_u32 s65, s49, 0
	s_and_b64 s[48:49], s[80:81], exec
	s_cselect_b32 s87, s31, s65
	s_cselect_b32 s86, s34, s63
	s_add_u32 s90, s35, 0x80080
	ds_read_b128 v[64:67], v218
	ds_read_b128 v[68:71], v218 offset:1024
	ds_read_b128 v[72:75], v218 offset:2048
	ds_read_b128 v[80:83], v218 offset:3072
	ds_read_b128 v[88:91], v219
	ds_read_b128 v[92:95], v219 offset:1024
	ds_read_b128 v[100:103], v219 offset:2048
	ds_read_b128 v[108:111], v219 offset:3072
	s_addc_u32 s91, s45, 0
	s_add_i32 s75, s33, s12
	s_add_i32 m0, s13, 0xc000
	s_add_i32 s92, s13, 0xe000
	s_add_i32 s63, s75, 0x2000
	s_add_u32 s88, s86, 0x10000
	s_addc_u32 s89, s87, 0
	s_add_i32 s67, s36, s12
	s_add_i32 s65, s67, 0x2000
	s_add_u32 s82, s84, 0x80000
	s_addc_u32 s83, s85, 0
	s_add_i32 s49, s37, s12
	s_add_i32 s45, s49, 0x2000
	s_add_u32 s80, s86, 0x10080
	s_addc_u32 s81, s87, 0
	s_add_i32 s48, s26, s12
	s_add_i32 s35, s48, 0x2000
	v_lshl_add_u64 v[204:205], s[90:91], 0, v[190:191]
	ds_read_b128 v[128:131], v220
	ds_read_b128 v[148:151], v220 offset:1024
	ds_read_b128 v[164:167], v220 offset:2048
	ds_read_b128 v[172:175], v220 offset:3072
	ds_read_b128 v[176:179], v220 offset:4096
	ds_read_b128 v[180:183], v220 offset:5120
	ds_read_b128 v[196:199], v220 offset:6144
	ds_read_b128 v[200:203], v220 offset:7168
	global_load_lds_dwordx4 v[204:205], off
	v_lshl_add_u64 v[204:205], s[90:91], 0, v[186:187]
	s_mov_b32 m0, s92
	s_nop 0
	global_load_lds_dwordx4 v[204:205], off
	s_waitcnt vmcnt(8)
	s_waitcnt lgkmcnt(0)
	s_barrier
	s_setprio 1
	v_mfma_f32_16x16x32_bf16 v[168:171], v[64:67], v[128:131], v[168:171]
	v_mfma_f32_16x16x32_bf16 v[156:159], v[72:75], v[128:131], v[156:159]
	v_mfma_f32_16x16x32_bf16 v[144:147], v[64:67], v[164:167], v[144:147]
	v_mfma_f32_16x16x32_bf16 v[136:139], v[72:75], v[164:167], v[136:139]
	v_mfma_f32_16x16x32_bf16 v[124:127], v[64:67], v[176:179], v[124:127]
	v_mfma_f32_16x16x32_bf16 v[116:119], v[72:75], v[176:179], v[116:119]
	v_mfma_f32_16x16x32_bf16 v[104:107], v[64:67], v[196:199], v[104:107]
	v_mfma_f32_16x16x32_bf16 v[84:87], v[72:75], v[196:199], v[84:87]
	v_mfma_f32_16x16x32_bf16 v[168:171], v[68:71], v[148:151], v[168:171]
	v_mfma_f32_16x16x32_bf16 v[156:159], v[80:83], v[148:151], v[156:159]
	v_mfma_f32_16x16x32_bf16 v[144:147], v[68:71], v[172:175], v[144:147]
	v_mfma_f32_16x16x32_bf16 v[136:139], v[80:83], v[172:175], v[136:139]
	v_mfma_f32_16x16x32_bf16 v[124:127], v[68:71], v[180:183], v[124:127]
	v_mfma_f32_16x16x32_bf16 v[116:119], v[80:83], v[180:183], v[116:119]
	v_mfma_f32_16x16x32_bf16 v[104:107], v[68:71], v[200:203], v[104:107]
	v_mfma_f32_16x16x32_bf16 v[84:87], v[80:83], v[200:203], v[84:87]
	s_setprio 0
	s_setprio 1
	v_mfma_f32_16x16x32_bf16 v[160:163], v[88:91], v[128:131], v[160:163]
	v_mfma_f32_16x16x32_bf16 v[140:143], v[88:91], v[164:167], v[140:143]
	v_mfma_f32_16x16x32_bf16 v[132:135], v[100:103], v[164:167], v[132:135]
	v_mfma_f32_16x16x32_bf16 v[120:123], v[88:91], v[176:179], v[120:123]
	v_mfma_f32_16x16x32_bf16 v[112:115], v[100:103], v[176:179], v[112:115]
	v_mfma_f32_16x16x32_bf16 v[96:99], v[88:91], v[196:199], v[96:99]
	v_mfma_f32_16x16x32_bf16 v[76:79], v[100:103], v[196:199], v[76:79]
	v_mfma_f32_16x16x32_bf16 v[160:163], v[92:95], v[148:151], v[160:163]
	v_mfma_f32_16x16x32_bf16 v[128:131], v[100:103], v[128:131], v[152:155]
	v_mfma_f32_16x16x32_bf16 v[140:143], v[92:95], v[172:175], v[140:143]
	v_mfma_f32_16x16x32_bf16 v[132:135], v[108:111], v[172:175], v[132:135]
	v_mfma_f32_16x16x32_bf16 v[120:123], v[92:95], v[180:183], v[120:123]
	v_mfma_f32_16x16x32_bf16 v[112:115], v[108:111], v[180:183], v[112:115]
	v_mfma_f32_16x16x32_bf16 v[96:99], v[92:95], v[200:203], v[96:99]
	v_mfma_f32_16x16x32_bf16 v[76:79], v[108:111], v[200:203], v[76:79]
	v_mfma_f32_16x16x32_bf16 v[128:131], v[108:111], v[148:151], v[128:131]
	s_setprio 0
	s_barrier
	s_mov_b32 m0, s75
	v_lshl_add_u64 v[204:205], s[86:87], 0, v[188:189]
	ds_read_b128 v[148:151], v220 offset:16384
	ds_read_b128 v[152:155], v220 offset:17408
	ds_read_b128 v[164:167], v220 offset:18432
	ds_read_b128 v[172:175], v220 offset:19456
	ds_read_b128 v[176:179], v220 offset:20480
	ds_read_b128 v[180:183], v220 offset:21504
	ds_read_b128 v[196:199], v220 offset:22528
	ds_read_b128 v[200:203], v220 offset:23552
	global_load_lds_dwordx4 v[204:205], off
	v_lshl_add_u64 v[206:207], s[86:87], 0, v[184:185]
	s_mov_b32 m0, s63
	v_lshl_add_u64 v[208:209], s[88:89], 0, v[188:189]
	global_load_lds_dwordx4 v[206:207], off
	s_mov_b32 m0, s67
	v_lshl_add_u64 v[210:211], s[84:85], 0, v[186:187]
	global_load_lds_dwordx4 v[208:209], off
	v_lshl_add_u64 v[208:209], s[88:89], 0, v[184:185]
	s_mov_b32 m0, s65
	s_nop 0
	global_load_lds_dwordx4 v[208:209], off
	v_lshl_add_u64 v[208:209], s[84:85], 0, v[190:191]
	s_mov_b32 m0, s13
	s_nop 0
	global_load_lds_dwordx4 v[208:209], off
	s_mov_b32 m0, s14
	s_nop 0
	global_load_lds_dwordx4 v[210:211], off
	s_waitcnt vmcnt(8)
	s_waitcnt lgkmcnt(0)
	s_barrier
; #define PG8_STAGE(bufoff, gbase, voff) do { _Pragma("unroll") for (int _i = 0; _i < 2; ++_i) \
;         __builtin_amdgcn_global_load_lds((const unsigned*)((const char*)(gbase) + (voff)[_i]), (LAS unsigned*)(lds + (bufoff) + ldsw + _i * 8192), 16, 0, 0); } while (0)
; #define PG8_LDA(dst, b, h) do { _Pragma("unroll") for (int m = 0; m < 4; ++m) _Pragma("unroll") for (int k = 0; k < 2; ++k) dst[m][k] = *(const LAS bf16x8*)(lds + PG8_SA(b, h) + aoff + m * 2048 + k * 1024); } while (0)
; #define PG8_LDB(dst, b, h) do { _Pragma("unroll") for (int n = 0; n < 2; ++n) _Pragma("unroll") for (int k = 0; k < 2; ++k) dst[n][k] = *(const LAS bf16x8*)(lds + PG8_SB(b, h) + boff + n * 2048 + k * 1024); } while (0)
; #define PG8_MMA(ai, bj, At, Bt) do { __builtin_amdgcn_s_setprio(1); _Pragma("unroll") for (int m = 0; m < 4; ++m) _Pragma("unroll") for (int n = 0; n < 2; ++n) _Pragma("unroll") for (int k = 0; k < 2; ++k) \
;         acc[ai][bj][m][n] = __builtin_amdgcn_mfma_f32_16x16x32_bf16(Bt[n][k], At[m][k], acc[ai][bj][m][n], 0, 0, 0); __builtin_amdgcn_s_setprio(0); } while (0)
; #define PG8_WAIT_V(n) asm volatile("s_waitcnt vmcnt(" #n ")" ::: "memory")
; #define PG8_WAIT_L(n) asm volatile("s_waitcnt lgkmcnt(" #n ")" ::: "memory")
; #define PG8_BAR __builtin_amdgcn_s_barrier()
; #define PG8_SCHED __builtin_amdgcn_sched_barrier(0)
; template <class Epi, class Sched>
; __device__ __forceinline__ void gemm_phase(LAS unsigned char* lds, const Gemm g, const Sched& S, const Epi& E) {
;     ...
;             PG8_LDA(At, 0, 1); PG8_STAGE(PG8_SB(0, 0), b2, voffB); PG8_STAGE(PG8_SB(0, 1), b2 + hstepB, voffB); PG8_STAGE(PG8_SA(0, 0), a2, voffA);
;             PG8_WAIT_V(8); PG8_WAIT_L(0); PG8_BAR; PG8_MMA(1, 0, At, B0); PG8_MMA(1, 1, At, B1); PG8_BAR; PG8_SCHED;
;             PG8_LDB(B0, 1, 0); PG8_LDB(B1, 1, 1); PG8_SCHED; PG8_LDA(At, 1, 0); PG8_STAGE(PG8_SA(0, 1), a2 + hstepA, voffA);
;             PG8_WAIT_V(8); PG8_WAIT_L(0); PG8_BAR; PG8_MMA(0, 0, At, B0); PG8_MMA(0, 1, At, B1); PG8_BAR; PG8_SCHED;
	s_setprio 1
	v_mfma_f32_16x16x32_bf16 v[60:63], v[64:67], v[148:151], v[60:63]
	v_mfma_f32_16x16x32_bf16 v[52:55], v[72:75], v[148:151], v[52:55]
	v_mfma_f32_16x16x32_bf16 v[44:47], v[64:67], v[164:167], v[44:47]
	v_mfma_f32_16x16x32_bf16 v[36:39], v[72:75], v[164:167], v[36:39]
	v_mfma_f32_16x16x32_bf16 v[28:31], v[64:67], v[176:179], v[28:31]
	v_mfma_f32_16x16x32_bf16 v[20:23], v[72:75], v[176:179], v[20:23]
	v_mfma_f32_16x16x32_bf16 v[12:15], v[64:67], v[196:199], v[12:15]
	v_mfma_f32_16x16x32_bf16 v[4:7], v[72:75], v[196:199], v[4:7]
	v_mfma_f32_16x16x32_bf16 v[60:63], v[68:71], v[152:155], v[60:63]
	v_mfma_f32_16x16x32_bf16 v[52:55], v[80:83], v[152:155], v[52:55]
	v_mfma_f32_16x16x32_bf16 v[44:47], v[68:71], v[172:175], v[44:47]
	v_mfma_f32_16x16x32_bf16 v[36:39], v[80:83], v[172:175], v[36:39]
	v_mfma_f32_16x16x32_bf16 v[28:31], v[68:71], v[180:183], v[28:31]
	v_mfma_f32_16x16x32_bf16 v[20:23], v[80:83], v[180:183], v[20:23]
	v_mfma_f32_16x16x32_bf16 v[12:15], v[68:71], v[200:203], v[12:15]
	v_mfma_f32_16x16x32_bf16 v[4:7], v[80:83], v[200:203], v[4:7]
	s_setprio 0
	s_setprio 1
	v_mfma_f32_16x16x32_bf16 v[56:59], v[88:91], v[148:151], v[56:59]
	v_mfma_f32_16x16x32_bf16 v[48:51], v[100:103], v[148:151], v[48:51]
	v_mfma_f32_16x16x32_bf16 v[40:43], v[88:91], v[164:167], v[40:43]
	v_mfma_f32_16x16x32_bf16 v[32:35], v[100:103], v[164:167], v[32:35]
	v_mfma_f32_16x16x32_bf16 v[24:27], v[88:91], v[176:179], v[24:27]
	v_mfma_f32_16x16x32_bf16 v[16:19], v[100:103], v[176:179], v[16:19]
	v_mfma_f32_16x16x32_bf16 v[8:11], v[88:91], v[196:199], v[8:11]
	v_mfma_f32_16x16x32_bf16 v[0:3], v[100:103], v[196:199], v[0:3]
	v_mfma_f32_16x16x32_bf16 v[56:59], v[92:95], v[152:155], v[56:59]
	v_mfma_f32_16x16x32_bf16 v[48:51], v[108:111], v[152:155], v[48:51]
	v_mfma_f32_16x16x32_bf16 v[40:43], v[92:95], v[172:175], v[40:43]
	v_mfma_f32_16x16x32_bf16 v[32:35], v[108:111], v[172:175], v[32:35]
	v_mfma_f32_16x16x32_bf16 v[24:27], v[92:95], v[180:183], v[24:27]
	v_mfma_f32_16x16x32_bf16 v[16:19], v[108:111], v[180:183], v[16:19]
	v_mfma_f32_16x16x32_bf16 v[8:11], v[92:95], v[200:203], v[8:11]
	v_mfma_f32_16x16x32_bf16 v[0:3], v[108:111], v[200:203], v[0:3]
	s_setprio 0
	s_barrier
	v_add_u32_e32 v80, s37, v217
	v_add_u32_e32 v108, s26, v217
	ds_read_b128 v[64:67], v80
	ds_read_b128 v[68:71], v80 offset:1024
	ds_read_b128 v[72:75], v80 offset:2048
	ds_read_b128 v[80:83], v80 offset:3072
	ds_read_b128 v[88:91], v108
	ds_read_b128 v[92:95], v108 offset:1024
	ds_read_b128 v[100:103], v108 offset:2048
	ds_read_b128 v[108:111], v108 offset:3072
	s_mov_b32 m0, s15
	v_lshl_add_u64 v[222:223], s[82:83], 0, v[190:191]
	ds_read_b128 v[148:151], v220 offset:32768
	ds_read_b128 v[152:155], v220 offset:33792
	ds_read_b128 v[164:167], v220 offset:34816
	ds_read_b128 v[172:175], v220 offset:35840
	ds_read_b128 v[176:179], v220 offset:36864
	ds_read_b128 v[180:183], v220 offset:37888
	ds_read_b128 v[196:199], v220 offset:38912
	ds_read_b128 v[200:203], v220 offset:39936
	global_load_lds_dwordx4 v[222:223], off
	v_lshl_add_u64 v[222:223], s[82:83], 0, v[186:187]
	s_mov_b32 m0, s18
	s_nop 0
	global_load_lds_dwordx4 v[222:223], off
	s_waitcnt vmcnt(8)
	s_waitcnt lgkmcnt(0)
	s_barrier
	s_setprio 1
	v_mfma_f32_16x16x32_bf16 v[168:171], v[64:67], v[148:151], v[168:171]
	v_mfma_f32_16x16x32_bf16 v[156:159], v[72:75], v[148:151], v[156:159]
	v_mfma_f32_16x16x32_bf16 v[144:147], v[64:67], v[164:167], v[144:147]
	v_mfma_f32_16x16x32_bf16 v[136:139], v[72:75], v[164:167], v[136:139]
	v_mfma_f32_16x16x32_bf16 v[124:127], v[64:67], v[176:179], v[124:127]
	v_mfma_f32_16x16x32_bf16 v[116:119], v[72:75], v[176:179], v[116:119]
	v_mfma_f32_16x16x32_bf16 v[104:107], v[64:67], v[196:199], v[104:107]
	v_mfma_f32_16x16x32_bf16 v[84:87], v[72:75], v[196:199], v[84:87]
	v_mfma_f32_16x16x32_bf16 v[168:171], v[68:71], v[152:155], v[168:171]
	v_mfma_f32_16x16x32_bf16 v[156:159], v[80:83], v[152:155], v[156:159]
	v_mfma_f32_16x16x32_bf16 v[144:147], v[68:71], v[172:175], v[144:147]
	v_mfma_f32_16x16x32_bf16 v[136:139], v[80:83], v[172:175], v[136:139]
	v_mfma_f32_16x16x32_bf16 v[124:127], v[68:71], v[180:183], v[124:127]
	v_mfma_f32_16x16x32_bf16 v[116:119], v[80:83], v[180:183], v[116:119]
	v_mfma_f32_16x16x32_bf16 v[104:107], v[68:71], v[200:203], v[104:107]
	v_mfma_f32_16x16x32_bf16 v[84:87], v[80:83], v[200:203], v[84:87]
	s_setprio 0
	s_setprio 1
	v_mfma_f32_16x16x32_bf16 v[160:163], v[88:91], v[148:151], v[160:163]
	v_mfma_f32_16x16x32_bf16 v[128:131], v[100:103], v[148:151], v[128:131]
	v_mfma_f32_16x16x32_bf16 v[160:163], v[92:95], v[152:155], v[160:163]
	v_mfma_f32_16x16x32_bf16 v[152:155], v[108:111], v[152:155], v[128:131]
	v_mfma_f32_16x16x32_bf16 v[128:131], v[88:91], v[164:167], v[140:143]
	v_mfma_f32_16x16x32_bf16 v[140:143], v[92:95], v[172:175], v[128:131]
	v_mfma_f32_16x16x32_bf16 v[128:131], v[100:103], v[164:167], v[132:135]
	v_mfma_f32_16x16x32_bf16 v[120:123], v[88:91], v[176:179], v[120:123]
	v_mfma_f32_16x16x32_bf16 v[112:115], v[100:103], v[176:179], v[112:115]
	v_mfma_f32_16x16x32_bf16 v[96:99], v[88:91], v[196:199], v[96:99]
	v_mfma_f32_16x16x32_bf16 v[76:79], v[100:103], v[196:199], v[76:79]
	v_mfma_f32_16x16x32_bf16 v[132:135], v[108:111], v[172:175], v[128:131]
	v_mfma_f32_16x16x32_bf16 v[120:123], v[92:95], v[180:183], v[120:123]
	v_mfma_f32_16x16x32_bf16 v[112:115], v[108:111], v[180:183], v[112:115]
	v_mfma_f32_16x16x32_bf16 v[96:99], v[92:95], v[200:203], v[96:99]
	v_mfma_f32_16x16x32_bf16 v[76:79], v[108:111], v[200:203], v[76:79]
	s_setprio 0
	s_barrier
; #define PG8_STAGE(bufoff, gbase, voff) do { _Pragma("unroll") for (int _i = 0; _i < 2; ++_i) \
;         __builtin_amdgcn_global_load_lds((const unsigned*)((const char*)(gbase) + (voff)[_i]), (LAS unsigned*)(lds + (bufoff) + ldsw + _i * 8192), 16, 0, 0); } while (0)
; #define PG8_LDA(dst, b, h) do { _Pragma("unroll") for (int m = 0; m < 4; ++m) _Pragma("unroll") for (int k = 0; k < 2; ++k) dst[m][k] = *(const LAS bf16x8*)(lds + PG8_SA(b, h) + aoff + m * 2048 + k * 1024); } while (0)
; #define PG8_MMA(ai, bj, At, Bt) do { __builtin_amdgcn_s_setprio(1); _Pragma("unroll") for (int m = 0; m < 4; ++m) _Pragma("unroll") for (int n = 0; n < 2; ++n) _Pragma("unroll") for (int k = 0; k < 2; ++k) \
;         acc[ai][bj][m][n] = __builtin_amdgcn_mfma_f32_16x16x32_bf16(Bt[n][k], At[m][k], acc[ai][bj][m][n], 0, 0, 0); __builtin_amdgcn_s_setprio(0); } while (0)
; #define PG8_WAIT_V(n) asm volatile("s_waitcnt vmcnt(" #n ")" ::: "memory")
; #define PG8_WAIT_L(n) asm volatile("s_waitcnt lgkmcnt(" #n ")" ::: "memory")
; #define PG8_BAR __builtin_amdgcn_s_barrier()
; #define PG8_SCHED __builtin_amdgcn_sched_barrier(0)
; template <class Epi, class Sched>
; __device__ __forceinline__ void gemm_phase(LAS unsigned char* lds, const Gemm g, const Sched& S, const Epi& E) {
;     ...
;             PG8_WAIT_V(8); PG8_WAIT_L(0); PG8_BAR; PG8_MMA(0, 0, At, B0); PG8_MMA(0, 1, At, B1); PG8_BAR; PG8_SCHED;
;             PG8_LDA(At, 1, 1); PG8_STAGE(PG8_SB(1, 0), b3, voffB); PG8_STAGE(PG8_SB(1, 1), b3 + hstepB, voffB); PG8_STAGE(PG8_SA(1, 0), a3, voffA);
;             PG8_WAIT_V(8); PG8_WAIT_L(0); PG8_BAR; PG8_MMA(1, 0, At, B0); PG8_MMA(1, 1, At, B1); PG8_BAR; PG8_SCHED;
;         }
;         if (wr == 0) PG8_BAR;
	s_mov_b32 m0, s49
	v_lshl_add_u64 v[204:205], v[204:205], 0, s[58:59]
	ds_read_b128 v[128:131], v220 offset:49152
	ds_read_b128 v[148:151], v220 offset:50176
	ds_read_b128 v[164:167], v220 offset:51200
	ds_read_b128 v[172:175], v220 offset:52224
	ds_read_b128 v[176:179], v220 offset:53248
	ds_read_b128 v[180:183], v220 offset:54272
	ds_read_b128 v[196:199], v220 offset:55296
	ds_read_b128 v[200:203], v220 offset:56320
	global_load_lds_dwordx4 v[204:205], off
	v_lshl_add_u64 v[204:205], v[206:207], 0, s[58:59]
	s_mov_b32 m0, s45
	s_nop 0
	global_load_lds_dwordx4 v[204:205], off
	v_lshl_add_u64 v[204:205], s[80:81], 0, v[188:189]
	s_mov_b32 m0, s48
	s_nop 0
	global_load_lds_dwordx4 v[204:205], off
	v_lshl_add_u64 v[204:205], s[80:81], 0, v[184:185]
	s_mov_b32 m0, s35
	s_nop 0
	global_load_lds_dwordx4 v[204:205], off
	v_lshl_add_u64 v[204:205], v[208:209], 0, s[58:59]
	s_mov_b32 m0, s24
	s_nop 0
	global_load_lds_dwordx4 v[204:205], off
	v_lshl_add_u64 v[204:205], v[210:211], 0, s[58:59]
	s_mov_b32 m0, s25
	s_nop 0
	global_load_lds_dwordx4 v[204:205], off
	s_waitcnt vmcnt(8)
	s_waitcnt lgkmcnt(0)
	s_barrier
	s_setprio 1
	v_mfma_f32_16x16x32_bf16 v[60:63], v[64:67], v[128:131], v[60:63]
	v_mfma_f32_16x16x32_bf16 v[52:55], v[72:75], v[128:131], v[52:55]
	v_mfma_f32_16x16x32_bf16 v[44:47], v[64:67], v[164:167], v[44:47]
	v_mfma_f32_16x16x32_bf16 v[36:39], v[72:75], v[164:167], v[36:39]
	v_mfma_f32_16x16x32_bf16 v[28:31], v[64:67], v[176:179], v[28:31]
	v_mfma_f32_16x16x32_bf16 v[20:23], v[72:75], v[176:179], v[20:23]
	v_mfma_f32_16x16x32_bf16 v[12:15], v[64:67], v[196:199], v[12:15]
	v_mfma_f32_16x16x32_bf16 v[4:7], v[72:75], v[196:199], v[4:7]
	v_mfma_f32_16x16x32_bf16 v[60:63], v[68:71], v[148:151], v[60:63]
	v_mfma_f32_16x16x32_bf16 v[52:55], v[80:83], v[148:151], v[52:55]
	v_mfma_f32_16x16x32_bf16 v[44:47], v[68:71], v[172:175], v[44:47]
	v_mfma_f32_16x16x32_bf16 v[36:39], v[80:83], v[172:175], v[36:39]
	v_mfma_f32_16x16x32_bf16 v[28:31], v[68:71], v[180:183], v[28:31]
	v_mfma_f32_16x16x32_bf16 v[20:23], v[80:83], v[180:183], v[20:23]
	v_mfma_f32_16x16x32_bf16 v[12:15], v[68:71], v[200:203], v[12:15]
	v_mfma_f32_16x16x32_bf16 v[4:7], v[80:83], v[200:203], v[4:7]
	s_setprio 0
	s_setprio 1
	v_mfma_f32_16x16x32_bf16 v[56:59], v[88:91], v[128:131], v[56:59]
	v_mfma_f32_16x16x32_bf16 v[48:51], v[100:103], v[128:131], v[48:51]
	v_mfma_f32_16x16x32_bf16 v[40:43], v[88:91], v[164:167], v[40:43]
	v_mfma_f32_16x16x32_bf16 v[32:35], v[100:103], v[164:167], v[32:35]
	v_mfma_f32_16x16x32_bf16 v[24:27], v[88:91], v[176:179], v[24:27]
	v_mfma_f32_16x16x32_bf16 v[16:19], v[100:103], v[176:179], v[16:19]
	v_mfma_f32_16x16x32_bf16 v[8:11], v[88:91], v[196:199], v[8:11]
	v_mfma_f32_16x16x32_bf16 v[0:3], v[100:103], v[196:199], v[0:3]
	v_mfma_f32_16x16x32_bf16 v[56:59], v[92:95], v[148:151], v[56:59]
	v_mfma_f32_16x16x32_bf16 v[48:51], v[108:111], v[148:151], v[48:51]
	v_mfma_f32_16x16x32_bf16 v[40:43], v[92:95], v[172:175], v[40:43]
	v_mfma_f32_16x16x32_bf16 v[32:35], v[108:111], v[172:175], v[32:35]
	v_mfma_f32_16x16x32_bf16 v[24:27], v[92:95], v[180:183], v[24:27]
	v_mfma_f32_16x16x32_bf16 v[16:19], v[108:111], v[180:183], v[16:19]
	v_mfma_f32_16x16x32_bf16 v[8:11], v[92:95], v[200:203], v[8:11]
	v_mfma_f32_16x16x32_bf16 v[0:3], v[108:111], v[200:203], v[0:3]
	s_setprio 0
	s_barrier
	s_andn2_b64 vcc, exec, s[0:1]
	s_mov_b64 s[80:81], -1
	s_mov_b64 s[0:1], 0
	s_mov_b64 s[82:83], 0x100
	s_cbranch_vccz .LBB0_553
	s_and_b64 vcc, exec, s[60:61]
	s_cbranch_vccz .LBB0_556
	s_barrier

; #define PG8_STAGE(bufoff, gbase, voff) do { _Pragma("unroll") for (int _i = 0; _i < 2; ++_i) \
;         __builtin_amdgcn_global_load_lds((const unsigned*)((const char*)(gbase) + (voff)[_i]), (LAS unsigned*)(lds + (bufoff) + ldsw + _i * 8192), 16, 0, 0); } while (0)
; #define PG8_LDA(dst, b, h) do { _Pragma("unroll") for (int m = 0; m < 4; ++m) _Pragma("unroll") for (int k = 0; k < 2; ++k) dst[m][k] = *(const LAS bf16x8*)(lds + PG8_SA(b, h) + aoff + m * 2048 + k * 1024); } while (0)
; #define PG8_LDB(dst, b, h) do { _Pragma("unroll") for (int n = 0; n < 2; ++n) _Pragma("unroll") for (int k = 0; k < 2; ++k) dst[n][k] = *(const LAS bf16x8*)(lds + PG8_SB(b, h) + boff + n * 2048 + k * 1024); } while (0)
; #define PG8_MMA(ai, bj, At, Bt) do { __builtin_amdgcn_s_setprio(1); _Pragma("unroll") for (int m = 0; m < 4; ++m) _Pragma("unroll") for (int n = 0; n < 2; ++n) _Pragma("unroll") for (int k = 0; k < 2; ++k) \
;         acc[ai][bj][m][n] = __builtin_amdgcn_mfma_f32_16x16x32_bf16(Bt[n][k], At[m][k], acc[ai][bj][m][n], 0, 0, 0); __builtin_amdgcn_s_setprio(0); } while (0)
; #define PG8_WAIT_V(n) asm volatile("s_waitcnt vmcnt(" #n ")" ::: "memory")
; #define PG8_WAIT_L(n) asm volatile("s_waitcnt lgkmcnt(" #n ")" ::: "memory")
; #define PG8_BAR __builtin_amdgcn_s_barrier()
; #define PG8_SCHED __builtin_amdgcn_sched_barrier(0)
; template <class Epi, class Sched>
; __device__ __forceinline__ void gemm_phase(LAS unsigned char* lds, const Gemm g, const Sched& S, const Epi& E) {
;     ...
;             const bool last = (t == nt - 2);
;             const char* a1 = cA + (size_t)(t + 1) * kstep;
;             const char* a2 = last ? nA : cA + (size_t)(t + 2) * kstep; const char* b2 = last ? nB : cB + (size_t)(t + 2) * kstep;
;             const char* a3 = a2 + kstep; const char* b3 = b2 + kstep;
;             PG8_LDB(B0, 0, 0); PG8_LDB(B1, 0, 1); PG8_SCHED; PG8_LDA(At, 0, 0); PG8_STAGE(PG8_SA(1, 1), a1 + hstepA, voffA);
;             PG8_WAIT_V(8); PG8_WAIT_L(0); PG8_BAR; PG8_MMA(0, 0, At, B0); PG8_MMA(0, 1, At, B1); PG8_BAR; PG8_SCHED;
;             PG8_LDA(At, 0, 1); PG8_STAGE(PG8_SB(0, 0), b2, voffB); PG8_STAGE(PG8_SB(0, 1), b2 + hstepB, voffB); PG8_STAGE(PG8_SA(0, 0), a2, voffA);
;             PG8_WAIT_V(8); PG8_WAIT_L(0); PG8_BAR; PG8_MMA(1, 0, At, B0); PG8_MMA(1, 1, At, B1); PG8_BAR; PG8_SCHED;
.LBB0_752:
	v_add_u32_e32 v1, s33, v166
	ds_read_b128 v[152:155], v1
	ds_read_b128 v[156:159], v1 offset:1024
	ds_read_b128 v[160:163], v1 offset:2048
	ds_read_b128 v[168:171], v1 offset:3072
	v_add_u32_e32 v1, s36, v166
	s_add_u32 s64, s60, s62
	ds_read_b128 v[172:175], v1
	ds_read_b128 v[176:179], v1 offset:1024
	ds_read_b128 v[180:183], v1 offset:2048
	ds_read_b128 v[184:187], v1 offset:3072
	s_addc_u32 s65, s61, s63
	s_add_u32 s64, s64, 0x100
	s_addc_u32 s65, s65, 0
	s_add_u32 s75, s72, s62
	s_addc_u32 s76, s73, s63
	s_cmpk_eq_i32 s62, 0x1700
	s_cselect_b32 s67, s1, s65
	s_cselect_b32 s66, s0, s64
	s_cselect_b32 s65, s59, s76
	s_cselect_b32 s64, s58, s75
	v_lshl_add_u64 v[2:3], v[148:149], 0, s[62:63]
	s_add_i32 m0, s13, 0xc000
	ds_read_b128 v[188:191], v167
	ds_read_b128 v[192:195], v167 offset:1024
	ds_read_b128 v[196:199], v167 offset:2048
	ds_read_b128 v[200:203], v167 offset:3072
	ds_read_b128 v[204:207], v167 offset:4096
	ds_read_b128 v[208:211], v167 offset:5120
	ds_read_b128 v[216:219], v167 offset:6144
	ds_read_b128 v[220:223], v167 offset:7168
	global_load_lds_dwordx4 v[2:3], off
	v_lshl_add_u64 v[2:3], v[150:151], 0, s[62:63]
	s_add_i32 m0, s13, 0xe000
	s_nop 0
	global_load_lds_dwordx4 v[2:3], off
	s_waitcnt vmcnt(8)
	s_waitcnt lgkmcnt(0)
	s_barrier
	s_setprio 1
	v_mfma_f32_16x16x32_bf16 v[128:131], v[152:155], v[188:191], v[128:131]
	v_mfma_f32_16x16x32_bf16 v[124:127], v[160:163], v[188:191], v[124:127]
	v_mfma_f32_16x16x32_bf16 v[112:115], v[152:155], v[196:199], v[112:115]
	v_mfma_f32_16x16x32_bf16 v[108:111], v[160:163], v[196:199], v[108:111]
	v_mfma_f32_16x16x32_bf16 v[96:99], v[152:155], v[204:207], v[96:99]
	v_mfma_f32_16x16x32_bf16 v[92:95], v[160:163], v[204:207], v[92:95]
	v_mfma_f32_16x16x32_bf16 v[80:83], v[152:155], v[216:219], v[80:83]
	v_mfma_f32_16x16x32_bf16 v[76:79], v[160:163], v[216:219], v[76:79]
	v_mfma_f32_16x16x32_bf16 v[128:131], v[156:159], v[192:195], v[128:131]
	v_mfma_f32_16x16x32_bf16 v[124:127], v[168:171], v[192:195], v[124:127]
	v_mfma_f32_16x16x32_bf16 v[112:115], v[156:159], v[200:203], v[112:115]
	v_mfma_f32_16x16x32_bf16 v[108:111], v[168:171], v[200:203], v[108:111]
	v_mfma_f32_16x16x32_bf16 v[96:99], v[156:159], v[208:211], v[96:99]
	v_mfma_f32_16x16x32_bf16 v[92:95], v[168:171], v[208:211], v[92:95]
	v_mfma_f32_16x16x32_bf16 v[80:83], v[156:159], v[220:223], v[80:83]
	v_mfma_f32_16x16x32_bf16 v[76:79], v[168:171], v[220:223], v[76:79]
	s_setprio 0
	s_setprio 1
	v_mfma_f32_16x16x32_bf16 v[120:123], v[172:175], v[188:191], v[120:123]
	v_mfma_f32_16x16x32_bf16 v[116:119], v[180:183], v[188:191], v[116:119]
	v_mfma_f32_16x16x32_bf16 v[104:107], v[172:175], v[196:199], v[104:107]
	v_mfma_f32_16x16x32_bf16 v[100:103], v[180:183], v[196:199], v[100:103]
	v_mfma_f32_16x16x32_bf16 v[88:91], v[172:175], v[204:207], v[88:91]
	v_mfma_f32_16x16x32_bf16 v[84:87], v[180:183], v[204:207], v[84:87]
	v_mfma_f32_16x16x32_bf16 v[72:75], v[172:175], v[216:219], v[72:75]
	v_mfma_f32_16x16x32_bf16 v[68:71], v[180:183], v[216:219], v[68:71]
	v_mfma_f32_16x16x32_bf16 v[120:123], v[176:179], v[192:195], v[120:123]
	v_mfma_f32_16x16x32_bf16 v[116:119], v[184:187], v[192:195], v[116:119]
	v_mfma_f32_16x16x32_bf16 v[104:107], v[176:179], v[200:203], v[104:107]
	v_mfma_f32_16x16x32_bf16 v[100:103], v[184:187], v[200:203], v[100:103]
	v_mfma_f32_16x16x32_bf16 v[88:91], v[176:179], v[208:211], v[88:91]
	v_mfma_f32_16x16x32_bf16 v[84:87], v[184:187], v[208:211], v[84:87]
	v_mfma_f32_16x16x32_bf16 v[72:75], v[176:179], v[220:223], v[72:75]
	v_mfma_f32_16x16x32_bf16 v[68:71], v[184:187], v[220:223], v[68:71]
	s_setprio 0
	s_barrier
	s_add_i32 s75, s33, s12
	v_lshl_add_u64 v[224:225], s[64:65], 0, v[136:137]
	s_mov_b32 m0, s75
	ds_read_b128 v[188:191], v167 offset:16384
	ds_read_b128 v[192:195], v167 offset:17408
	ds_read_b128 v[196:199], v167 offset:18432
	ds_read_b128 v[200:203], v167 offset:19456
	ds_read_b128 v[204:207], v167 offset:20480
	ds_read_b128 v[208:211], v167 offset:21504
	ds_read_b128 v[216:219], v167 offset:22528
	ds_read_b128 v[220:223], v167 offset:23552
	global_load_lds_dwordx4 v[224:225], off
	s_add_i32 m0, s75, 0x2000
	s_add_u32 s76, s64, 0xc0000
	v_lshl_add_u64 v[226:227], s[64:65], 0, v[132:133]
	s_addc_u32 s77, s65, 0
	s_add_i32 s75, s36, s12
	global_load_lds_dwordx4 v[226:227], off
	v_lshl_add_u64 v[2:3], s[76:77], 0, v[136:137]
	s_mov_b32 m0, s75
	v_lshl_add_u64 v[228:229], s[66:67], 0, v[138:139]
	global_load_lds_dwordx4 v[2:3], off
	v_lshl_add_u64 v[2:3], s[76:77], 0, v[132:133]
	s_add_i32 m0, s75, 0x2000
	v_lshl_add_u64 v[230:231], s[66:67], 0, v[134:135]
	global_load_lds_dwordx4 v[2:3], off
	s_mov_b32 m0, s13
	s_nop 0
	global_load_lds_dwordx4 v[228:229], off
	s_mov_b32 m0, s14
	s_nop 0
	global_load_lds_dwordx4 v[230:231], off
	s_waitcnt vmcnt(8)
	s_waitcnt lgkmcnt(0)
	s_barrier
; #define PG8_STAGE(bufoff, gbase, voff) do { _Pragma("unroll") for (int _i = 0; _i < 2; ++_i) \
;         __builtin_amdgcn_global_load_lds((const unsigned*)((const char*)(gbase) + (voff)[_i]), (LAS unsigned*)(lds + (bufoff) + ldsw + _i * 8192), 16, 0, 0); } while (0)
; #define PG8_LDA(dst, b, h) do { _Pragma("unroll") for (int m = 0; m < 4; ++m) _Pragma("unroll") for (int k = 0; k < 2; ++k) dst[m][k] = *(const LAS bf16x8*)(lds + PG8_SA(b, h) + aoff + m * 2048 + k * 1024); } while (0)
; #define PG8_LDB(dst, b, h) do { _Pragma("unroll") for (int n = 0; n < 2; ++n) _Pragma("unroll") for (int k = 0; k < 2; ++k) dst[n][k] = *(const LAS bf16x8*)(lds + PG8_SB(b, h) + boff + n * 2048 + k * 1024); } while (0)
; #define PG8_MMA(ai, bj, At, Bt) do { __builtin_amdgcn_s_setprio(1); _Pragma("unroll") for (int m = 0; m < 4; ++m) _Pragma("unroll") for (int n = 0; n < 2; ++n) _Pragma("unroll") for (int k = 0; k < 2; ++k) \
;         acc[ai][bj][m][n] = __builtin_amdgcn_mfma_f32_16x16x32_bf16(Bt[n][k], At[m][k], acc[ai][bj][m][n], 0, 0, 0); __builtin_amdgcn_s_setprio(0); } while (0)
; #define PG8_WAIT_V(n) asm volatile("s_waitcnt vmcnt(" #n ")" ::: "memory")
; #define PG8_WAIT_L(n) asm volatile("s_waitcnt lgkmcnt(" #n ")" ::: "memory")
; #define PG8_BAR __builtin_amdgcn_s_barrier()
; #define PG8_SCHED __builtin_amdgcn_sched_barrier(0)
; template <class Epi, class Sched>
; __device__ __forceinline__ void gemm_phase(LAS unsigned char* lds, const Gemm g, const Sched& S, const Epi& E) {
;     ...
;             PG8_LDA(At, 0, 1); PG8_STAGE(PG8_SB(0, 0), b2, voffB); PG8_STAGE(PG8_SB(0, 1), b2 + hstepB, voffB); PG8_STAGE(PG8_SA(0, 0), a2, voffA);
;             PG8_WAIT_V(8); PG8_WAIT_L(0); PG8_BAR; PG8_MMA(1, 0, At, B0); PG8_MMA(1, 1, At, B1); PG8_BAR; PG8_SCHED;
;             PG8_LDB(B0, 1, 0); PG8_LDB(B1, 1, 1); PG8_SCHED; PG8_LDA(At, 1, 0); PG8_STAGE(PG8_SA(0, 1), a2 + hstepA, voffA);
;             PG8_WAIT_V(8); PG8_WAIT_L(0); PG8_BAR; PG8_MMA(0, 0, At, B0); PG8_MMA(0, 1, At, B1); PG8_BAR; PG8_SCHED;
	s_setprio 1
	v_mfma_f32_16x16x32_bf16 v[64:67], v[152:155], v[188:191], v[64:67]
	v_mfma_f32_16x16x32_bf16 v[60:63], v[160:163], v[188:191], v[60:63]
	v_mfma_f32_16x16x32_bf16 v[48:51], v[152:155], v[196:199], v[48:51]
	v_mfma_f32_16x16x32_bf16 v[44:47], v[160:163], v[196:199], v[44:47]
	v_mfma_f32_16x16x32_bf16 v[32:35], v[152:155], v[204:207], v[32:35]
	v_mfma_f32_16x16x32_bf16 v[28:31], v[160:163], v[204:207], v[28:31]
	v_mfma_f32_16x16x32_bf16 v[16:19], v[152:155], v[216:219], v[16:19]
	v_mfma_f32_16x16x32_bf16 v[12:15], v[160:163], v[216:219], v[12:15]
	v_mfma_f32_16x16x32_bf16 v[64:67], v[156:159], v[192:195], v[64:67]
	v_mfma_f32_16x16x32_bf16 v[60:63], v[168:171], v[192:195], v[60:63]
	v_mfma_f32_16x16x32_bf16 v[48:51], v[156:159], v[200:203], v[48:51]
	v_mfma_f32_16x16x32_bf16 v[44:47], v[168:171], v[200:203], v[44:47]
	v_mfma_f32_16x16x32_bf16 v[32:35], v[156:159], v[208:211], v[32:35]
	v_mfma_f32_16x16x32_bf16 v[28:31], v[168:171], v[208:211], v[28:31]
	v_mfma_f32_16x16x32_bf16 v[16:19], v[156:159], v[220:223], v[16:19]
	v_mfma_f32_16x16x32_bf16 v[12:15], v[168:171], v[220:223], v[12:15]
	s_setprio 0
	s_setprio 1
	v_mfma_f32_16x16x32_bf16 v[56:59], v[172:175], v[188:191], v[56:59]
	v_mfma_f32_16x16x32_bf16 v[52:55], v[180:183], v[188:191], v[52:55]
	v_mfma_f32_16x16x32_bf16 v[40:43], v[172:175], v[196:199], v[40:43]
	v_mfma_f32_16x16x32_bf16 v[36:39], v[180:183], v[196:199], v[36:39]
	v_mfma_f32_16x16x32_bf16 v[24:27], v[172:175], v[204:207], v[24:27]
	v_mfma_f32_16x16x32_bf16 v[20:23], v[180:183], v[204:207], v[20:23]
	v_mfma_f32_16x16x32_bf16 v[8:11], v[172:175], v[216:219], v[8:11]
	v_mfma_f32_16x16x32_bf16 v[2:5], v[180:183], v[216:219], v[4:7]
	v_mfma_f32_16x16x32_bf16 v[56:59], v[176:179], v[192:195], v[56:59]
	v_mfma_f32_16x16x32_bf16 v[52:55], v[184:187], v[192:195], v[52:55]
	v_mfma_f32_16x16x32_bf16 v[40:43], v[176:179], v[200:203], v[40:43]
	v_mfma_f32_16x16x32_bf16 v[36:39], v[184:187], v[200:203], v[36:39]
	v_mfma_f32_16x16x32_bf16 v[24:27], v[176:179], v[208:211], v[24:27]
	v_mfma_f32_16x16x32_bf16 v[20:23], v[184:187], v[208:211], v[20:23]
	v_mfma_f32_16x16x32_bf16 v[8:11], v[176:179], v[220:223], v[8:11]
	v_mfma_f32_16x16x32_bf16 v[2:5], v[184:187], v[220:223], v[2:5]
	s_setprio 0
	s_barrier
	v_add_u32_e32 v1, s37, v166
	ds_read_b128 v[152:155], v1
	ds_read_b128 v[156:159], v1 offset:1024
	ds_read_b128 v[160:163], v1 offset:2048
	ds_read_b128 v[168:171], v1 offset:3072
	v_add_u32_e32 v1, s26, v166
	ds_read_b128 v[172:175], v1
	ds_read_b128 v[176:179], v1 offset:1024
	ds_read_b128 v[180:183], v1 offset:2048
	ds_read_b128 v[184:187], v1 offset:3072
	s_add_u32 s66, s66, 0xc0000
	s_addc_u32 s67, s67, 0
	s_mov_b32 m0, s15
	v_lshl_add_u64 v[6:7], s[66:67], 0, v[138:139]
	ds_read_b128 v[188:191], v167 offset:32768
	ds_read_b128 v[192:195], v167 offset:33792
	ds_read_b128 v[196:199], v167 offset:34816
	ds_read_b128 v[200:203], v167 offset:35840
	ds_read_b128 v[204:207], v167 offset:36864
	ds_read_b128 v[208:211], v167 offset:37888
	ds_read_b128 v[216:219], v167 offset:38912
	ds_read_b128 v[220:223], v167 offset:39936
	global_load_lds_dwordx4 v[6:7], off
	v_lshl_add_u64 v[6:7], s[66:67], 0, v[134:135]
	s_mov_b32 m0, s19
	s_nop 0
	global_load_lds_dwordx4 v[6:7], off
	s_waitcnt vmcnt(8)
	s_waitcnt lgkmcnt(0)
	s_barrier
	s_setprio 1
	v_mfma_f32_16x16x32_bf16 v[128:131], v[152:155], v[188:191], v[128:131]
	v_mfma_f32_16x16x32_bf16 v[124:127], v[160:163], v[188:191], v[124:127]
	v_mfma_f32_16x16x32_bf16 v[112:115], v[152:155], v[196:199], v[112:115]
	v_mfma_f32_16x16x32_bf16 v[108:111], v[160:163], v[196:199], v[108:111]
	v_mfma_f32_16x16x32_bf16 v[96:99], v[152:155], v[204:207], v[96:99]
	v_mfma_f32_16x16x32_bf16 v[92:95], v[160:163], v[204:207], v[92:95]
	v_mfma_f32_16x16x32_bf16 v[80:83], v[152:155], v[216:219], v[80:83]
	v_mfma_f32_16x16x32_bf16 v[76:79], v[160:163], v[216:219], v[76:79]
	v_mfma_f32_16x16x32_bf16 v[128:131], v[156:159], v[192:195], v[128:131]
	v_mfma_f32_16x16x32_bf16 v[124:127], v[168:171], v[192:195], v[124:127]
	v_mfma_f32_16x16x32_bf16 v[112:115], v[156:159], v[200:203], v[112:115]
	v_mfma_f32_16x16x32_bf16 v[108:111], v[168:171], v[200:203], v[108:111]
	v_mfma_f32_16x16x32_bf16 v[96:99], v[156:159], v[208:211], v[96:99]
	v_mfma_f32_16x16x32_bf16 v[92:95], v[168:171], v[208:211], v[92:95]
	v_mfma_f32_16x16x32_bf16 v[80:83], v[156:159], v[220:223], v[80:83]
	v_mfma_f32_16x16x32_bf16 v[76:79], v[168:171], v[220:223], v[76:79]
	s_setprio 0
	s_setprio 1
	v_mfma_f32_16x16x32_bf16 v[120:123], v[172:175], v[188:191], v[120:123]
	v_mfma_f32_16x16x32_bf16 v[116:119], v[180:183], v[188:191], v[116:119]
	v_mfma_f32_16x16x32_bf16 v[104:107], v[172:175], v[196:199], v[104:107]
	v_mfma_f32_16x16x32_bf16 v[100:103], v[180:183], v[196:199], v[100:103]
	v_mfma_f32_16x16x32_bf16 v[88:91], v[172:175], v[204:207], v[88:91]
	v_mfma_f32_16x16x32_bf16 v[84:87], v[180:183], v[204:207], v[84:87]
	v_mfma_f32_16x16x32_bf16 v[72:75], v[172:175], v[216:219], v[72:75]
	v_mfma_f32_16x16x32_bf16 v[68:71], v[180:183], v[216:219], v[68:71]
	v_mfma_f32_16x16x32_bf16 v[120:123], v[176:179], v[192:195], v[120:123]
	v_mfma_f32_16x16x32_bf16 v[116:119], v[184:187], v[192:195], v[116:119]
	v_mfma_f32_16x16x32_bf16 v[104:107], v[176:179], v[200:203], v[104:107]
	v_mfma_f32_16x16x32_bf16 v[100:103], v[184:187], v[200:203], v[100:103]
	v_mfma_f32_16x16x32_bf16 v[88:91], v[176:179], v[208:211], v[88:91]
	v_mfma_f32_16x16x32_bf16 v[84:87], v[184:187], v[208:211], v[84:87]
	v_mfma_f32_16x16x32_bf16 v[72:75], v[176:179], v[220:223], v[72:75]
	v_mfma_f32_16x16x32_bf16 v[68:71], v[184:187], v[220:223], v[68:71]
	s_setprio 0
	s_barrier
; #define PG8_STAGE(bufoff, gbase, voff) do { _Pragma("unroll") for (int _i = 0; _i < 2; ++_i) \
;         __builtin_amdgcn_global_load_lds((const unsigned*)((const char*)(gbase) + (voff)[_i]), (LAS unsigned*)(lds + (bufoff) + ldsw + _i * 8192), 16, 0, 0); } while (0)
; #define PG8_LDA(dst, b, h) do { _Pragma("unroll") for (int m = 0; m < 4; ++m) _Pragma("unroll") for (int k = 0; k < 2; ++k) dst[m][k] = *(const LAS bf16x8*)(lds + PG8_SA(b, h) + aoff + m * 2048 + k * 1024); } while (0)
; #define PG8_MMA(ai, bj, At, Bt) do { __builtin_amdgcn_s_setprio(1); _Pragma("unroll") for (int m = 0; m < 4; ++m) _Pragma("unroll") for (int n = 0; n < 2; ++n) _Pragma("unroll") for (int k = 0; k < 2; ++k) \
;         acc[ai][bj][m][n] = __builtin_amdgcn_mfma_f32_16x16x32_bf16(Bt[n][k], At[m][k], acc[ai][bj][m][n], 0, 0, 0); __builtin_amdgcn_s_setprio(0); } while (0)
; #define PG8_WAIT_V(n) asm volatile("s_waitcnt vmcnt(" #n ")" ::: "memory")
; #define PG8_WAIT_L(n) asm volatile("s_waitcnt lgkmcnt(" #n ")" ::: "memory")
; #define PG8_BAR __builtin_amdgcn_s_barrier()
; #define PG8_SCHED __builtin_amdgcn_sched_barrier(0)
; template <class Epi, class Sched>
; __device__ __forceinline__ void gemm_phase(LAS unsigned char* lds, const Gemm g, const Sched& S, const Epi& E) {
;     ...
;             PG8_WAIT_V(8); PG8_WAIT_L(0); PG8_BAR; PG8_MMA(0, 0, At, B0); PG8_MMA(0, 1, At, B1); PG8_BAR; PG8_SCHED;
;             PG8_LDA(At, 1, 1); PG8_STAGE(PG8_SB(1, 0), b3, voffB); PG8_STAGE(PG8_SB(1, 1), b3 + hstepB, voffB); PG8_STAGE(PG8_SA(1, 0), a3, voffA);
;             PG8_WAIT_V(8); PG8_WAIT_L(0); PG8_BAR; PG8_MMA(1, 0, At, B0); PG8_MMA(1, 1, At, B1); PG8_BAR; PG8_SCHED;
;         }
	s_add_i32 s66, s37, s12
	v_lshl_add_u64 v[6:7], v[224:225], 0, s[42:43]
	s_mov_b32 m0, s66
	ds_read_b128 v[188:191], v167 offset:49152
	ds_read_b128 v[192:195], v167 offset:50176
	ds_read_b128 v[196:199], v167 offset:51200
	ds_read_b128 v[200:203], v167 offset:52224
	ds_read_b128 v[204:207], v167 offset:53248
	ds_read_b128 v[208:211], v167 offset:54272
	ds_read_b128 v[216:219], v167 offset:55296
	ds_read_b128 v[220:223], v167 offset:56320
	global_load_lds_dwordx4 v[6:7], off
	s_add_i32 m0, s66, 0x2000
	s_add_u32 s64, s64, 0xc0080
	v_lshl_add_u64 v[6:7], v[226:227], 0, s[42:43]
	s_addc_u32 s65, s65, 0
	s_add_i32 s66, s26, s12
	global_load_lds_dwordx4 v[6:7], off
	v_lshl_add_u64 v[6:7], s[64:65], 0, v[136:137]
	s_mov_b32 m0, s66
	s_nop 0
	global_load_lds_dwordx4 v[6:7], off
	v_lshl_add_u64 v[6:7], s[64:65], 0, v[132:133]
	s_add_i32 m0, s66, 0x2000
	s_nop 0
	global_load_lds_dwordx4 v[6:7], off
	v_lshl_add_u64 v[6:7], v[228:229], 0, s[42:43]
	s_mov_b32 m0, s23
	s_nop 0
	global_load_lds_dwordx4 v[6:7], off
	v_lshl_add_u64 v[6:7], v[230:231], 0, s[42:43]
	s_mov_b32 m0, s24
	s_nop 0
	global_load_lds_dwordx4 v[6:7], off
	s_waitcnt vmcnt(8)
	s_waitcnt lgkmcnt(0)
	s_barrier
	s_setprio 1
	v_mfma_f32_16x16x32_bf16 v[64:67], v[152:155], v[188:191], v[64:67]
	v_mfma_f32_16x16x32_bf16 v[60:63], v[160:163], v[188:191], v[60:63]
	v_mfma_f32_16x16x32_bf16 v[48:51], v[152:155], v[196:199], v[48:51]
	v_mfma_f32_16x16x32_bf16 v[44:47], v[160:163], v[196:199], v[44:47]
	v_mfma_f32_16x16x32_bf16 v[32:35], v[152:155], v[204:207], v[32:35]
	v_mfma_f32_16x16x32_bf16 v[28:31], v[160:163], v[204:207], v[28:31]
	v_mfma_f32_16x16x32_bf16 v[16:19], v[152:155], v[216:219], v[16:19]
	v_mfma_f32_16x16x32_bf16 v[12:15], v[160:163], v[216:219], v[12:15]
	v_mfma_f32_16x16x32_bf16 v[64:67], v[156:159], v[192:195], v[64:67]
	v_mfma_f32_16x16x32_bf16 v[60:63], v[168:171], v[192:195], v[60:63]
	v_mfma_f32_16x16x32_bf16 v[48:51], v[156:159], v[200:203], v[48:51]
	v_mfma_f32_16x16x32_bf16 v[44:47], v[168:171], v[200:203], v[44:47]
	v_mfma_f32_16x16x32_bf16 v[32:35], v[156:159], v[208:211], v[32:35]
	v_mfma_f32_16x16x32_bf16 v[28:31], v[168:171], v[208:211], v[28:31]
	v_mfma_f32_16x16x32_bf16 v[16:19], v[156:159], v[220:223], v[16:19]
	v_mfma_f32_16x16x32_bf16 v[12:15], v[168:171], v[220:223], v[12:15]
	s_setprio 0
	s_setprio 1
	v_mfma_f32_16x16x32_bf16 v[56:59], v[172:175], v[188:191], v[56:59]
	v_mfma_f32_16x16x32_bf16 v[52:55], v[180:183], v[188:191], v[52:55]
	v_mfma_f32_16x16x32_bf16 v[40:43], v[172:175], v[196:199], v[40:43]
	v_mfma_f32_16x16x32_bf16 v[36:39], v[180:183], v[196:199], v[36:39]
	v_mfma_f32_16x16x32_bf16 v[24:27], v[172:175], v[204:207], v[24:27]
	v_mfma_f32_16x16x32_bf16 v[20:23], v[180:183], v[204:207], v[20:23]
	v_mfma_f32_16x16x32_bf16 v[6:9], v[172:175], v[216:219], v[8:11]
	v_mfma_f32_16x16x32_bf16 v[2:5], v[180:183], v[216:219], v[2:5]
	v_mfma_f32_16x16x32_bf16 v[56:59], v[176:179], v[192:195], v[56:59]
	v_mfma_f32_16x16x32_bf16 v[52:55], v[184:187], v[192:195], v[52:55]
	v_mfma_f32_16x16x32_bf16 v[40:43], v[176:179], v[200:203], v[40:43]
	v_mfma_f32_16x16x32_bf16 v[36:39], v[184:187], v[200:203], v[36:39]
	v_mfma_f32_16x16x32_bf16 v[24:27], v[176:179], v[208:211], v[24:27]
	v_mfma_f32_16x16x32_bf16 v[20:23], v[184:187], v[208:211], v[20:23]
	v_mfma_f32_16x16x32_bf16 v[8:11], v[176:179], v[220:223], v[6:9]
	v_mfma_f32_16x16x32_bf16 v[4:7], v[184:187], v[220:223], v[2:5]
	s_setprio 0
	s_barrier
	s_add_i32 s74, s74, 2
	s_add_u32 s62, s62, 0x100
	s_addc_u32 s63, s63, 0
	s_cmp_gt_u32 s74, 45
	s_cbranch_scc1 .LBB0_755

; #define PG8_STAGE(bufoff, gbase, voff) do { _Pragma("unroll") for (int _i = 0; _i < 2; ++_i) \
;         __builtin_amdgcn_global_load_lds((const unsigned*)((const char*)(gbase) + (voff)[_i]), (LAS unsigned*)(lds + (bufoff) + ldsw + _i * 8192), 16, 0, 0); } while (0)
; #define PG8_LDA(dst, b, h) do { _Pragma("unroll") for (int m = 0; m < 4; ++m) _Pragma("unroll") for (int k = 0; k < 2; ++k) dst[m][k] = *(const LAS bf16x8*)(lds + PG8_SA(b, h) + aoff + m * 2048 + k * 1024); } while (0)
; #define PG8_LDB(dst, b, h) do { _Pragma("unroll") for (int n = 0; n < 2; ++n) _Pragma("unroll") for (int k = 0; k < 2; ++k) dst[n][k] = *(const LAS bf16x8*)(lds + PG8_SB(b, h) + boff + n * 2048 + k * 1024); } while (0)
; #define PG8_MMA(ai, bj, At, Bt) do { __builtin_amdgcn_s_setprio(1); _Pragma("unroll") for (int m = 0; m < 4; ++m) _Pragma("unroll") for (int n = 0; n < 2; ++n) _Pragma("unroll") for (int k = 0; k < 2; ++k) \
;         acc[ai][bj][m][n] = __builtin_amdgcn_mfma_f32_16x16x32_bf16(Bt[n][k], At[m][k], acc[ai][bj][m][n], 0, 0, 0); __builtin_amdgcn_s_setprio(0); } while (0)
; #define PG8_WAIT_V(n) asm volatile("s_waitcnt vmcnt(" #n ")" ::: "memory")
; #define PG8_WAIT_L(n) asm volatile("s_waitcnt lgkmcnt(" #n ")" ::: "memory")
; #define PG8_BAR __builtin_amdgcn_s_barrier()
; #define PG8_SCHED __builtin_amdgcn_sched_barrier(0)
; template <class Epi, class Sched>
; __device__ __forceinline__ void gemm_phase(LAS unsigned char* lds, const Gemm g, const Sched& S, const Epi& E) {
;     ...
;             const bool last = (t == nt - 2);
;             const char* a1 = cA + (size_t)(t + 1) * kstep;
;             const char* a2 = last ? nA : cA + (size_t)(t + 2) * kstep; const char* b2 = last ? nB : cB + (size_t)(t + 2) * kstep;
;             const char* a3 = a2 + kstep; const char* b3 = b2 + kstep;
;             PG8_LDB(B0, 0, 0); PG8_LDB(B1, 0, 1); PG8_SCHED; PG8_LDA(At, 0, 0); PG8_STAGE(PG8_SA(1, 1), a1 + hstepA, voffA);
;             PG8_WAIT_V(8); PG8_WAIT_L(0); PG8_BAR; PG8_MMA(0, 0, At, B0); PG8_MMA(0, 1, At, B1); PG8_BAR; PG8_SCHED;
;             PG8_LDA(At, 0, 1); PG8_STAGE(PG8_SB(0, 0), b2, voffB); PG8_STAGE(PG8_SB(0, 1), b2 + hstepB, voffB); PG8_STAGE(PG8_SA(0, 0), a2, voffA);
;             PG8_WAIT_V(8); PG8_WAIT_L(0); PG8_BAR; PG8_MMA(1, 0, At, B0); PG8_MMA(1, 1, At, B1); PG8_BAR; PG8_SCHED;
.LBB0_829:
	ds_read_b128 v[128:131], v167
	ds_read_b128 v[132:135], v167 offset:1024
	ds_read_b128 v[170:173], v167 offset:2048
	ds_read_b128 v[176:179], v167 offset:3072
	ds_read_b128 v[180:183], v169
	ds_read_b128 v[184:187], v169 offset:1024
	ds_read_b128 v[188:191], v169 offset:2048
	ds_read_b128 v[192:195], v169 offset:3072
	s_add_u32 s39, s60, 0xfff80080
	s_addc_u32 s43, s61, -1
	s_cmp_eq_u32 s35, 28
	s_cselect_b32 s65, s12, s43
	s_cselect_b32 s64, s13, s39
	s_cselect_b32 s63, s29, s34
	s_cselect_b32 s62, s30, s31
	v_lshl_add_u64 v[152:153], s[60:61], 0, v[144:145]
	s_add_i32 m0, s18, 0xc000
	ds_read_b128 v[196:199], v175
	ds_read_b128 v[200:203], v175 offset:1024
	ds_read_b128 v[204:207], v175 offset:2048
	ds_read_b128 v[208:211], v175 offset:3072
	ds_read_b128 v[216:219], v175 offset:4096
	ds_read_b128 v[220:223], v175 offset:5120
	ds_read_b128 v[224:227], v175 offset:6144
	ds_read_b128 v[228:231], v175 offset:7168
	global_load_lds_dwordx4 v[152:153], off
	v_lshl_add_u64 v[152:153], s[60:61], 0, v[146:147]
	s_add_i32 m0, s18, 0xe000
	s_nop 0
	global_load_lds_dwordx4 v[152:153], off
	s_waitcnt vmcnt(8)
	s_waitcnt lgkmcnt(0)
	s_barrier
	s_setprio 1
	v_mfma_f32_16x16x32_bf16 v[124:127], v[128:131], v[196:199], v[124:127]
	v_mfma_f32_16x16x32_bf16 v[120:123], v[170:173], v[196:199], v[120:123]
	v_mfma_f32_16x16x32_bf16 v[108:111], v[128:131], v[204:207], v[108:111]
	v_mfma_f32_16x16x32_bf16 v[104:107], v[170:173], v[204:207], v[104:107]
	v_mfma_f32_16x16x32_bf16 v[92:95], v[128:131], v[216:219], v[92:95]
	v_mfma_f32_16x16x32_bf16 v[88:91], v[170:173], v[216:219], v[88:91]
	v_mfma_f32_16x16x32_bf16 v[76:79], v[128:131], v[224:227], v[76:79]
	v_mfma_f32_16x16x32_bf16 v[72:75], v[170:173], v[224:227], v[72:75]
	v_mfma_f32_16x16x32_bf16 v[124:127], v[132:135], v[200:203], v[124:127]
	v_mfma_f32_16x16x32_bf16 v[120:123], v[176:179], v[200:203], v[120:123]
	v_mfma_f32_16x16x32_bf16 v[108:111], v[132:135], v[208:211], v[108:111]
	v_mfma_f32_16x16x32_bf16 v[104:107], v[176:179], v[208:211], v[104:107]
	v_mfma_f32_16x16x32_bf16 v[92:95], v[132:135], v[220:223], v[92:95]
	v_mfma_f32_16x16x32_bf16 v[88:91], v[176:179], v[220:223], v[88:91]
	v_mfma_f32_16x16x32_bf16 v[76:79], v[132:135], v[228:231], v[76:79]
	v_mfma_f32_16x16x32_bf16 v[72:75], v[176:179], v[228:231], v[72:75]
	s_setprio 0
	s_setprio 1
	v_mfma_f32_16x16x32_bf16 v[116:119], v[180:183], v[196:199], v[116:119]
	v_mfma_f32_16x16x32_bf16 v[112:115], v[188:191], v[196:199], v[112:115]
	v_mfma_f32_16x16x32_bf16 v[100:103], v[180:183], v[204:207], v[100:103]
	v_mfma_f32_16x16x32_bf16 v[96:99], v[188:191], v[204:207], v[96:99]
	v_mfma_f32_16x16x32_bf16 v[84:87], v[180:183], v[216:219], v[84:87]
	v_mfma_f32_16x16x32_bf16 v[80:83], v[188:191], v[216:219], v[80:83]
	v_mfma_f32_16x16x32_bf16 v[68:71], v[180:183], v[224:227], v[68:71]
	v_mfma_f32_16x16x32_bf16 v[64:67], v[188:191], v[224:227], v[64:67]
	v_mfma_f32_16x16x32_bf16 v[116:119], v[184:187], v[200:203], v[116:119]
	v_mfma_f32_16x16x32_bf16 v[112:115], v[192:195], v[200:203], v[112:115]
	v_mfma_f32_16x16x32_bf16 v[100:103], v[184:187], v[208:211], v[100:103]
	v_mfma_f32_16x16x32_bf16 v[96:99], v[192:195], v[208:211], v[96:99]
	v_mfma_f32_16x16x32_bf16 v[84:87], v[184:187], v[220:223], v[84:87]
	v_mfma_f32_16x16x32_bf16 v[80:83], v[192:195], v[220:223], v[80:83]
	v_mfma_f32_16x16x32_bf16 v[68:71], v[184:187], v[228:231], v[68:71]
	v_mfma_f32_16x16x32_bf16 v[64:67], v[192:195], v[228:231], v[64:67]
	s_setprio 0
	s_barrier
	s_add_i32 s39, s33, s15
	v_lshl_add_u64 v[152:153], s[62:63], 0, v[138:139]
	s_mov_b32 m0, s39
	ds_read_b128 v[196:199], v175 offset:16384
	ds_read_b128 v[200:203], v175 offset:17408
	ds_read_b128 v[204:207], v175 offset:18432
	ds_read_b128 v[208:211], v175 offset:19456
	ds_read_b128 v[216:219], v175 offset:20480
	ds_read_b128 v[220:223], v175 offset:21504
	ds_read_b128 v[224:227], v175 offset:22528
	ds_read_b128 v[228:231], v175 offset:23552
	global_load_lds_dwordx4 v[152:153], off
	s_add_i32 m0, s39, 0x2000
	s_add_u32 s48, s62, 0x80000
	v_lshl_add_u64 v[156:157], s[62:63], 0, v[142:143]
	s_addc_u32 s49, s63, 0
	s_add_i32 s39, s36, s15
	global_load_lds_dwordx4 v[156:157], off
	v_lshl_add_u64 v[160:161], s[48:49], 0, v[138:139]
	s_mov_b32 m0, s39
	v_lshl_add_u64 v[232:233], s[64:65], 0, v[140:141]
	global_load_lds_dwordx4 v[160:161], off
	v_lshl_add_u64 v[160:161], s[48:49], 0, v[142:143]
	s_add_i32 m0, s39, 0x2000
	s_nop 0
	global_load_lds_dwordx4 v[160:161], off
	v_lshl_add_u64 v[160:161], s[64:65], 0, v[136:137]
	s_mov_b32 m0, s18
	s_nop 0
	global_load_lds_dwordx4 v[160:161], off
	s_mov_b32 m0, s19
	s_nop 0
	global_load_lds_dwordx4 v[232:233], off
	s_waitcnt vmcnt(8)
	s_waitcnt lgkmcnt(0)
	s_barrier
; #define PG8_STAGE(bufoff, gbase, voff) do { _Pragma("unroll") for (int _i = 0; _i < 2; ++_i) \
;         __builtin_amdgcn_global_load_lds((const unsigned*)((const char*)(gbase) + (voff)[_i]), (LAS unsigned*)(lds + (bufoff) + ldsw + _i * 8192), 16, 0, 0); } while (0)
; #define PG8_LDA(dst, b, h) do { _Pragma("unroll") for (int m = 0; m < 4; ++m) _Pragma("unroll") for (int k = 0; k < 2; ++k) dst[m][k] = *(const LAS bf16x8*)(lds + PG8_SA(b, h) + aoff + m * 2048 + k * 1024); } while (0)
; #define PG8_LDB(dst, b, h) do { _Pragma("unroll") for (int n = 0; n < 2; ++n) _Pragma("unroll") for (int k = 0; k < 2; ++k) dst[n][k] = *(const LAS bf16x8*)(lds + PG8_SB(b, h) + boff + n * 2048 + k * 1024); } while (0)
; #define PG8_MMA(ai, bj, At, Bt) do { __builtin_amdgcn_s_setprio(1); _Pragma("unroll") for (int m = 0; m < 4; ++m) _Pragma("unroll") for (int n = 0; n < 2; ++n) _Pragma("unroll") for (int k = 0; k < 2; ++k) \
;         acc[ai][bj][m][n] = __builtin_amdgcn_mfma_f32_16x16x32_bf16(Bt[n][k], At[m][k], acc[ai][bj][m][n], 0, 0, 0); __builtin_amdgcn_s_setprio(0); } while (0)
; #define PG8_WAIT_V(n) asm volatile("s_waitcnt vmcnt(" #n ")" ::: "memory")
; #define PG8_WAIT_L(n) asm volatile("s_waitcnt lgkmcnt(" #n ")" ::: "memory")
; #define PG8_BAR __builtin_amdgcn_s_barrier()
; #define PG8_SCHED __builtin_amdgcn_sched_barrier(0)
; template <class Epi, class Sched>
; __device__ __forceinline__ void gemm_phase(LAS unsigned char* lds, const Gemm g, const Sched& S, const Epi& E) {
;     ...
;             PG8_LDA(At, 0, 1); PG8_STAGE(PG8_SB(0, 0), b2, voffB); PG8_STAGE(PG8_SB(0, 1), b2 + hstepB, voffB); PG8_STAGE(PG8_SA(0, 0), a2, voffA);
;             PG8_WAIT_V(8); PG8_WAIT_L(0); PG8_BAR; PG8_MMA(1, 0, At, B0); PG8_MMA(1, 1, At, B1); PG8_BAR; PG8_SCHED;
;             PG8_LDB(B0, 1, 0); PG8_LDB(B1, 1, 1); PG8_SCHED; PG8_LDA(At, 1, 0); PG8_STAGE(PG8_SA(0, 1), a2 + hstepA, voffA);
;             PG8_WAIT_V(8); PG8_WAIT_L(0); PG8_BAR; PG8_MMA(0, 0, At, B0); PG8_MMA(0, 1, At, B1); PG8_BAR; PG8_SCHED;
	s_setprio 1
	v_mfma_f32_16x16x32_bf16 v[60:63], v[128:131], v[196:199], v[60:63]
	v_mfma_f32_16x16x32_bf16 v[56:59], v[170:173], v[196:199], v[56:59]
	v_mfma_f32_16x16x32_bf16 v[44:47], v[128:131], v[204:207], v[44:47]
	v_mfma_f32_16x16x32_bf16 v[40:43], v[170:173], v[204:207], v[40:43]
	v_mfma_f32_16x16x32_bf16 v[28:31], v[128:131], v[216:219], v[28:31]
	v_mfma_f32_16x16x32_bf16 v[24:27], v[170:173], v[216:219], v[24:27]
	v_mfma_f32_16x16x32_bf16 v[12:15], v[128:131], v[224:227], v[12:15]
	v_mfma_f32_16x16x32_bf16 v[8:11], v[170:173], v[224:227], v[8:11]
	v_mfma_f32_16x16x32_bf16 v[60:63], v[132:135], v[200:203], v[60:63]
	v_mfma_f32_16x16x32_bf16 v[56:59], v[176:179], v[200:203], v[56:59]
	v_mfma_f32_16x16x32_bf16 v[44:47], v[132:135], v[208:211], v[44:47]
	v_mfma_f32_16x16x32_bf16 v[40:43], v[176:179], v[208:211], v[40:43]
	v_mfma_f32_16x16x32_bf16 v[28:31], v[132:135], v[220:223], v[28:31]
	v_mfma_f32_16x16x32_bf16 v[24:27], v[176:179], v[220:223], v[24:27]
	v_mfma_f32_16x16x32_bf16 v[12:15], v[132:135], v[228:231], v[12:15]
	v_mfma_f32_16x16x32_bf16 v[8:11], v[176:179], v[228:231], v[8:11]
	s_setprio 0
	s_setprio 1
	v_mfma_f32_16x16x32_bf16 v[52:55], v[180:183], v[196:199], v[52:55]
	v_mfma_f32_16x16x32_bf16 v[48:51], v[188:191], v[196:199], v[48:51]
	v_mfma_f32_16x16x32_bf16 v[36:39], v[180:183], v[204:207], v[36:39]
	v_mfma_f32_16x16x32_bf16 v[32:35], v[188:191], v[204:207], v[32:35]
	v_mfma_f32_16x16x32_bf16 v[20:23], v[180:183], v[216:219], v[20:23]
	v_mfma_f32_16x16x32_bf16 v[16:19], v[188:191], v[216:219], v[16:19]
	v_mfma_f32_16x16x32_bf16 v[4:7], v[180:183], v[224:227], v[4:7]
	v_mfma_f32_16x16x32_bf16 v[0:3], v[188:191], v[224:227], v[0:3]
	v_mfma_f32_16x16x32_bf16 v[52:55], v[184:187], v[200:203], v[52:55]
	v_mfma_f32_16x16x32_bf16 v[48:51], v[192:195], v[200:203], v[48:51]
	v_mfma_f32_16x16x32_bf16 v[36:39], v[184:187], v[208:211], v[36:39]
	v_mfma_f32_16x16x32_bf16 v[32:35], v[192:195], v[208:211], v[32:35]
	v_mfma_f32_16x16x32_bf16 v[20:23], v[184:187], v[220:223], v[20:23]
	v_mfma_f32_16x16x32_bf16 v[16:19], v[192:195], v[220:223], v[16:19]
	v_mfma_f32_16x16x32_bf16 v[4:7], v[184:187], v[228:231], v[4:7]
	v_mfma_f32_16x16x32_bf16 v[0:3], v[192:195], v[228:231], v[0:3]
	s_setprio 0
	s_barrier
	v_add_u32_e32 v154, s37, v165
	ds_read_b128 v[128:131], v154
	ds_read_b128 v[132:135], v154 offset:1024
	ds_read_b128 v[170:173], v154 offset:2048
	ds_read_b128 v[176:179], v154 offset:3072
	v_add_u32_e32 v154, s26, v165
	ds_read_b128 v[180:183], v154
	ds_read_b128 v[184:187], v154 offset:1024
	ds_read_b128 v[188:191], v154 offset:2048
	ds_read_b128 v[192:195], v154 offset:3072
	s_add_u32 s48, s64, 0x80000
	s_addc_u32 s49, s65, 0
	s_mov_b32 m0, s21
	v_lshl_add_u64 v[234:235], s[48:49], 0, v[136:137]
	ds_read_b128 v[196:199], v175 offset:32768
	ds_read_b128 v[200:203], v175 offset:33792
	ds_read_b128 v[204:207], v175 offset:34816
	ds_read_b128 v[208:211], v175 offset:35840
	ds_read_b128 v[216:219], v175 offset:36864
	ds_read_b128 v[220:223], v175 offset:37888
	ds_read_b128 v[224:227], v175 offset:38912
	ds_read_b128 v[228:231], v175 offset:39936
	global_load_lds_dwordx4 v[234:235], off
	v_lshl_add_u64 v[234:235], s[48:49], 0, v[140:141]
	s_mov_b32 m0, s22
	s_nop 0
	global_load_lds_dwordx4 v[234:235], off
	s_waitcnt vmcnt(8)
	s_waitcnt lgkmcnt(0)
	s_barrier
	s_setprio 1
	v_mfma_f32_16x16x32_bf16 v[124:127], v[128:131], v[196:199], v[124:127]
	v_mfma_f32_16x16x32_bf16 v[120:123], v[170:173], v[196:199], v[120:123]
	v_mfma_f32_16x16x32_bf16 v[108:111], v[128:131], v[204:207], v[108:111]
	v_mfma_f32_16x16x32_bf16 v[104:107], v[170:173], v[204:207], v[104:107]
	v_mfma_f32_16x16x32_bf16 v[92:95], v[128:131], v[216:219], v[92:95]
	v_mfma_f32_16x16x32_bf16 v[88:91], v[170:173], v[216:219], v[88:91]
	v_mfma_f32_16x16x32_bf16 v[76:79], v[128:131], v[224:227], v[76:79]
	v_mfma_f32_16x16x32_bf16 v[72:75], v[170:173], v[224:227], v[72:75]
	v_mfma_f32_16x16x32_bf16 v[124:127], v[132:135], v[200:203], v[124:127]
	v_mfma_f32_16x16x32_bf16 v[120:123], v[176:179], v[200:203], v[120:123]
	v_mfma_f32_16x16x32_bf16 v[108:111], v[132:135], v[208:211], v[108:111]
	v_mfma_f32_16x16x32_bf16 v[104:107], v[176:179], v[208:211], v[104:107]
	v_mfma_f32_16x16x32_bf16 v[92:95], v[132:135], v[220:223], v[92:95]
	v_mfma_f32_16x16x32_bf16 v[88:91], v[176:179], v[220:223], v[88:91]
	v_mfma_f32_16x16x32_bf16 v[76:79], v[132:135], v[228:231], v[76:79]
	v_mfma_f32_16x16x32_bf16 v[72:75], v[176:179], v[228:231], v[72:75]
	s_setprio 0
	s_setprio 1
	v_mfma_f32_16x16x32_bf16 v[116:119], v[180:183], v[196:199], v[116:119]
	v_mfma_f32_16x16x32_bf16 v[112:115], v[188:191], v[196:199], v[112:115]
	v_mfma_f32_16x16x32_bf16 v[100:103], v[180:183], v[204:207], v[100:103]
	v_mfma_f32_16x16x32_bf16 v[96:99], v[188:191], v[204:207], v[96:99]
	v_mfma_f32_16x16x32_bf16 v[84:87], v[180:183], v[216:219], v[84:87]
	v_mfma_f32_16x16x32_bf16 v[80:83], v[188:191], v[216:219], v[80:83]
	v_mfma_f32_16x16x32_bf16 v[68:71], v[180:183], v[224:227], v[68:71]
	v_mfma_f32_16x16x32_bf16 v[64:67], v[188:191], v[224:227], v[64:67]
	v_mfma_f32_16x16x32_bf16 v[116:119], v[184:187], v[200:203], v[116:119]
	v_mfma_f32_16x16x32_bf16 v[112:115], v[192:195], v[200:203], v[112:115]
	v_mfma_f32_16x16x32_bf16 v[100:103], v[184:187], v[208:211], v[100:103]
	v_mfma_f32_16x16x32_bf16 v[96:99], v[192:195], v[208:211], v[96:99]
	v_mfma_f32_16x16x32_bf16 v[84:87], v[184:187], v[220:223], v[84:87]
	v_mfma_f32_16x16x32_bf16 v[80:83], v[192:195], v[220:223], v[80:83]
	v_mfma_f32_16x16x32_bf16 v[68:71], v[184:187], v[228:231], v[68:71]
	v_mfma_f32_16x16x32_bf16 v[64:67], v[192:195], v[228:231], v[64:67]
	s_setprio 0
	s_barrier
; #define PG8_STAGE(bufoff, gbase, voff) do { _Pragma("unroll") for (int _i = 0; _i < 2; ++_i) \
;         __builtin_amdgcn_global_load_lds((const unsigned*)((const char*)(gbase) + (voff)[_i]), (LAS unsigned*)(lds + (bufoff) + ldsw + _i * 8192), 16, 0, 0); } while (0)
; #define PG8_LDA(dst, b, h) do { _Pragma("unroll") for (int m = 0; m < 4; ++m) _Pragma("unroll") for (int k = 0; k < 2; ++k) dst[m][k] = *(const LAS bf16x8*)(lds + PG8_SA(b, h) + aoff + m * 2048 + k * 1024); } while (0)
; #define PG8_MMA(ai, bj, At, Bt) do { __builtin_amdgcn_s_setprio(1); _Pragma("unroll") for (int m = 0; m < 4; ++m) _Pragma("unroll") for (int n = 0; n < 2; ++n) _Pragma("unroll") for (int k = 0; k < 2; ++k) \
;         acc[ai][bj][m][n] = __builtin_amdgcn_mfma_f32_16x16x32_bf16(Bt[n][k], At[m][k], acc[ai][bj][m][n], 0, 0, 0); __builtin_amdgcn_s_setprio(0); } while (0)
; #define PG8_WAIT_V(n) asm volatile("s_waitcnt vmcnt(" #n ")" ::: "memory")
; #define PG8_WAIT_L(n) asm volatile("s_waitcnt lgkmcnt(" #n ")" ::: "memory")
; #define PG8_BAR __builtin_amdgcn_s_barrier()
; #define PG8_SCHED __builtin_amdgcn_sched_barrier(0)
; template <class Epi, class Sched>
; __device__ __forceinline__ void gemm_phase(LAS unsigned char* lds, const Gemm g, const Sched& S, const Epi& E) {
;     ...
;             PG8_LDA(At, 1, 1); PG8_STAGE(PG8_SB(1, 0), b3, voffB); PG8_STAGE(PG8_SB(1, 1), b3 + hstepB, voffB); PG8_STAGE(PG8_SA(1, 0), a3, voffA);
;             PG8_WAIT_V(8); PG8_WAIT_L(0); PG8_BAR; PG8_MMA(1, 0, At, B0); PG8_MMA(1, 1, At, B1); PG8_BAR; PG8_SCHED;
;         }
;         if (wr == 0) PG8_BAR;
	s_add_i32 s39, s37, s15
	v_lshl_add_u64 v[152:153], v[152:153], 0, s[8:9]
	s_mov_b32 m0, s39
	ds_read_b128 v[196:199], v175 offset:49152
	ds_read_b128 v[200:203], v175 offset:50176
	ds_read_b128 v[204:207], v175 offset:51200
	ds_read_b128 v[208:211], v175 offset:52224
	ds_read_b128 v[216:219], v175 offset:53248
	ds_read_b128 v[220:223], v175 offset:54272
	ds_read_b128 v[224:227], v175 offset:55296
	ds_read_b128 v[228:231], v175 offset:56320
	global_load_lds_dwordx4 v[152:153], off
	s_add_i32 m0, s39, 0x2000
	s_add_u32 s48, s62, 0x80080
	v_lshl_add_u64 v[152:153], v[156:157], 0, s[8:9]
	s_addc_u32 s49, s63, 0
	s_add_i32 s39, s26, s15
	global_load_lds_dwordx4 v[152:153], off
	v_lshl_add_u64 v[152:153], s[48:49], 0, v[138:139]
	s_mov_b32 m0, s39
	s_nop 0
	global_load_lds_dwordx4 v[152:153], off
	v_lshl_add_u64 v[152:153], s[48:49], 0, v[142:143]
	s_add_i32 m0, s39, 0x2000
	s_nop 0
	global_load_lds_dwordx4 v[152:153], off
	v_lshl_add_u64 v[152:153], v[160:161], 0, s[8:9]
	s_mov_b32 m0, s25
	s_nop 0
	global_load_lds_dwordx4 v[152:153], off
	v_lshl_add_u64 v[152:153], v[232:233], 0, s[8:9]
	s_mov_b32 m0, s27
	s_nop 0
	global_load_lds_dwordx4 v[152:153], off
	s_waitcnt vmcnt(8)
	s_waitcnt lgkmcnt(0)
	s_barrier
	s_setprio 1
	v_mfma_f32_16x16x32_bf16 v[60:63], v[128:131], v[196:199], v[60:63]
	v_mfma_f32_16x16x32_bf16 v[56:59], v[170:173], v[196:199], v[56:59]
	v_mfma_f32_16x16x32_bf16 v[44:47], v[128:131], v[204:207], v[44:47]
	v_mfma_f32_16x16x32_bf16 v[40:43], v[170:173], v[204:207], v[40:43]
	v_mfma_f32_16x16x32_bf16 v[28:31], v[128:131], v[216:219], v[28:31]
	v_mfma_f32_16x16x32_bf16 v[24:27], v[170:173], v[216:219], v[24:27]
	v_mfma_f32_16x16x32_bf16 v[12:15], v[128:131], v[224:227], v[12:15]
	v_mfma_f32_16x16x32_bf16 v[8:11], v[170:173], v[224:227], v[8:11]
	v_mfma_f32_16x16x32_bf16 v[60:63], v[132:135], v[200:203], v[60:63]
	v_mfma_f32_16x16x32_bf16 v[56:59], v[176:179], v[200:203], v[56:59]
	v_mfma_f32_16x16x32_bf16 v[44:47], v[132:135], v[208:211], v[44:47]
	v_mfma_f32_16x16x32_bf16 v[40:43], v[176:179], v[208:211], v[40:43]
	v_mfma_f32_16x16x32_bf16 v[28:31], v[132:135], v[220:223], v[28:31]
	v_mfma_f32_16x16x32_bf16 v[24:27], v[176:179], v[220:223], v[24:27]
	v_mfma_f32_16x16x32_bf16 v[12:15], v[132:135], v[228:231], v[12:15]
	v_mfma_f32_16x16x32_bf16 v[8:11], v[176:179], v[228:231], v[8:11]
	s_setprio 0
	s_setprio 1
	v_mfma_f32_16x16x32_bf16 v[52:55], v[180:183], v[196:199], v[52:55]
	v_mfma_f32_16x16x32_bf16 v[48:51], v[188:191], v[196:199], v[48:51]
	v_mfma_f32_16x16x32_bf16 v[36:39], v[180:183], v[204:207], v[36:39]
	v_mfma_f32_16x16x32_bf16 v[32:35], v[188:191], v[204:207], v[32:35]
	v_mfma_f32_16x16x32_bf16 v[20:23], v[180:183], v[216:219], v[20:23]
	v_mfma_f32_16x16x32_bf16 v[16:19], v[188:191], v[216:219], v[16:19]
	v_mfma_f32_16x16x32_bf16 v[4:7], v[180:183], v[224:227], v[4:7]
	v_mfma_f32_16x16x32_bf16 v[0:3], v[188:191], v[224:227], v[0:3]
	v_mfma_f32_16x16x32_bf16 v[52:55], v[184:187], v[200:203], v[52:55]
	v_mfma_f32_16x16x32_bf16 v[48:51], v[192:195], v[200:203], v[48:51]
	v_mfma_f32_16x16x32_bf16 v[36:39], v[184:187], v[208:211], v[36:39]
	v_mfma_f32_16x16x32_bf16 v[32:35], v[192:195], v[208:211], v[32:35]
	v_mfma_f32_16x16x32_bf16 v[20:23], v[184:187], v[220:223], v[20:23]
	v_mfma_f32_16x16x32_bf16 v[16:19], v[192:195], v[220:223], v[16:19]
	v_mfma_f32_16x16x32_bf16 v[4:7], v[184:187], v[228:231], v[4:7]
	v_mfma_f32_16x16x32_bf16 v[0:3], v[192:195], v[228:231], v[0:3]
	s_setprio 0
	s_barrier
	s_add_i32 s35, s35, 2
	s_add_u32 s60, s60, 0x100
	s_addc_u32 s61, s61, 0
	s_add_u32 s31, s31, 0x100
	s_addc_u32 s34, s34, 0
	s_cmp_gt_u32 s35, 29
	s_cbranch_scc0 .LBB0_829
	s_and_b64 vcc, exec, s[10:11]
	s_cbranch_vccz .LBB0_832
	s_barrier

; #define PG8_STAGE(bufoff, gbase, voff) do { _Pragma("unroll") for (int _i = 0; _i < 2; ++_i) \
;         __builtin_amdgcn_global_load_lds((const unsigned*)((const char*)(gbase) + (voff)[_i]), (LAS unsigned*)(lds + (bufoff) + ldsw + _i * 8192), 16, 0, 0); } while (0)
; #define PG8_LDA(dst, b, h) do { _Pragma("unroll") for (int m = 0; m < 4; ++m) _Pragma("unroll") for (int k = 0; k < 2; ++k) dst[m][k] = *(const LAS bf16x8*)(lds + PG8_SA(b, h) + aoff + m * 2048 + k * 1024); } while (0)
; #define PG8_LDB(dst, b, h) do { _Pragma("unroll") for (int n = 0; n < 2; ++n) _Pragma("unroll") for (int k = 0; k < 2; ++k) dst[n][k] = *(const LAS bf16x8*)(lds + PG8_SB(b, h) + boff + n * 2048 + k * 1024); } while (0)
; #define PG8_MMA(ai, bj, At, Bt) do { __builtin_amdgcn_s_setprio(1); _Pragma("unroll") for (int m = 0; m < 4; ++m) _Pragma("unroll") for (int n = 0; n < 2; ++n) _Pragma("unroll") for (int k = 0; k < 2; ++k) \
;         acc[ai][bj][m][n] = __builtin_amdgcn_mfma_f32_16x16x32_bf16(Bt[n][k], At[m][k], acc[ai][bj][m][n], 0, 0, 0); __builtin_amdgcn_s_setprio(0); } while (0)
; #define PG8_WAIT_V(n) asm volatile("s_waitcnt vmcnt(" #n ")" ::: "memory")
; #define PG8_WAIT_L(n) asm volatile("s_waitcnt lgkmcnt(" #n ")" ::: "memory")
; #define PG8_BAR __builtin_amdgcn_s_barrier()
; #define PG8_SCHED __builtin_amdgcn_sched_barrier(0)
; template <class Epi, class Sched>
; __device__ __forceinline__ void gemm_phase(LAS unsigned char* lds, const Gemm g, const Sched& S, const Epi& E) {
;     ...
;             const bool last = (t == nt - 2);
;             const char* a1 = cA + (size_t)(t + 1) * kstep;
;             const char* a2 = last ? nA : cA + (size_t)(t + 2) * kstep; const char* b2 = last ? nB : cB + (size_t)(t + 2) * kstep;
;             const char* a3 = a2 + kstep; const char* b3 = b2 + kstep;
;             PG8_LDB(B0, 0, 0); PG8_LDB(B1, 0, 1); PG8_SCHED; PG8_LDA(At, 0, 0); PG8_STAGE(PG8_SA(1, 1), a1 + hstepA, voffA);
;             PG8_WAIT_V(8); PG8_WAIT_L(0); PG8_BAR; PG8_MMA(0, 0, At, B0); PG8_MMA(0, 1, At, B1); PG8_BAR; PG8_SCHED;
;             PG8_LDA(At, 0, 1); PG8_STAGE(PG8_SB(0, 0), b2, voffB); PG8_STAGE(PG8_SB(0, 1), b2 + hstepB, voffB); PG8_STAGE(PG8_SA(0, 0), a2, voffA);
.LBB0_923:
	ds_read_b128 v[64:67], v209
	ds_read_b128 v[68:71], v209 offset:1024
	ds_read_b128 v[72:75], v209 offset:2048
	ds_read_b128 v[76:79], v209 offset:3072
	ds_read_b128 v[84:87], v210
	ds_read_b128 v[88:91], v210 offset:1024
	ds_read_b128 v[92:95], v210 offset:2048
	ds_read_b128 v[96:99], v210 offset:3072
	s_add_u32 s4, s0, 0xfff80080
	s_addc_u32 s5, s1, -1
	s_cmp_eq_u32 s62, 28
	s_cselect_b32 s7, s12, s5
	s_cselect_b32 s6, s13, s4
	s_cselect_b32 s5, s53, s61
	s_cselect_b32 s4, s55, s60
	v_lshl_add_u64 v[218:219], s[0:1], 0, v[170:171]
	s_add_i32 m0, s15, 0xc000
	ds_read_b128 v[174:177], v211
	ds_read_b128 v[178:181], v211 offset:1024
	ds_read_b128 v[182:185], v211 offset:2048
	ds_read_b128 v[186:189], v211 offset:3072
	ds_read_b128 v[190:193], v211 offset:4096
	ds_read_b128 v[194:197], v211 offset:5120
	ds_read_b128 v[198:201], v211 offset:6144
	ds_read_b128 v[202:205], v211 offset:7168
	global_load_lds_dwordx4 v[218:219], off
	v_lshl_add_u64 v[218:219], s[0:1], 0, v[172:173]
	s_add_i32 m0, s15, 0xe000
	s_nop 0
	global_load_lds_dwordx4 v[218:219], off
	s_waitcnt vmcnt(8)
	s_waitcnt lgkmcnt(0)
	s_barrier
	s_setprio 1
	v_mfma_f32_16x16x32_bf16 v[156:159], v[64:67], v[174:177], v[156:159]
	v_mfma_f32_16x16x32_bf16 v[148:151], v[72:75], v[174:177], v[148:151]
	v_mfma_f32_16x16x32_bf16 v[140:143], v[64:67], v[182:185], v[140:143]
	v_mfma_f32_16x16x32_bf16 v[136:139], v[72:75], v[182:185], v[136:139]
	v_mfma_f32_16x16x32_bf16 v[124:127], v[64:67], v[190:193], v[124:127]
	v_mfma_f32_16x16x32_bf16 v[120:123], v[72:75], v[190:193], v[120:123]
	v_mfma_f32_16x16x32_bf16 v[108:111], v[64:67], v[198:201], v[108:111]
	v_mfma_f32_16x16x32_bf16 v[104:107], v[72:75], v[198:201], v[104:107]
	v_mfma_f32_16x16x32_bf16 v[156:159], v[68:71], v[178:181], v[156:159]
	v_mfma_f32_16x16x32_bf16 v[148:151], v[76:79], v[178:181], v[148:151]
	v_mfma_f32_16x16x32_bf16 v[140:143], v[68:71], v[186:189], v[140:143]
	v_mfma_f32_16x16x32_bf16 v[136:139], v[76:79], v[186:189], v[136:139]
	v_mfma_f32_16x16x32_bf16 v[124:127], v[68:71], v[194:197], v[124:127]
	v_mfma_f32_16x16x32_bf16 v[120:123], v[76:79], v[194:197], v[120:123]
	v_mfma_f32_16x16x32_bf16 v[108:111], v[68:71], v[202:205], v[108:111]
	v_mfma_f32_16x16x32_bf16 v[104:107], v[76:79], v[202:205], v[104:107]
	s_setprio 0
	s_setprio 1
	v_mfma_f32_16x16x32_bf16 v[152:155], v[84:87], v[174:177], v[152:155]
	v_mfma_f32_16x16x32_bf16 v[144:147], v[92:95], v[174:177], v[144:147]
	v_mfma_f32_16x16x32_bf16 v[132:135], v[84:87], v[182:185], v[132:135]
	v_mfma_f32_16x16x32_bf16 v[128:131], v[92:95], v[182:185], v[128:131]
	v_mfma_f32_16x16x32_bf16 v[116:119], v[84:87], v[190:193], v[116:119]
	v_mfma_f32_16x16x32_bf16 v[112:115], v[92:95], v[190:193], v[112:115]
	v_mfma_f32_16x16x32_bf16 v[80:83], v[84:87], v[198:201], v[80:83]
	v_mfma_f32_16x16x32_bf16 v[100:103], v[92:95], v[198:201], v[100:103]
	v_mfma_f32_16x16x32_bf16 v[152:155], v[88:91], v[178:181], v[152:155]
	v_mfma_f32_16x16x32_bf16 v[144:147], v[96:99], v[178:181], v[144:147]
	v_mfma_f32_16x16x32_bf16 v[132:135], v[88:91], v[186:189], v[132:135]
	v_mfma_f32_16x16x32_bf16 v[128:131], v[96:99], v[186:189], v[128:131]
	v_mfma_f32_16x16x32_bf16 v[116:119], v[88:91], v[194:197], v[116:119]
	v_mfma_f32_16x16x32_bf16 v[112:115], v[96:99], v[194:197], v[112:115]
	v_mfma_f32_16x16x32_bf16 v[80:83], v[88:91], v[202:205], v[80:83]
	v_mfma_f32_16x16x32_bf16 v[100:103], v[96:99], v[202:205], v[100:103]
	s_setprio 0
	s_barrier
	s_add_i32 s63, s33, s14
	v_lshl_add_u64 v[218:219], s[4:5], 0, v[162:163]
	s_mov_b32 m0, s63
	ds_read_b128 v[174:177], v211 offset:16384
	ds_read_b128 v[178:181], v211 offset:17408
	ds_read_b128 v[182:185], v211 offset:18432
	ds_read_b128 v[186:189], v211 offset:19456
	ds_read_b128 v[190:193], v211 offset:20480
	ds_read_b128 v[194:197], v211 offset:21504
	ds_read_b128 v[198:201], v211 offset:22528
	ds_read_b128 v[202:205], v211 offset:23552
	global_load_lds_dwordx4 v[218:219], off
	s_add_i32 m0, s63, 0x2000
	s_add_u32 s70, s4, 0x80000
	v_lshl_add_u64 v[220:221], s[4:5], 0, v[166:167]
	s_addc_u32 s71, s5, 0
	s_add_i32 s63, s36, s14
	global_load_lds_dwordx4 v[220:221], off
	v_lshl_add_u64 v[222:223], s[70:71], 0, v[162:163]
	s_mov_b32 m0, s63
	v_lshl_add_u64 v[224:225], s[6:7], 0, v[164:165]
	global_load_lds_dwordx4 v[222:223], off
	v_lshl_add_u64 v[222:223], s[70:71], 0, v[166:167]
	s_add_i32 m0, s63, 0x2000
	s_nop 0
	global_load_lds_dwordx4 v[222:223], off
	v_lshl_add_u64 v[222:223], s[6:7], 0, v[160:161]
	s_mov_b32 m0, s15
	s_nop 0
	global_load_lds_dwordx4 v[222:223], off
	s_mov_b32 m0, s21
	s_nop 0
	global_load_lds_dwordx4 v[224:225], off
	s_waitcnt vmcnt(8)
	s_waitcnt lgkmcnt(0)
	s_barrier
; #define PG8_STAGE(bufoff, gbase, voff) do { _Pragma("unroll") for (int _i = 0; _i < 2; ++_i) \
;         __builtin_amdgcn_global_load_lds((const unsigned*)((const char*)(gbase) + (voff)[_i]), (LAS unsigned*)(lds + (bufoff) + ldsw + _i * 8192), 16, 0, 0); } while (0)
; #define PG8_LDA(dst, b, h) do { _Pragma("unroll") for (int m = 0; m < 4; ++m) _Pragma("unroll") for (int k = 0; k < 2; ++k) dst[m][k] = *(const LAS bf16x8*)(lds + PG8_SA(b, h) + aoff + m * 2048 + k * 1024); } while (0)
; #define PG8_LDB(dst, b, h) do { _Pragma("unroll") for (int n = 0; n < 2; ++n) _Pragma("unroll") for (int k = 0; k < 2; ++k) dst[n][k] = *(const LAS bf16x8*)(lds + PG8_SB(b, h) + boff + n * 2048 + k * 1024); } while (0)
; #define PG8_MMA(ai, bj, At, Bt) do { __builtin_amdgcn_s_setprio(1); _Pragma("unroll") for (int m = 0; m < 4; ++m) _Pragma("unroll") for (int n = 0; n < 2; ++n) _Pragma("unroll") for (int k = 0; k < 2; ++k) \
;         acc[ai][bj][m][n] = __builtin_amdgcn_mfma_f32_16x16x32_bf16(Bt[n][k], At[m][k], acc[ai][bj][m][n], 0, 0, 0); __builtin_amdgcn_s_setprio(0); } while (0)
; #define PG8_WAIT_V(n) asm volatile("s_waitcnt vmcnt(" #n ")" ::: "memory")
; #define PG8_WAIT_L(n) asm volatile("s_waitcnt lgkmcnt(" #n ")" ::: "memory")
; #define PG8_BAR __builtin_amdgcn_s_barrier()
; #define PG8_SCHED __builtin_amdgcn_sched_barrier(0)
; template <class Epi, class Sched>
; __device__ __forceinline__ void gemm_phase(LAS unsigned char* lds, const Gemm g, const Sched& S, const Epi& E) {
;     ...
;             PG8_LDA(At, 0, 1); PG8_STAGE(PG8_SB(0, 0), b2, voffB); PG8_STAGE(PG8_SB(0, 1), b2 + hstepB, voffB); PG8_STAGE(PG8_SA(0, 0), a2, voffA);
;             PG8_WAIT_V(8); PG8_WAIT_L(0); PG8_BAR; PG8_MMA(1, 0, At, B0); PG8_MMA(1, 1, At, B1); PG8_BAR; PG8_SCHED;
;             PG8_LDB(B0, 1, 0); PG8_LDB(B1, 1, 1); PG8_SCHED; PG8_LDA(At, 1, 0); PG8_STAGE(PG8_SA(0, 1), a2 + hstepA, voffA);
;             PG8_WAIT_V(8); PG8_WAIT_L(0); PG8_BAR; PG8_MMA(0, 0, At, B0); PG8_MMA(0, 1, At, B1); PG8_BAR; PG8_SCHED;
	s_setprio 1
	v_mfma_f32_16x16x32_bf16 v[60:63], v[64:67], v[174:177], v[60:63]
	v_mfma_f32_16x16x32_bf16 v[56:59], v[72:75], v[174:177], v[56:59]
	v_mfma_f32_16x16x32_bf16 v[44:47], v[64:67], v[182:185], v[44:47]
	v_mfma_f32_16x16x32_bf16 v[40:43], v[72:75], v[182:185], v[40:43]
	v_mfma_f32_16x16x32_bf16 v[28:31], v[64:67], v[190:193], v[28:31]
	v_mfma_f32_16x16x32_bf16 v[24:27], v[72:75], v[190:193], v[24:27]
	v_mfma_f32_16x16x32_bf16 v[12:15], v[64:67], v[198:201], v[12:15]
	v_mfma_f32_16x16x32_bf16 v[8:11], v[72:75], v[198:201], v[8:11]
	v_mfma_f32_16x16x32_bf16 v[60:63], v[68:71], v[178:181], v[60:63]
	v_mfma_f32_16x16x32_bf16 v[56:59], v[76:79], v[178:181], v[56:59]
	v_mfma_f32_16x16x32_bf16 v[44:47], v[68:71], v[186:189], v[44:47]
	v_mfma_f32_16x16x32_bf16 v[40:43], v[76:79], v[186:189], v[40:43]
	v_mfma_f32_16x16x32_bf16 v[28:31], v[68:71], v[194:197], v[28:31]
	v_mfma_f32_16x16x32_bf16 v[24:27], v[76:79], v[194:197], v[24:27]
	v_mfma_f32_16x16x32_bf16 v[12:15], v[68:71], v[202:205], v[12:15]
	v_mfma_f32_16x16x32_bf16 v[8:11], v[76:79], v[202:205], v[8:11]
	s_setprio 0
	s_setprio 1
	v_mfma_f32_16x16x32_bf16 v[52:55], v[84:87], v[174:177], v[52:55]
	v_mfma_f32_16x16x32_bf16 v[48:51], v[92:95], v[174:177], v[48:51]
	v_mfma_f32_16x16x32_bf16 v[36:39], v[84:87], v[182:185], v[36:39]
	v_mfma_f32_16x16x32_bf16 v[32:35], v[92:95], v[182:185], v[32:35]
	v_mfma_f32_16x16x32_bf16 v[20:23], v[84:87], v[190:193], v[20:23]
	v_mfma_f32_16x16x32_bf16 v[16:19], v[92:95], v[190:193], v[16:19]
	v_mfma_f32_16x16x32_bf16 v[0:3], v[84:87], v[198:201], v[0:3]
	v_mfma_f32_16x16x32_bf16 v[4:7], v[92:95], v[198:201], v[4:7]
	v_mfma_f32_16x16x32_bf16 v[52:55], v[88:91], v[178:181], v[52:55]
	v_mfma_f32_16x16x32_bf16 v[48:51], v[96:99], v[178:181], v[48:51]
	v_mfma_f32_16x16x32_bf16 v[36:39], v[88:91], v[186:189], v[36:39]
	v_mfma_f32_16x16x32_bf16 v[32:35], v[96:99], v[186:189], v[32:35]
	v_mfma_f32_16x16x32_bf16 v[20:23], v[88:91], v[194:197], v[20:23]
	v_mfma_f32_16x16x32_bf16 v[16:19], v[96:99], v[194:197], v[16:19]
	v_mfma_f32_16x16x32_bf16 v[0:3], v[88:91], v[202:205], v[0:3]
	v_mfma_f32_16x16x32_bf16 v[4:7], v[96:99], v[202:205], v[4:7]
	s_setprio 0
	s_barrier
	v_add_u32_e32 v76, s37, v208
	v_add_u32_e32 v96, s26, v208
	ds_read_b128 v[64:67], v76
	ds_read_b128 v[68:71], v76 offset:1024
	ds_read_b128 v[72:75], v76 offset:2048
	ds_read_b128 v[76:79], v76 offset:3072
	ds_read_b128 v[84:87], v96
	ds_read_b128 v[88:91], v96 offset:1024
	ds_read_b128 v[92:95], v96 offset:2048
	ds_read_b128 v[96:99], v96 offset:3072
	s_add_u32 s6, s6, 0x80000
	s_addc_u32 s7, s7, 0
	s_mov_b32 m0, s22
	v_lshl_add_u64 v[226:227], s[6:7], 0, v[160:161]
	ds_read_b128 v[174:177], v211 offset:32768
	ds_read_b128 v[178:181], v211 offset:33792
	ds_read_b128 v[182:185], v211 offset:34816
	ds_read_b128 v[186:189], v211 offset:35840
	ds_read_b128 v[190:193], v211 offset:36864
	ds_read_b128 v[194:197], v211 offset:37888
	ds_read_b128 v[198:201], v211 offset:38912
	ds_read_b128 v[202:205], v211 offset:39936
	global_load_lds_dwordx4 v[226:227], off
	v_lshl_add_u64 v[226:227], s[6:7], 0, v[164:165]
	s_mov_b32 m0, s23
	s_nop 0
	global_load_lds_dwordx4 v[226:227], off
	s_waitcnt vmcnt(8)
	s_waitcnt lgkmcnt(0)
	s_barrier
	s_setprio 1
	v_mfma_f32_16x16x32_bf16 v[156:159], v[64:67], v[174:177], v[156:159]
	v_mfma_f32_16x16x32_bf16 v[148:151], v[72:75], v[174:177], v[148:151]
	v_mfma_f32_16x16x32_bf16 v[140:143], v[64:67], v[182:185], v[140:143]
	v_mfma_f32_16x16x32_bf16 v[136:139], v[72:75], v[182:185], v[136:139]
	v_mfma_f32_16x16x32_bf16 v[124:127], v[64:67], v[190:193], v[124:127]
	v_mfma_f32_16x16x32_bf16 v[120:123], v[72:75], v[190:193], v[120:123]
	v_mfma_f32_16x16x32_bf16 v[108:111], v[64:67], v[198:201], v[108:111]
	v_mfma_f32_16x16x32_bf16 v[104:107], v[72:75], v[198:201], v[104:107]
	v_mfma_f32_16x16x32_bf16 v[156:159], v[68:71], v[178:181], v[156:159]
	v_mfma_f32_16x16x32_bf16 v[148:151], v[76:79], v[178:181], v[148:151]
	v_mfma_f32_16x16x32_bf16 v[140:143], v[68:71], v[186:189], v[140:143]
	v_mfma_f32_16x16x32_bf16 v[136:139], v[76:79], v[186:189], v[136:139]
	v_mfma_f32_16x16x32_bf16 v[124:127], v[68:71], v[194:197], v[124:127]
	v_mfma_f32_16x16x32_bf16 v[120:123], v[76:79], v[194:197], v[120:123]
	v_mfma_f32_16x16x32_bf16 v[108:111], v[68:71], v[202:205], v[108:111]
	v_mfma_f32_16x16x32_bf16 v[104:107], v[76:79], v[202:205], v[104:107]
	s_setprio 0
	s_setprio 1
	v_mfma_f32_16x16x32_bf16 v[152:155], v[84:87], v[174:177], v[152:155]
	v_mfma_f32_16x16x32_bf16 v[144:147], v[92:95], v[174:177], v[144:147]
	v_mfma_f32_16x16x32_bf16 v[132:135], v[84:87], v[182:185], v[132:135]
	v_mfma_f32_16x16x32_bf16 v[128:131], v[92:95], v[182:185], v[128:131]
	v_mfma_f32_16x16x32_bf16 v[116:119], v[84:87], v[190:193], v[116:119]
	v_mfma_f32_16x16x32_bf16 v[112:115], v[92:95], v[190:193], v[112:115]
	v_mfma_f32_16x16x32_bf16 v[80:83], v[84:87], v[198:201], v[80:83]
	v_mfma_f32_16x16x32_bf16 v[100:103], v[92:95], v[198:201], v[100:103]
	v_mfma_f32_16x16x32_bf16 v[152:155], v[88:91], v[178:181], v[152:155]
	v_mfma_f32_16x16x32_bf16 v[144:147], v[96:99], v[178:181], v[144:147]
	v_mfma_f32_16x16x32_bf16 v[132:135], v[88:91], v[186:189], v[132:135]
	v_mfma_f32_16x16x32_bf16 v[128:131], v[96:99], v[186:189], v[128:131]
	v_mfma_f32_16x16x32_bf16 v[116:119], v[88:91], v[194:197], v[116:119]
	v_mfma_f32_16x16x32_bf16 v[112:115], v[96:99], v[194:197], v[112:115]
	v_mfma_f32_16x16x32_bf16 v[80:83], v[88:91], v[202:205], v[80:83]
	v_mfma_f32_16x16x32_bf16 v[100:103], v[96:99], v[202:205], v[100:103]
	s_setprio 0
	s_barrier
; #define PG8_STAGE(bufoff, gbase, voff) do { _Pragma("unroll") for (int _i = 0; _i < 2; ++_i) \
;         __builtin_amdgcn_global_load_lds((const unsigned*)((const char*)(gbase) + (voff)[_i]), (LAS unsigned*)(lds + (bufoff) + ldsw + _i * 8192), 16, 0, 0); } while (0)
; #define PG8_LDA(dst, b, h) do { _Pragma("unroll") for (int m = 0; m < 4; ++m) _Pragma("unroll") for (int k = 0; k < 2; ++k) dst[m][k] = *(const LAS bf16x8*)(lds + PG8_SA(b, h) + aoff + m * 2048 + k * 1024); } while (0)
; #define PG8_MMA(ai, bj, At, Bt) do { __builtin_amdgcn_s_setprio(1); _Pragma("unroll") for (int m = 0; m < 4; ++m) _Pragma("unroll") for (int n = 0; n < 2; ++n) _Pragma("unroll") for (int k = 0; k < 2; ++k) \
;         acc[ai][bj][m][n] = __builtin_amdgcn_mfma_f32_16x16x32_bf16(Bt[n][k], At[m][k], acc[ai][bj][m][n], 0, 0, 0); __builtin_amdgcn_s_setprio(0); } while (0)
; #define PG8_WAIT_V(n) asm volatile("s_waitcnt vmcnt(" #n ")" ::: "memory")
; #define PG8_WAIT_L(n) asm volatile("s_waitcnt lgkmcnt(" #n ")" ::: "memory")
; #define PG8_BAR __builtin_amdgcn_s_barrier()
; #define PG8_SCHED __builtin_amdgcn_sched_barrier(0)
; template <class Epi, class Sched>
; __device__ __forceinline__ void gemm_phase(LAS unsigned char* lds, const Gemm g, const Sched& S, const Epi& E) {
;     ...
;             PG8_LDA(At, 1, 1); PG8_STAGE(PG8_SB(1, 0), b3, voffB); PG8_STAGE(PG8_SB(1, 1), b3 + hstepB, voffB); PG8_STAGE(PG8_SA(1, 0), a3, voffA);
;             PG8_WAIT_V(8); PG8_WAIT_L(0); PG8_BAR; PG8_MMA(1, 0, At, B0); PG8_MMA(1, 1, At, B1); PG8_BAR; PG8_SCHED;
;         }
;         if (wr == 0) PG8_BAR;
	s_add_i32 s6, s37, s14
	v_lshl_add_u64 v[218:219], v[218:219], 0, s[48:49]
	s_mov_b32 m0, s6
	ds_read_b128 v[174:177], v211 offset:49152
	ds_read_b128 v[178:181], v211 offset:50176
	ds_read_b128 v[182:185], v211 offset:51200
	ds_read_b128 v[186:189], v211 offset:52224
	ds_read_b128 v[190:193], v211 offset:53248
	ds_read_b128 v[194:197], v211 offset:54272
	ds_read_b128 v[198:201], v211 offset:55296
	ds_read_b128 v[202:205], v211 offset:56320
	global_load_lds_dwordx4 v[218:219], off
	s_add_i32 m0, s6, 0x2000
	s_add_u32 s4, s4, 0x80080
	v_lshl_add_u64 v[218:219], v[220:221], 0, s[48:49]
	s_addc_u32 s5, s5, 0
	s_add_i32 s6, s26, s14
	global_load_lds_dwordx4 v[218:219], off
	v_lshl_add_u64 v[218:219], s[4:5], 0, v[162:163]
	s_mov_b32 m0, s6
	s_nop 0
	global_load_lds_dwordx4 v[218:219], off
	v_lshl_add_u64 v[218:219], s[4:5], 0, v[166:167]
	s_add_i32 m0, s6, 0x2000
	s_nop 0
	global_load_lds_dwordx4 v[218:219], off
	v_lshl_add_u64 v[218:219], v[222:223], 0, s[48:49]
	s_mov_b32 m0, s45
	s_nop 0
	global_load_lds_dwordx4 v[218:219], off
	v_lshl_add_u64 v[218:219], v[224:225], 0, s[48:49]
	s_mov_b32 m0, s64
	s_nop 0
	global_load_lds_dwordx4 v[218:219], off
	s_waitcnt vmcnt(8)
	s_waitcnt lgkmcnt(0)
	s_barrier
	s_setprio 1
	v_mfma_f32_16x16x32_bf16 v[60:63], v[64:67], v[174:177], v[60:63]
	v_mfma_f32_16x16x32_bf16 v[56:59], v[72:75], v[174:177], v[56:59]
	v_mfma_f32_16x16x32_bf16 v[44:47], v[64:67], v[182:185], v[44:47]
	v_mfma_f32_16x16x32_bf16 v[40:43], v[72:75], v[182:185], v[40:43]
	v_mfma_f32_16x16x32_bf16 v[28:31], v[64:67], v[190:193], v[28:31]
	v_mfma_f32_16x16x32_bf16 v[24:27], v[72:75], v[190:193], v[24:27]
	v_mfma_f32_16x16x32_bf16 v[12:15], v[64:67], v[198:201], v[12:15]
	v_mfma_f32_16x16x32_bf16 v[8:11], v[72:75], v[198:201], v[8:11]
	v_mfma_f32_16x16x32_bf16 v[60:63], v[68:71], v[178:181], v[60:63]
	v_mfma_f32_16x16x32_bf16 v[56:59], v[76:79], v[178:181], v[56:59]
	v_mfma_f32_16x16x32_bf16 v[44:47], v[68:71], v[186:189], v[44:47]
	v_mfma_f32_16x16x32_bf16 v[40:43], v[76:79], v[186:189], v[40:43]
	v_mfma_f32_16x16x32_bf16 v[28:31], v[68:71], v[194:197], v[28:31]
	v_mfma_f32_16x16x32_bf16 v[24:27], v[76:79], v[194:197], v[24:27]
	v_mfma_f32_16x16x32_bf16 v[12:15], v[68:71], v[202:205], v[12:15]
	v_mfma_f32_16x16x32_bf16 v[8:11], v[76:79], v[202:205], v[8:11]
	s_setprio 0
	s_setprio 1
	v_mfma_f32_16x16x32_bf16 v[52:55], v[84:87], v[174:177], v[52:55]
	v_mfma_f32_16x16x32_bf16 v[48:51], v[92:95], v[174:177], v[48:51]
	v_mfma_f32_16x16x32_bf16 v[36:39], v[84:87], v[182:185], v[36:39]
	v_mfma_f32_16x16x32_bf16 v[32:35], v[92:95], v[182:185], v[32:35]
	v_mfma_f32_16x16x32_bf16 v[20:23], v[84:87], v[190:193], v[20:23]
	v_mfma_f32_16x16x32_bf16 v[16:19], v[92:95], v[190:193], v[16:19]
	v_mfma_f32_16x16x32_bf16 v[0:3], v[84:87], v[198:201], v[0:3]
	v_mfma_f32_16x16x32_bf16 v[4:7], v[92:95], v[198:201], v[4:7]
	v_mfma_f32_16x16x32_bf16 v[52:55], v[88:91], v[178:181], v[52:55]
	v_mfma_f32_16x16x32_bf16 v[48:51], v[96:99], v[178:181], v[48:51]
	v_mfma_f32_16x16x32_bf16 v[36:39], v[88:91], v[186:189], v[36:39]
	v_mfma_f32_16x16x32_bf16 v[32:35], v[96:99], v[186:189], v[32:35]
	v_mfma_f32_16x16x32_bf16 v[20:23], v[88:91], v[194:197], v[20:23]
	v_mfma_f32_16x16x32_bf16 v[16:19], v[96:99], v[194:197], v[16:19]
	v_mfma_f32_16x16x32_bf16 v[0:3], v[88:91], v[202:205], v[0:3]
	v_mfma_f32_16x16x32_bf16 v[4:7], v[96:99], v[202:205], v[4:7]
	s_setprio 0
	s_barrier
	s_add_i32 s62, s62, 2
	s_add_u32 s0, s0, 0x100
	s_addc_u32 s1, s1, 0
	s_add_u32 s60, s60, 0x100
	s_addc_u32 s61, s61, 0
	s_cmp_gt_u32 s62, 29
	s_cbranch_scc0 .LBB0_923
	s_and_b64 vcc, exec, s[50:51]
	s_cbranch_vccz .LBB0_926
	s_barrier

; #define PG8_STAGE(bufoff, gbase, voff) do { _Pragma("unroll") for (int _i = 0; _i < 2; ++_i) \
;         __builtin_amdgcn_global_load_lds((const unsigned*)((const char*)(gbase) + (voff)[_i]), (LAS unsigned*)(lds + (bufoff) + ldsw + _i * 8192), 16, 0, 0); } while (0)
; #define PG8_LDA(dst, b, h) do { _Pragma("unroll") for (int m = 0; m < 4; ++m) _Pragma("unroll") for (int k = 0; k < 2; ++k) dst[m][k] = *(const LAS bf16x8*)(lds + PG8_SA(b, h) + aoff + m * 2048 + k * 1024); } while (0)
; #define PG8_LDB(dst, b, h) do { _Pragma("unroll") for (int n = 0; n < 2; ++n) _Pragma("unroll") for (int k = 0; k < 2; ++k) dst[n][k] = *(const LAS bf16x8*)(lds + PG8_SB(b, h) + boff + n * 2048 + k * 1024); } while (0)
; #define PG8_MMA(ai, bj, At, Bt) do { __builtin_amdgcn_s_setprio(1); _Pragma("unroll") for (int m = 0; m < 4; ++m) _Pragma("unroll") for (int n = 0; n < 2; ++n) _Pragma("unroll") for (int k = 0; k < 2; ++k) \
;         acc[ai][bj][m][n] = __builtin_amdgcn_mfma_f32_16x16x32_bf16(Bt[n][k], At[m][k], acc[ai][bj][m][n], 0, 0, 0); __builtin_amdgcn_s_setprio(0); } while (0)
; #define PG8_WAIT_V(n) asm volatile("s_waitcnt vmcnt(" #n ")" ::: "memory")
; #define PG8_WAIT_L(n) asm volatile("s_waitcnt lgkmcnt(" #n ")" ::: "memory")
; #define PG8_BAR __builtin_amdgcn_s_barrier()
; #define PG8_SCHED __builtin_amdgcn_sched_barrier(0)
; template <class Epi, class Sched>
; __device__ __forceinline__ void gemm_phase(LAS unsigned char* lds, const Gemm g, const Sched& S, const Epi& E) {
;     ...
;             const bool last = (t == nt - 2);
;             const char* a1 = cA + (size_t)(t + 1) * kstep;
;             const char* a2 = last ? nA : cA + (size_t)(t + 2) * kstep; const char* b2 = last ? nB : cB + (size_t)(t + 2) * kstep;
;             const char* a3 = a2 + kstep; const char* b3 = b2 + kstep;
;             PG8_LDB(B0, 0, 0); PG8_LDB(B1, 0, 1); PG8_SCHED; PG8_LDA(At, 0, 0); PG8_STAGE(PG8_SA(1, 1), a1 + hstepA, voffA);
;             PG8_WAIT_V(8); PG8_WAIT_L(0); PG8_BAR; PG8_MMA(0, 0, At, B0); PG8_MMA(0, 1, At, B1); PG8_BAR; PG8_SCHED;
;             PG8_LDA(At, 0, 1); PG8_STAGE(PG8_SB(0, 0), b2, voffB); PG8_STAGE(PG8_SB(0, 1), b2 + hstepB, voffB); PG8_STAGE(PG8_SA(0, 0), a2, voffA);
.LBB0_1077:
	ds_read_b128 v[128:131], v193
	ds_read_b128 v[132:135], v193 offset:1024
	ds_read_b128 v[148:151], v193 offset:2048
	ds_read_b128 v[152:155], v193 offset:3072
	ds_read_b128 v[156:159], v194
	ds_read_b128 v[160:163], v194 offset:1024
	ds_read_b128 v[164:167], v194 offset:2048
	ds_read_b128 v[168:171], v194 offset:3072
	s_add_u32 s30, s24, 0x100
	s_addc_u32 s31, s25, 0
	s_cmpk_eq_i32 s1, 0x5c
	s_cselect_b32 s39, s23, s31
	s_cselect_b32 s38, s22, s30
	s_cselect_b32 s35, s7, s5
	s_cselect_b32 s34, s6, s4
	v_lshl_add_u64 v[214:215], s[24:25], 0, v[144:145]
	s_add_i32 m0, s28, 0xc000
	ds_read_b128 v[172:175], v195
	ds_read_b128 v[176:179], v195 offset:1024
	ds_read_b128 v[180:183], v195 offset:2048
	ds_read_b128 v[184:187], v195 offset:3072
	ds_read_b128 v[198:201], v195 offset:4096
	ds_read_b128 v[202:205], v195 offset:5120
	ds_read_b128 v[206:209], v195 offset:6144
	ds_read_b128 v[210:213], v195 offset:7168
	global_load_lds_dwordx4 v[214:215], off
	v_lshl_add_u64 v[214:215], s[24:25], 0, v[146:147]
	s_add_i32 m0, s28, 0xe000
	s_nop 0
	global_load_lds_dwordx4 v[214:215], off
	s_waitcnt vmcnt(8)
	s_waitcnt lgkmcnt(0)
	s_barrier
	s_setprio 1
	v_mfma_f32_16x16x32_bf16 v[124:127], v[128:131], v[172:175], v[124:127]
	v_mfma_f32_16x16x32_bf16 v[120:123], v[148:151], v[172:175], v[120:123]
	v_mfma_f32_16x16x32_bf16 v[108:111], v[128:131], v[180:183], v[108:111]
	v_mfma_f32_16x16x32_bf16 v[104:107], v[148:151], v[180:183], v[104:107]
	v_mfma_f32_16x16x32_bf16 v[92:95], v[128:131], v[198:201], v[92:95]
	v_mfma_f32_16x16x32_bf16 v[88:91], v[148:151], v[198:201], v[88:91]
	v_mfma_f32_16x16x32_bf16 v[76:79], v[128:131], v[206:209], v[76:79]
	v_mfma_f32_16x16x32_bf16 v[72:75], v[148:151], v[206:209], v[72:75]
	v_mfma_f32_16x16x32_bf16 v[124:127], v[132:135], v[176:179], v[124:127]
	v_mfma_f32_16x16x32_bf16 v[120:123], v[152:155], v[176:179], v[120:123]
	v_mfma_f32_16x16x32_bf16 v[108:111], v[132:135], v[184:187], v[108:111]
	v_mfma_f32_16x16x32_bf16 v[104:107], v[152:155], v[184:187], v[104:107]
	v_mfma_f32_16x16x32_bf16 v[92:95], v[132:135], v[202:205], v[92:95]
	v_mfma_f32_16x16x32_bf16 v[88:91], v[152:155], v[202:205], v[88:91]
	v_mfma_f32_16x16x32_bf16 v[76:79], v[132:135], v[210:213], v[76:79]
	v_mfma_f32_16x16x32_bf16 v[72:75], v[152:155], v[210:213], v[72:75]
	s_setprio 0
	s_setprio 1
	v_mfma_f32_16x16x32_bf16 v[116:119], v[156:159], v[172:175], v[116:119]
	v_mfma_f32_16x16x32_bf16 v[112:115], v[164:167], v[172:175], v[112:115]
	v_mfma_f32_16x16x32_bf16 v[100:103], v[156:159], v[180:183], v[100:103]
	v_mfma_f32_16x16x32_bf16 v[96:99], v[164:167], v[180:183], v[96:99]
	v_mfma_f32_16x16x32_bf16 v[84:87], v[156:159], v[198:201], v[84:87]
	v_mfma_f32_16x16x32_bf16 v[80:83], v[164:167], v[198:201], v[80:83]
	v_mfma_f32_16x16x32_bf16 v[68:71], v[156:159], v[206:209], v[68:71]
	v_mfma_f32_16x16x32_bf16 v[64:67], v[164:167], v[206:209], v[64:67]
	v_mfma_f32_16x16x32_bf16 v[116:119], v[160:163], v[176:179], v[116:119]
	v_mfma_f32_16x16x32_bf16 v[112:115], v[168:171], v[176:179], v[112:115]
	v_mfma_f32_16x16x32_bf16 v[100:103], v[160:163], v[184:187], v[100:103]
	v_mfma_f32_16x16x32_bf16 v[96:99], v[168:171], v[184:187], v[96:99]
	v_mfma_f32_16x16x32_bf16 v[84:87], v[160:163], v[202:205], v[84:87]
	v_mfma_f32_16x16x32_bf16 v[80:83], v[168:171], v[202:205], v[80:83]
	v_mfma_f32_16x16x32_bf16 v[68:71], v[160:163], v[210:213], v[68:71]
	v_mfma_f32_16x16x32_bf16 v[64:67], v[168:171], v[210:213], v[64:67]
	s_setprio 0
	s_barrier
	s_add_i32 s12, s33, s27
	v_lshl_add_u64 v[214:215], s[34:35], 0, v[138:139]
	s_mov_b32 m0, s12
	ds_read_b128 v[172:175], v195 offset:16384
	ds_read_b128 v[176:179], v195 offset:17408
	ds_read_b128 v[180:183], v195 offset:18432
	ds_read_b128 v[184:187], v195 offset:19456
	ds_read_b128 v[198:201], v195 offset:20480
	ds_read_b128 v[202:205], v195 offset:21504
	ds_read_b128 v[206:209], v195 offset:22528
	ds_read_b128 v[210:213], v195 offset:23552
	global_load_lds_dwordx4 v[214:215], off
	s_add_i32 m0, s12, 0x2000
	s_add_u32 s12, s34, 0x180000
	v_lshl_add_u64 v[216:217], s[34:35], 0, v[142:143]
	s_addc_u32 s13, s35, 0
	s_add_i32 s24, s36, s27
	global_load_lds_dwordx4 v[216:217], off
	v_lshl_add_u64 v[218:219], s[12:13], 0, v[138:139]
	s_mov_b32 m0, s24
	v_lshl_add_u64 v[220:221], s[38:39], 0, v[140:141]
	global_load_lds_dwordx4 v[218:219], off
	v_lshl_add_u64 v[218:219], s[12:13], 0, v[142:143]
	s_add_i32 m0, s24, 0x2000
	s_nop 0
	global_load_lds_dwordx4 v[218:219], off
	v_lshl_add_u64 v[218:219], s[38:39], 0, v[136:137]
	s_mov_b32 m0, s28
	s_nop 0
	global_load_lds_dwordx4 v[218:219], off
	s_mov_b32 m0, s40
	s_nop 0
	global_load_lds_dwordx4 v[220:221], off
	s_waitcnt vmcnt(8)
	s_waitcnt lgkmcnt(0)
	s_barrier
; #define PG8_STAGE(bufoff, gbase, voff) do { _Pragma("unroll") for (int _i = 0; _i < 2; ++_i) \
;         __builtin_amdgcn_global_load_lds((const unsigned*)((const char*)(gbase) + (voff)[_i]), (LAS unsigned*)(lds + (bufoff) + ldsw + _i * 8192), 16, 0, 0); } while (0)
; #define PG8_LDA(dst, b, h) do { _Pragma("unroll") for (int m = 0; m < 4; ++m) _Pragma("unroll") for (int k = 0; k < 2; ++k) dst[m][k] = *(const LAS bf16x8*)(lds + PG8_SA(b, h) + aoff + m * 2048 + k * 1024); } while (0)
; #define PG8_LDB(dst, b, h) do { _Pragma("unroll") for (int n = 0; n < 2; ++n) _Pragma("unroll") for (int k = 0; k < 2; ++k) dst[n][k] = *(const LAS bf16x8*)(lds + PG8_SB(b, h) + boff + n * 2048 + k * 1024); } while (0)
; #define PG8_MMA(ai, bj, At, Bt) do { __builtin_amdgcn_s_setprio(1); _Pragma("unroll") for (int m = 0; m < 4; ++m) _Pragma("unroll") for (int n = 0; n < 2; ++n) _Pragma("unroll") for (int k = 0; k < 2; ++k) \
;         acc[ai][bj][m][n] = __builtin_amdgcn_mfma_f32_16x16x32_bf16(Bt[n][k], At[m][k], acc[ai][bj][m][n], 0, 0, 0); __builtin_amdgcn_s_setprio(0); } while (0)
; #define PG8_WAIT_V(n) asm volatile("s_waitcnt vmcnt(" #n ")" ::: "memory")
; #define PG8_WAIT_L(n) asm volatile("s_waitcnt lgkmcnt(" #n ")" ::: "memory")
; #define PG8_BAR __builtin_amdgcn_s_barrier()
; #define PG8_SCHED __builtin_amdgcn_sched_barrier(0)
; template <class Epi, class Sched>
; __device__ __forceinline__ void gemm_phase(LAS unsigned char* lds, const Gemm g, const Sched& S, const Epi& E) {
;     ...
;             PG8_LDA(At, 0, 1); PG8_STAGE(PG8_SB(0, 0), b2, voffB); PG8_STAGE(PG8_SB(0, 1), b2 + hstepB, voffB); PG8_STAGE(PG8_SA(0, 0), a2, voffA);
;             PG8_WAIT_V(8); PG8_WAIT_L(0); PG8_BAR; PG8_MMA(1, 0, At, B0); PG8_MMA(1, 1, At, B1); PG8_BAR; PG8_SCHED;
;             PG8_LDB(B0, 1, 0); PG8_LDB(B1, 1, 1); PG8_SCHED; PG8_LDA(At, 1, 0); PG8_STAGE(PG8_SA(0, 1), a2 + hstepA, voffA);
;             PG8_WAIT_V(8); PG8_WAIT_L(0); PG8_BAR; PG8_MMA(0, 0, At, B0); PG8_MMA(0, 1, At, B1); PG8_BAR; PG8_SCHED;
	s_setprio 1
	v_mfma_f32_16x16x32_bf16 v[60:63], v[128:131], v[172:175], v[60:63]
	v_mfma_f32_16x16x32_bf16 v[56:59], v[148:151], v[172:175], v[56:59]
	v_mfma_f32_16x16x32_bf16 v[44:47], v[128:131], v[180:183], v[44:47]
	v_mfma_f32_16x16x32_bf16 v[40:43], v[148:151], v[180:183], v[40:43]
	v_mfma_f32_16x16x32_bf16 v[28:31], v[128:131], v[198:201], v[28:31]
	v_mfma_f32_16x16x32_bf16 v[24:27], v[148:151], v[198:201], v[24:27]
	v_mfma_f32_16x16x32_bf16 v[12:15], v[128:131], v[206:209], v[12:15]
	v_mfma_f32_16x16x32_bf16 v[8:11], v[148:151], v[206:209], v[8:11]
	v_mfma_f32_16x16x32_bf16 v[60:63], v[132:135], v[176:179], v[60:63]
	v_mfma_f32_16x16x32_bf16 v[56:59], v[152:155], v[176:179], v[56:59]
	v_mfma_f32_16x16x32_bf16 v[44:47], v[132:135], v[184:187], v[44:47]
	v_mfma_f32_16x16x32_bf16 v[40:43], v[152:155], v[184:187], v[40:43]
	v_mfma_f32_16x16x32_bf16 v[28:31], v[132:135], v[202:205], v[28:31]
	v_mfma_f32_16x16x32_bf16 v[24:27], v[152:155], v[202:205], v[24:27]
	v_mfma_f32_16x16x32_bf16 v[12:15], v[132:135], v[210:213], v[12:15]
	v_mfma_f32_16x16x32_bf16 v[8:11], v[152:155], v[210:213], v[8:11]
	s_setprio 0
	s_setprio 1
	v_mfma_f32_16x16x32_bf16 v[52:55], v[156:159], v[172:175], v[52:55]
	v_mfma_f32_16x16x32_bf16 v[48:51], v[164:167], v[172:175], v[48:51]
	v_mfma_f32_16x16x32_bf16 v[36:39], v[156:159], v[180:183], v[36:39]
	v_mfma_f32_16x16x32_bf16 v[32:35], v[164:167], v[180:183], v[32:35]
	v_mfma_f32_16x16x32_bf16 v[20:23], v[156:159], v[198:201], v[20:23]
	v_mfma_f32_16x16x32_bf16 v[16:19], v[164:167], v[198:201], v[16:19]
	v_mfma_f32_16x16x32_bf16 v[4:7], v[156:159], v[206:209], v[4:7]
	v_mfma_f32_16x16x32_bf16 v[0:3], v[164:167], v[206:209], v[0:3]
	v_mfma_f32_16x16x32_bf16 v[52:55], v[160:163], v[176:179], v[52:55]
	v_mfma_f32_16x16x32_bf16 v[48:51], v[168:171], v[176:179], v[48:51]
	v_mfma_f32_16x16x32_bf16 v[36:39], v[160:163], v[184:187], v[36:39]
	v_mfma_f32_16x16x32_bf16 v[32:35], v[168:171], v[184:187], v[32:35]
	v_mfma_f32_16x16x32_bf16 v[20:23], v[160:163], v[202:205], v[20:23]
	v_mfma_f32_16x16x32_bf16 v[16:19], v[168:171], v[202:205], v[16:19]
	v_mfma_f32_16x16x32_bf16 v[4:7], v[160:163], v[210:213], v[4:7]
	v_mfma_f32_16x16x32_bf16 v[0:3], v[168:171], v[210:213], v[0:3]
	s_setprio 0
	s_barrier
	v_add_u32_e32 v152, s37, v190
	v_add_u32_e32 v168, s26, v190
	ds_read_b128 v[128:131], v152
	ds_read_b128 v[132:135], v152 offset:1024
	ds_read_b128 v[148:151], v152 offset:2048
	ds_read_b128 v[152:155], v152 offset:3072
	ds_read_b128 v[156:159], v168
	ds_read_b128 v[160:163], v168 offset:1024
	ds_read_b128 v[164:167], v168 offset:2048
	ds_read_b128 v[168:171], v168 offset:3072
	s_add_u32 s12, s38, 0x180000
	s_addc_u32 s13, s39, 0
	s_mov_b32 m0, s41
	v_lshl_add_u64 v[222:223], s[12:13], 0, v[136:137]
	ds_read_b128 v[172:175], v195 offset:32768
	ds_read_b128 v[176:179], v195 offset:33792
	ds_read_b128 v[180:183], v195 offset:34816
	ds_read_b128 v[184:187], v195 offset:35840
	ds_read_b128 v[198:201], v195 offset:36864
	ds_read_b128 v[202:205], v195 offset:37888
	ds_read_b128 v[206:209], v195 offset:38912
	ds_read_b128 v[210:213], v195 offset:39936
	global_load_lds_dwordx4 v[222:223], off
	v_lshl_add_u64 v[222:223], s[12:13], 0, v[140:141]
	s_mov_b32 m0, s42
	s_nop 0
	global_load_lds_dwordx4 v[222:223], off
	s_waitcnt vmcnt(8)
	s_waitcnt lgkmcnt(0)
	s_barrier
	s_setprio 1
	v_mfma_f32_16x16x32_bf16 v[124:127], v[128:131], v[172:175], v[124:127]
	v_mfma_f32_16x16x32_bf16 v[120:123], v[148:151], v[172:175], v[120:123]
	v_mfma_f32_16x16x32_bf16 v[108:111], v[128:131], v[180:183], v[108:111]
	v_mfma_f32_16x16x32_bf16 v[104:107], v[148:151], v[180:183], v[104:107]
	v_mfma_f32_16x16x32_bf16 v[92:95], v[128:131], v[198:201], v[92:95]
	v_mfma_f32_16x16x32_bf16 v[88:91], v[148:151], v[198:201], v[88:91]
	v_mfma_f32_16x16x32_bf16 v[76:79], v[128:131], v[206:209], v[76:79]
	v_mfma_f32_16x16x32_bf16 v[72:75], v[148:151], v[206:209], v[72:75]
	v_mfma_f32_16x16x32_bf16 v[124:127], v[132:135], v[176:179], v[124:127]
	v_mfma_f32_16x16x32_bf16 v[120:123], v[152:155], v[176:179], v[120:123]
	v_mfma_f32_16x16x32_bf16 v[108:111], v[132:135], v[184:187], v[108:111]
	v_mfma_f32_16x16x32_bf16 v[104:107], v[152:155], v[184:187], v[104:107]
	v_mfma_f32_16x16x32_bf16 v[92:95], v[132:135], v[202:205], v[92:95]
	v_mfma_f32_16x16x32_bf16 v[88:91], v[152:155], v[202:205], v[88:91]
	v_mfma_f32_16x16x32_bf16 v[76:79], v[132:135], v[210:213], v[76:79]
	v_mfma_f32_16x16x32_bf16 v[72:75], v[152:155], v[210:213], v[72:75]
	s_setprio 0
	s_setprio 1
	v_mfma_f32_16x16x32_bf16 v[116:119], v[156:159], v[172:175], v[116:119]
	v_mfma_f32_16x16x32_bf16 v[112:115], v[164:167], v[172:175], v[112:115]
	v_mfma_f32_16x16x32_bf16 v[100:103], v[156:159], v[180:183], v[100:103]
	v_mfma_f32_16x16x32_bf16 v[96:99], v[164:167], v[180:183], v[96:99]
	v_mfma_f32_16x16x32_bf16 v[84:87], v[156:159], v[198:201], v[84:87]
	v_mfma_f32_16x16x32_bf16 v[80:83], v[164:167], v[198:201], v[80:83]
	v_mfma_f32_16x16x32_bf16 v[68:71], v[156:159], v[206:209], v[68:71]
	v_mfma_f32_16x16x32_bf16 v[64:67], v[164:167], v[206:209], v[64:67]
	v_mfma_f32_16x16x32_bf16 v[116:119], v[160:163], v[176:179], v[116:119]
	v_mfma_f32_16x16x32_bf16 v[112:115], v[168:171], v[176:179], v[112:115]
	v_mfma_f32_16x16x32_bf16 v[100:103], v[160:163], v[184:187], v[100:103]
	v_mfma_f32_16x16x32_bf16 v[96:99], v[168:171], v[184:187], v[96:99]
	v_mfma_f32_16x16x32_bf16 v[84:87], v[160:163], v[202:205], v[84:87]
	v_mfma_f32_16x16x32_bf16 v[80:83], v[168:171], v[202:205], v[80:83]
	v_mfma_f32_16x16x32_bf16 v[68:71], v[160:163], v[210:213], v[68:71]
	v_mfma_f32_16x16x32_bf16 v[64:67], v[168:171], v[210:213], v[64:67]
	s_setprio 0
	s_barrier
; #define PG8_STAGE(bufoff, gbase, voff) do { _Pragma("unroll") for (int _i = 0; _i < 2; ++_i) \
;         __builtin_amdgcn_global_load_lds((const unsigned*)((const char*)(gbase) + (voff)[_i]), (LAS unsigned*)(lds + (bufoff) + ldsw + _i * 8192), 16, 0, 0); } while (0)
; #define PG8_LDA(dst, b, h) do { _Pragma("unroll") for (int m = 0; m < 4; ++m) _Pragma("unroll") for (int k = 0; k < 2; ++k) dst[m][k] = *(const LAS bf16x8*)(lds + PG8_SA(b, h) + aoff + m * 2048 + k * 1024); } while (0)
; #define PG8_MMA(ai, bj, At, Bt) do { __builtin_amdgcn_s_setprio(1); _Pragma("unroll") for (int m = 0; m < 4; ++m) _Pragma("unroll") for (int n = 0; n < 2; ++n) _Pragma("unroll") for (int k = 0; k < 2; ++k) \
;         acc[ai][bj][m][n] = __builtin_amdgcn_mfma_f32_16x16x32_bf16(Bt[n][k], At[m][k], acc[ai][bj][m][n], 0, 0, 0); __builtin_amdgcn_s_setprio(0); } while (0)
; #define PG8_WAIT_V(n) asm volatile("s_waitcnt vmcnt(" #n ")" ::: "memory")
; #define PG8_WAIT_L(n) asm volatile("s_waitcnt lgkmcnt(" #n ")" ::: "memory")
; #define PG8_BAR __builtin_amdgcn_s_barrier()
; #define PG8_SCHED __builtin_amdgcn_sched_barrier(0)
; template <class Epi, class Sched>
; __device__ __forceinline__ void gemm_phase(LAS unsigned char* lds, const Gemm g, const Sched& S, const Epi& E) {
;     ...
;             PG8_LDA(At, 1, 1); PG8_STAGE(PG8_SB(1, 0), b3, voffB); PG8_STAGE(PG8_SB(1, 1), b3 + hstepB, voffB); PG8_STAGE(PG8_SA(1, 0), a3, voffA);
;             PG8_WAIT_V(8); PG8_WAIT_L(0); PG8_BAR; PG8_MMA(1, 0, At, B0); PG8_MMA(1, 1, At, B1); PG8_BAR; PG8_SCHED;
;         }
;         if (wr == 0) PG8_BAR;
	s_add_i32 s12, s37, s27
	v_lshl_add_u64 v[214:215], v[214:215], 0, s[16:17]
	s_mov_b32 m0, s12
	ds_read_b128 v[172:175], v195 offset:49152
	ds_read_b128 v[176:179], v195 offset:50176
	ds_read_b128 v[180:183], v195 offset:51200
	ds_read_b128 v[184:187], v195 offset:52224
	ds_read_b128 v[198:201], v195 offset:53248
	ds_read_b128 v[202:205], v195 offset:54272
	ds_read_b128 v[206:209], v195 offset:55296
	ds_read_b128 v[210:213], v195 offset:56320
	global_load_lds_dwordx4 v[214:215], off
	s_add_i32 m0, s12, 0x2000
	s_add_u32 s12, s34, 0x180080
	v_lshl_add_u64 v[214:215], v[216:217], 0, s[16:17]
	s_addc_u32 s13, s35, 0
	s_add_i32 s24, s26, s27
	global_load_lds_dwordx4 v[214:215], off
	v_lshl_add_u64 v[214:215], s[12:13], 0, v[138:139]
	s_mov_b32 m0, s24
	s_nop 0
	global_load_lds_dwordx4 v[214:215], off
	v_lshl_add_u64 v[214:215], s[12:13], 0, v[142:143]
	s_add_i32 m0, s24, 0x2000
	s_nop 0
	global_load_lds_dwordx4 v[214:215], off
	v_lshl_add_u64 v[214:215], v[218:219], 0, s[16:17]
	s_mov_b32 m0, s46
	s_nop 0
	global_load_lds_dwordx4 v[214:215], off
	v_lshl_add_u64 v[214:215], v[220:221], 0, s[16:17]
	s_mov_b32 m0, s47
	s_nop 0
	global_load_lds_dwordx4 v[214:215], off
	s_waitcnt vmcnt(8)
	s_waitcnt lgkmcnt(0)
	s_barrier
	s_setprio 1
	v_mfma_f32_16x16x32_bf16 v[60:63], v[128:131], v[172:175], v[60:63]
	v_mfma_f32_16x16x32_bf16 v[56:59], v[148:151], v[172:175], v[56:59]
	v_mfma_f32_16x16x32_bf16 v[44:47], v[128:131], v[180:183], v[44:47]
	v_mfma_f32_16x16x32_bf16 v[40:43], v[148:151], v[180:183], v[40:43]
	v_mfma_f32_16x16x32_bf16 v[28:31], v[128:131], v[198:201], v[28:31]
	v_mfma_f32_16x16x32_bf16 v[24:27], v[148:151], v[198:201], v[24:27]
	v_mfma_f32_16x16x32_bf16 v[12:15], v[128:131], v[206:209], v[12:15]
	v_mfma_f32_16x16x32_bf16 v[8:11], v[148:151], v[206:209], v[8:11]
	v_mfma_f32_16x16x32_bf16 v[60:63], v[132:135], v[176:179], v[60:63]
	v_mfma_f32_16x16x32_bf16 v[56:59], v[152:155], v[176:179], v[56:59]
	v_mfma_f32_16x16x32_bf16 v[44:47], v[132:135], v[184:187], v[44:47]
	v_mfma_f32_16x16x32_bf16 v[40:43], v[152:155], v[184:187], v[40:43]
	v_mfma_f32_16x16x32_bf16 v[28:31], v[132:135], v[202:205], v[28:31]
	v_mfma_f32_16x16x32_bf16 v[24:27], v[152:155], v[202:205], v[24:27]
	v_mfma_f32_16x16x32_bf16 v[12:15], v[132:135], v[210:213], v[12:15]
	v_mfma_f32_16x16x32_bf16 v[8:11], v[152:155], v[210:213], v[8:11]
	s_setprio 0
	s_setprio 1
	v_mfma_f32_16x16x32_bf16 v[52:55], v[156:159], v[172:175], v[52:55]
	v_mfma_f32_16x16x32_bf16 v[48:51], v[164:167], v[172:175], v[48:51]
	v_mfma_f32_16x16x32_bf16 v[36:39], v[156:159], v[180:183], v[36:39]
	v_mfma_f32_16x16x32_bf16 v[32:35], v[164:167], v[180:183], v[32:35]
	v_mfma_f32_16x16x32_bf16 v[20:23], v[156:159], v[198:201], v[20:23]
	v_mfma_f32_16x16x32_bf16 v[16:19], v[164:167], v[198:201], v[16:19]
	v_mfma_f32_16x16x32_bf16 v[4:7], v[156:159], v[206:209], v[4:7]
	v_mfma_f32_16x16x32_bf16 v[0:3], v[164:167], v[206:209], v[0:3]
	v_mfma_f32_16x16x32_bf16 v[52:55], v[160:163], v[176:179], v[52:55]
	v_mfma_f32_16x16x32_bf16 v[48:51], v[168:171], v[176:179], v[48:51]
	v_mfma_f32_16x16x32_bf16 v[36:39], v[160:163], v[184:187], v[36:39]
	v_mfma_f32_16x16x32_bf16 v[32:35], v[168:171], v[184:187], v[32:35]
	v_mfma_f32_16x16x32_bf16 v[20:23], v[160:163], v[202:205], v[20:23]
	v_mfma_f32_16x16x32_bf16 v[16:19], v[168:171], v[202:205], v[16:19]
	v_mfma_f32_16x16x32_bf16 v[4:7], v[160:163], v[210:213], v[4:7]
	v_mfma_f32_16x16x32_bf16 v[0:3], v[168:171], v[210:213], v[0:3]
	s_setprio 0
	s_barrier
	s_add_i32 s1, s1, 2
	s_add_u32 s4, s4, 0x100
	s_addc_u32 s5, s5, 0
	s_cmpk_gt_u32 s1, 0x5d
	s_mov_b64 s[24:25], s[30:31]
	s_cbranch_scc0 .LBB0_1077
	s_and_b64 vcc, exec, s[18:19]
	s_cbranch_vccz .LBB0_1080
	s_barrier
